# K-loops: last 2 LDS-DMA groups of each 6-DMA load segment issued after the last MFMA of the following compute segment (vmcnt 8 to 6)
# speedup vs baseline: 1.0771x; 1.0771x over previous
;     __device__ __forceinline__ const char* tile(const Unit& u, int t) const { return A + (size_t)u.pm * 2 * hstep() + (size_t)t * (BK * 2); }
;     __device__ __forceinline__ const char* tile(const Unit& u, int t) const { return U + (long)(t >> 2) * xoff + (size_t)u.pn * (1024 * 512) + (size_t)u.pm * 2 * hstep() + (size_t)(t & 3) * (BK * 2); }
; #define PG8_STAGE(bufoff, gbase, voff) do { _Pragma("unroll") for (int _i = 0; _i < 2; ++_i) \
;         __builtin_amdgcn_global_load_lds((const unsigned*)((const char*)(gbase) + (voff)[_i]), (PG8_LAS unsigned*)(lds + (bufoff) + ldsw + _i * 8192), 16, 0, 0); } while (0)
; #define PG8_LDA(dst, b, h) do { _Pragma("unroll") for (int m = 0; m < 4; ++m) _Pragma("unroll") for (int k = 0; k < 2; ++k) dst[m][k] = *(const PG8_LAS bf16x8*)(lds + PG8_SA(b, h) + aoff + m * 2048 + k * 1024); } while (0)
; #define PG8_LDB(dst, b, h) do { _Pragma("unroll") for (int n = 0; n < 2; ++n) _Pragma("unroll") for (int k = 0; k < 2; ++k) dst[n][k] = *(const PG8_LAS bf16x8*)(lds + PG8_SB(b, h) + boff + n * 2048 + k * 1024); } while (0)
; #define PG8_MMA(ai, bj, At, Bt) do { __builtin_amdgcn_s_setprio(1); _Pragma("unroll") for (int m = 0; m < 4; ++m) _Pragma("unroll") for (int n = 0; n < 2; ++n) _Pragma("unroll") for (int k = 0; k < 2; ++k) \
;         acc[ai][bj][m][n] = __builtin_amdgcn_mfma_f32_16x16x32_bf16(Bt[n][k], At[m][k], acc[ai][bj][m][n], 0, 0, 0); __builtin_amdgcn_s_setprio(0); } while (0)
; #define PG8_BAR __builtin_amdgcn_s_barrier()
;     ...
;         for (int t = 0; t < nt; t += 2) {
;             const bool last = (t == nt - 2);
;             const char* a1 = AS.tile(cur, t + 1);
;             const char* a2 = last ? AS.tile(nu, 0) : AS.tile(cur, t + 2); const char* b2 = last ? nB : cB + (size_t)(t + 2) * kstep;
;             const char* a3 = last ? AS.tile(nu, 1) : AS.tile(cur, t + 3); const char* b3 = b2 + kstep;
;             PG8_LDB(B0, 0, 0); PG8_LDB(B1, 0, 1); PG8_SCHED; PG8_LDA(At, 0, 0); PG8_STAGE(PG8_SA(1, 1), a1 + hstepA, voffA);
;             PG8_WAIT_V(8); PG8_WAIT_L(0); PG8_BAR; PG8_MMA(0, 0, At, B0); PG8_MMA(0, 1, At, B1); PG8_BAR; PG8_SCHED;
;             PG8_LDA(At, 0, 1); PG8_STAGE(PG8_SB(0, 0), b2, voffB); PG8_STAGE(PG8_SB(0, 1), b2 + hstepB, voffB); PG8_STAGE(PG8_SA(0, 0), a2, voffA);
;             PG8_WAIT_V(8); PG8_WAIT_L(0); PG8_BAR; PG8_MMA(1, 0, At, B0); PG8_MMA(1, 1, At, B1); PG8_BAR; PG8_SCHED;
.LBB0_380:
	s_add_u32 s28, s1, s2
	s_addc_u32 s29, s77, s3
	s_add_u32 s48, s28, 0x100
	s_addc_u32 s49, s29, 0
	s_add_u32 s46, s82, s2
	s_addc_u32 s47, s83, s3
	s_add_u32 s28, s28, 0x180
	s_addc_u32 s29, s29, 0
	s_add_i32 s85, 0, 0x10000
	s_add_i32 s88, 0, 0x14000
	v_add_u32_e32 v158, s85, v174
	v_add_u32_e32 v186, s88, v174
	ds_read_b128 v[132:135], v158
	ds_read_b128 v[136:139], v158 offset:1024
	ds_read_b128 v[140:143], v158 offset:2048
	ds_read_b128 v[158:161], v158 offset:3072
	ds_read_b128 v[162:165], v186
	ds_read_b128 v[166:169], v186 offset:1024
	ds_read_b128 v[182:185], v186 offset:2048
	ds_read_b128 v[186:189], v186 offset:3072
	s_cmpk_eq_i32 s2, 0x700
	s_cselect_b32 s29, s81, s29
	s_cselect_b32 s28, s80, s28
	s_cselect_b32 s47, s76, s47
	s_cselect_b32 s46, s75, s46
	s_cselect_b32 s49, s79, s49
	s_cselect_b32 s48, s78, s48
	v_lshl_add_u64 v[222:223], v[128:129], 0, s[2:3]
	s_add_i32 m0, s27, 0xc000
	ds_read_b128 v[190:193], v180
	ds_read_b128 v[194:197], v180 offset:1024
	ds_read_b128 v[198:201], v180 offset:2048
	ds_read_b128 v[204:207], v180 offset:3072
	ds_read_b128 v[218:221], v180 offset:4096
	ds_read_b128 v[238:241], v180 offset:5120
	ds_read_b128 v[242:245], v180 offset:6144
	ds_read_b128 v[246:249], v180 offset:7168
	global_load_lds_dwordx4 v[222:223], off
	v_lshl_add_u64 v[222:223], v[130:131], 0, s[2:3]
	s_add_i32 m0, s27, 0xe000
	s_nop 0
	global_load_lds_dwordx4 v[222:223], off
	s_waitcnt vmcnt(8)
	s_waitcnt lgkmcnt(0)
	s_barrier
	s_setprio 1
	s_waitcnt lgkmcnt(0)
	v_mfma_f32_16x16x32_bf16 v[124:127], v[132:135], v[190:193], v[124:127]
	v_mfma_f32_16x16x32_bf16 v[120:123], v[140:143], v[190:193], v[120:123]
	v_mfma_f32_16x16x32_bf16 v[108:111], v[132:135], v[198:201], v[108:111]
	v_mfma_f32_16x16x32_bf16 v[104:107], v[140:143], v[198:201], v[104:107]
	v_mfma_f32_16x16x32_bf16 v[92:95], v[132:135], v[218:221], v[92:95]
	v_mfma_f32_16x16x32_bf16 v[88:91], v[140:143], v[218:221], v[88:91]
	v_mfma_f32_16x16x32_bf16 v[76:79], v[132:135], v[242:245], v[76:79]
	v_mfma_f32_16x16x32_bf16 v[72:75], v[140:143], v[242:245], v[72:75]
	v_mfma_f32_16x16x32_bf16 v[124:127], v[136:139], v[194:197], v[124:127]
	v_mfma_f32_16x16x32_bf16 v[120:123], v[158:161], v[194:197], v[120:123]
	v_mfma_f32_16x16x32_bf16 v[108:111], v[136:139], v[204:207], v[108:111]
	v_mfma_f32_16x16x32_bf16 v[104:107], v[158:161], v[204:207], v[104:107]
	v_mfma_f32_16x16x32_bf16 v[92:95], v[136:139], v[238:241], v[92:95]
	v_mfma_f32_16x16x32_bf16 v[88:91], v[158:161], v[238:241], v[88:91]
	v_mfma_f32_16x16x32_bf16 v[76:79], v[136:139], v[246:249], v[76:79]
	v_mfma_f32_16x16x32_bf16 v[72:75], v[158:161], v[246:249], v[72:75]
	s_setprio 0
	s_setprio 1
	v_mfma_f32_16x16x32_bf16 v[116:119], v[162:165], v[190:193], v[116:119]
	v_mfma_f32_16x16x32_bf16 v[112:115], v[182:185], v[190:193], v[112:115]
	v_mfma_f32_16x16x32_bf16 v[100:103], v[162:165], v[198:201], v[100:103]
	v_mfma_f32_16x16x32_bf16 v[96:99], v[182:185], v[198:201], v[96:99]
	v_mfma_f32_16x16x32_bf16 v[84:87], v[162:165], v[218:221], v[84:87]
	v_mfma_f32_16x16x32_bf16 v[80:83], v[182:185], v[218:221], v[80:83]
	v_mfma_f32_16x16x32_bf16 v[68:71], v[162:165], v[242:245], v[68:71]
	v_mfma_f32_16x16x32_bf16 v[64:67], v[182:185], v[242:245], v[64:67]
	v_mfma_f32_16x16x32_bf16 v[116:119], v[166:169], v[194:197], v[116:119]
	v_mfma_f32_16x16x32_bf16 v[112:115], v[186:189], v[194:197], v[112:115]
	v_mfma_f32_16x16x32_bf16 v[100:103], v[166:169], v[204:207], v[100:103]
	v_mfma_f32_16x16x32_bf16 v[96:99], v[186:189], v[204:207], v[96:99]
	v_mfma_f32_16x16x32_bf16 v[84:87], v[166:169], v[238:241], v[84:87]
	v_mfma_f32_16x16x32_bf16 v[80:83], v[186:189], v[238:241], v[80:83]
	v_mfma_f32_16x16x32_bf16 v[68:71], v[166:169], v[246:249], v[68:71]
	v_mfma_f32_16x16x32_bf16 v[64:67], v[186:189], v[246:249], v[64:67]
	s_setprio 0
	s_barrier
	s_add_i32 s85, s85, s52
	v_lshl_add_u64 v[222:223], s[46:47], 0, v[146:147]
	s_mov_b32 m0, s85
	ds_read_b128 v[190:193], v180 offset:16384
	ds_read_b128 v[194:197], v180 offset:17408
	ds_read_b128 v[198:201], v180 offset:18432
	ds_read_b128 v[204:207], v180 offset:19456
	ds_read_b128 v[218:221], v180 offset:20480
	ds_read_b128 v[238:241], v180 offset:21504
	ds_read_b128 v[242:245], v180 offset:22528
	ds_read_b128 v[246:249], v180 offset:23552
	global_load_lds_dwordx4 v[222:223], off
	s_add_i32 m0, s85, 0x2000
	s_add_u32 s86, s46, 0x40000
	v_lshl_add_u64 v[224:225], s[46:47], 0, v[150:151]
	s_addc_u32 s87, s47, 0
	s_add_i32 s85, s88, s52
	global_load_lds_dwordx4 v[224:225], off
	v_lshl_add_u64 v[250:251], s[86:87], 0, v[146:147]
	s_mov_b32 m0, s85
	s_nop 0
	global_load_lds_dwordx4 v[250:251], off
	v_lshl_add_u64 v[250:251], s[86:87], 0, v[150:151]
	s_add_i32 m0, s85, 0x2000
	s_nop 0
	global_load_lds_dwordx4 v[250:251], off
	s_waitcnt vmcnt(6)
	s_waitcnt lgkmcnt(0)
	s_barrier
; #define PG8_STAGE(bufoff, gbase, voff) do { _Pragma("unroll") for (int _i = 0; _i < 2; ++_i) \
;         __builtin_amdgcn_global_load_lds((const unsigned*)((const char*)(gbase) + (voff)[_i]), (PG8_LAS unsigned*)(lds + (bufoff) + ldsw + _i * 8192), 16, 0, 0); } while (0)
; #define PG8_LDA(dst, b, h) do { _Pragma("unroll") for (int m = 0; m < 4; ++m) _Pragma("unroll") for (int k = 0; k < 2; ++k) dst[m][k] = *(const PG8_LAS bf16x8*)(lds + PG8_SA(b, h) + aoff + m * 2048 + k * 1024); } while (0)
; #define PG8_LDB(dst, b, h) do { _Pragma("unroll") for (int n = 0; n < 2; ++n) _Pragma("unroll") for (int k = 0; k < 2; ++k) dst[n][k] = *(const PG8_LAS bf16x8*)(lds + PG8_SB(b, h) + boff + n * 2048 + k * 1024); } while (0)
; #define PG8_MMA(ai, bj, At, Bt) do { __builtin_amdgcn_s_setprio(1); _Pragma("unroll") for (int m = 0; m < 4; ++m) _Pragma("unroll") for (int n = 0; n < 2; ++n) _Pragma("unroll") for (int k = 0; k < 2; ++k) \
;         acc[ai][bj][m][n] = __builtin_amdgcn_mfma_f32_16x16x32_bf16(Bt[n][k], At[m][k], acc[ai][bj][m][n], 0, 0, 0); __builtin_amdgcn_s_setprio(0); } while (0)
; #define PG8_WAIT_V(n) asm volatile("s_waitcnt vmcnt(" #n ")" ::: "memory")
; #define PG8_WAIT_L(n) asm volatile("s_waitcnt lgkmcnt(" #n ")" ::: "memory")
; #define PG8_BAR __builtin_amdgcn_s_barrier()
; #define PG8_SCHED __builtin_amdgcn_sched_barrier(0)
;     ...
;             PG8_WAIT_V(8); PG8_WAIT_L(0); PG8_BAR; PG8_MMA(1, 0, At, B0); PG8_MMA(1, 1, At, B1); PG8_BAR; PG8_SCHED;
;             PG8_LDB(B0, 1, 0); PG8_LDB(B1, 1, 1); PG8_SCHED; PG8_LDA(At, 1, 0); PG8_STAGE(PG8_SA(0, 1), a2 + hstepA, voffA);
;             PG8_WAIT_V(8); PG8_WAIT_L(0); PG8_BAR; PG8_MMA(0, 0, At, B0); PG8_MMA(0, 1, At, B1); PG8_BAR; PG8_SCHED;
	s_setprio 1
	s_waitcnt lgkmcnt(0)
	v_mfma_f32_16x16x32_bf16 v[60:63], v[132:135], v[190:193], v[60:63]
	v_mfma_f32_16x16x32_bf16 v[56:59], v[140:143], v[190:193], v[56:59]
	v_mfma_f32_16x16x32_bf16 v[44:47], v[132:135], v[198:201], v[44:47]
	v_mfma_f32_16x16x32_bf16 v[40:43], v[140:143], v[198:201], v[40:43]
	v_mfma_f32_16x16x32_bf16 v[28:31], v[132:135], v[218:221], v[28:31]
	v_mfma_f32_16x16x32_bf16 v[24:27], v[140:143], v[218:221], v[24:27]
	v_mfma_f32_16x16x32_bf16 v[12:15], v[132:135], v[242:245], v[12:15]
	v_mfma_f32_16x16x32_bf16 v[8:11], v[140:143], v[242:245], v[8:11]
	v_mfma_f32_16x16x32_bf16 v[60:63], v[136:139], v[194:197], v[60:63]
	v_mfma_f32_16x16x32_bf16 v[56:59], v[158:161], v[194:197], v[56:59]
	v_mfma_f32_16x16x32_bf16 v[44:47], v[136:139], v[204:207], v[44:47]
	v_mfma_f32_16x16x32_bf16 v[40:43], v[158:161], v[204:207], v[40:43]
	v_mfma_f32_16x16x32_bf16 v[28:31], v[136:139], v[238:241], v[28:31]
	v_mfma_f32_16x16x32_bf16 v[24:27], v[158:161], v[238:241], v[24:27]
	v_mfma_f32_16x16x32_bf16 v[12:15], v[136:139], v[246:249], v[12:15]
	v_mfma_f32_16x16x32_bf16 v[8:11], v[158:161], v[246:249], v[8:11]
	s_setprio 0
	s_setprio 1
	v_mfma_f32_16x16x32_bf16 v[52:55], v[162:165], v[190:193], v[52:55]
	v_mfma_f32_16x16x32_bf16 v[48:51], v[182:185], v[190:193], v[48:51]
	v_mfma_f32_16x16x32_bf16 v[36:39], v[162:165], v[198:201], v[36:39]
	v_mfma_f32_16x16x32_bf16 v[32:35], v[182:185], v[198:201], v[32:35]
	v_mfma_f32_16x16x32_bf16 v[20:23], v[162:165], v[218:221], v[20:23]
	v_mfma_f32_16x16x32_bf16 v[16:19], v[182:185], v[218:221], v[16:19]
	v_mfma_f32_16x16x32_bf16 v[4:7], v[162:165], v[242:245], v[4:7]
	v_mfma_f32_16x16x32_bf16 v[0:3], v[182:185], v[242:245], v[0:3]
	v_mfma_f32_16x16x32_bf16 v[52:55], v[166:169], v[194:197], v[52:55]
	v_mfma_f32_16x16x32_bf16 v[48:51], v[186:189], v[194:197], v[48:51]
	v_mfma_f32_16x16x32_bf16 v[36:39], v[166:169], v[204:207], v[36:39]
	v_mfma_f32_16x16x32_bf16 v[32:35], v[186:189], v[204:207], v[32:35]
	v_mfma_f32_16x16x32_bf16 v[20:23], v[166:169], v[238:241], v[20:23]
	v_mfma_f32_16x16x32_bf16 v[16:19], v[186:189], v[238:241], v[16:19]
	v_mfma_f32_16x16x32_bf16 v[4:7], v[166:169], v[246:249], v[4:7]
	v_mfma_f32_16x16x32_bf16 v[0:3], v[186:189], v[246:249], v[0:3]
	v_lshl_add_u64 v[250:251], s[48:49], 0, v[144:145]
	s_mov_b32 m0, s27
	s_nop 0
	global_load_lds_dwordx4 v[250:251], off
	v_lshl_add_u64 v[250:251], s[48:49], 0, v[148:149]
	s_mov_b32 m0, s57
	s_nop 0
	global_load_lds_dwordx4 v[250:251], off
	s_setprio 0
	s_barrier
	s_add_i32 s85, 0, 0x18000
	s_add_i32 s86, 0, 0x1c000
	v_add_u32_e32 v158, s85, v174
	v_add_u32_e32 v186, s86, v174
	ds_read_b128 v[132:135], v158
	ds_read_b128 v[136:139], v158 offset:1024
	ds_read_b128 v[140:143], v158 offset:2048
	ds_read_b128 v[158:161], v158 offset:3072
	ds_read_b128 v[162:165], v186
	ds_read_b128 v[166:169], v186 offset:1024
	ds_read_b128 v[182:185], v186 offset:2048
	ds_read_b128 v[186:189], v186 offset:3072
	s_add_u32 s48, s48, 0x40000
	s_addc_u32 s49, s49, 0
	s_mov_b32 m0, s58
	v_lshl_add_u64 v[250:251], s[48:49], 0, v[144:145]
	ds_read_b128 v[190:193], v180 offset:32768
	ds_read_b128 v[194:197], v180 offset:33792
	ds_read_b128 v[198:201], v180 offset:34816
	ds_read_b128 v[204:207], v180 offset:35840
	ds_read_b128 v[218:221], v180 offset:36864
	ds_read_b128 v[238:241], v180 offset:37888
	ds_read_b128 v[242:245], v180 offset:38912
	ds_read_b128 v[246:249], v180 offset:39936
	global_load_lds_dwordx4 v[250:251], off
	v_lshl_add_u64 v[250:251], s[48:49], 0, v[148:149]
	s_mov_b32 m0, s59
	s_nop 0
	global_load_lds_dwordx4 v[250:251], off
	s_waitcnt vmcnt(8)
	s_waitcnt lgkmcnt(0)
	s_barrier
	s_setprio 1
	s_waitcnt lgkmcnt(0)
	v_mfma_f32_16x16x32_bf16 v[124:127], v[132:135], v[190:193], v[124:127]
	v_mfma_f32_16x16x32_bf16 v[120:123], v[140:143], v[190:193], v[120:123]
	v_mfma_f32_16x16x32_bf16 v[108:111], v[132:135], v[198:201], v[108:111]
	v_mfma_f32_16x16x32_bf16 v[104:107], v[140:143], v[198:201], v[104:107]
	v_mfma_f32_16x16x32_bf16 v[92:95], v[132:135], v[218:221], v[92:95]
	v_mfma_f32_16x16x32_bf16 v[88:91], v[140:143], v[218:221], v[88:91]
	v_mfma_f32_16x16x32_bf16 v[76:79], v[132:135], v[242:245], v[76:79]
	v_mfma_f32_16x16x32_bf16 v[72:75], v[140:143], v[242:245], v[72:75]
	v_mfma_f32_16x16x32_bf16 v[124:127], v[136:139], v[194:197], v[124:127]
	v_mfma_f32_16x16x32_bf16 v[120:123], v[158:161], v[194:197], v[120:123]
	v_mfma_f32_16x16x32_bf16 v[108:111], v[136:139], v[204:207], v[108:111]
	v_mfma_f32_16x16x32_bf16 v[104:107], v[158:161], v[204:207], v[104:107]
	v_mfma_f32_16x16x32_bf16 v[92:95], v[136:139], v[238:241], v[92:95]
	v_mfma_f32_16x16x32_bf16 v[88:91], v[158:161], v[238:241], v[88:91]
	v_mfma_f32_16x16x32_bf16 v[76:79], v[136:139], v[246:249], v[76:79]
	v_mfma_f32_16x16x32_bf16 v[72:75], v[158:161], v[246:249], v[72:75]
	s_setprio 0
	s_setprio 1
	v_mfma_f32_16x16x32_bf16 v[116:119], v[162:165], v[190:193], v[116:119]
	v_mfma_f32_16x16x32_bf16 v[112:115], v[182:185], v[190:193], v[112:115]
	v_mfma_f32_16x16x32_bf16 v[100:103], v[162:165], v[198:201], v[100:103]
	v_mfma_f32_16x16x32_bf16 v[96:99], v[182:185], v[198:201], v[96:99]
	v_mfma_f32_16x16x32_bf16 v[84:87], v[162:165], v[218:221], v[84:87]
	v_mfma_f32_16x16x32_bf16 v[80:83], v[182:185], v[218:221], v[80:83]
	v_mfma_f32_16x16x32_bf16 v[68:71], v[162:165], v[242:245], v[68:71]
	v_mfma_f32_16x16x32_bf16 v[64:67], v[182:185], v[242:245], v[64:67]
	v_mfma_f32_16x16x32_bf16 v[116:119], v[166:169], v[194:197], v[116:119]
	v_mfma_f32_16x16x32_bf16 v[112:115], v[186:189], v[194:197], v[112:115]
	v_mfma_f32_16x16x32_bf16 v[100:103], v[166:169], v[204:207], v[100:103]
	v_mfma_f32_16x16x32_bf16 v[96:99], v[186:189], v[204:207], v[96:99]
	v_mfma_f32_16x16x32_bf16 v[84:87], v[166:169], v[238:241], v[84:87]
	v_mfma_f32_16x16x32_bf16 v[80:83], v[186:189], v[238:241], v[80:83]
	v_mfma_f32_16x16x32_bf16 v[68:71], v[166:169], v[246:249], v[68:71]
	v_mfma_f32_16x16x32_bf16 v[64:67], v[186:189], v[246:249], v[64:67]
	s_setprio 0
	s_barrier
; #define PG8_STAGE(bufoff, gbase, voff) do { _Pragma("unroll") for (int _i = 0; _i < 2; ++_i) \
;         __builtin_amdgcn_global_load_lds((const unsigned*)((const char*)(gbase) + (voff)[_i]), (PG8_LAS unsigned*)(lds + (bufoff) + ldsw + _i * 8192), 16, 0, 0); } while (0)
; #define PG8_LDA(dst, b, h) do { _Pragma("unroll") for (int m = 0; m < 4; ++m) _Pragma("unroll") for (int k = 0; k < 2; ++k) dst[m][k] = *(const PG8_LAS bf16x8*)(lds + PG8_SA(b, h) + aoff + m * 2048 + k * 1024); } while (0)
; #define PG8_MMA(ai, bj, At, Bt) do { __builtin_amdgcn_s_setprio(1); _Pragma("unroll") for (int m = 0; m < 4; ++m) _Pragma("unroll") for (int n = 0; n < 2; ++n) _Pragma("unroll") for (int k = 0; k < 2; ++k) \
;         acc[ai][bj][m][n] = __builtin_amdgcn_mfma_f32_16x16x32_bf16(Bt[n][k], At[m][k], acc[ai][bj][m][n], 0, 0, 0); __builtin_amdgcn_s_setprio(0); } while (0)
; #define PG8_WAIT_V(n) asm volatile("s_waitcnt vmcnt(" #n ")" ::: "memory")
; #define PG8_WAIT_L(n) asm volatile("s_waitcnt lgkmcnt(" #n ")" ::: "memory")
; #define PG8_BAR __builtin_amdgcn_s_barrier()
; #define PG8_SCHED __builtin_amdgcn_sched_barrier(0)
;     ...
;             PG8_LDA(At, 1, 1); PG8_STAGE(PG8_SB(1, 0), b3, voffB); PG8_STAGE(PG8_SB(1, 1), b3 + hstepB, voffB); PG8_STAGE(PG8_SA(1, 0), a3, voffA);
;             PG8_WAIT_V(8); PG8_WAIT_L(0); PG8_BAR; PG8_MMA(1, 0, At, B0); PG8_MMA(1, 1, At, B1); PG8_BAR; PG8_SCHED;
;         }
;         if (wr == 0) PG8_BAR;
;         if (!has_next && wmat && gtid * 128u < wbytes) asm volatile("global_load_dword %0, %1, off" : "+v"(warmm) : "v"(wmat + (size_t)gtid * 128u) : "memory");
	s_add_i32 s48, s85, s52
	v_lshl_add_u64 v[222:223], v[222:223], 0, s[90:91]
	s_mov_b32 m0, s48
	ds_read_b128 v[190:193], v180 offset:49152
	ds_read_b128 v[194:197], v180 offset:50176
	ds_read_b128 v[198:201], v180 offset:51200
	ds_read_b128 v[204:207], v180 offset:52224
	ds_read_b128 v[218:221], v180 offset:53248
	ds_read_b128 v[238:241], v180 offset:54272
	ds_read_b128 v[242:245], v180 offset:55296
	ds_read_b128 v[246:249], v180 offset:56320
	global_load_lds_dwordx4 v[222:223], off
	s_add_i32 m0, s48, 0x2000
	s_add_u32 s46, s46, 0x40080
	v_lshl_add_u64 v[222:223], v[224:225], 0, s[90:91]
	s_addc_u32 s47, s47, 0
	s_add_i32 s48, s86, s52
	global_load_lds_dwordx4 v[222:223], off
	v_lshl_add_u64 v[222:223], s[46:47], 0, v[146:147]
	s_mov_b32 m0, s48
	s_nop 0
	global_load_lds_dwordx4 v[222:223], off
	v_lshl_add_u64 v[222:223], s[46:47], 0, v[150:151]
	s_add_i32 m0, s48, 0x2000
	s_nop 0
	global_load_lds_dwordx4 v[222:223], off
	s_waitcnt vmcnt(6)
	s_waitcnt lgkmcnt(0)
	s_barrier
	s_setprio 1
	s_waitcnt lgkmcnt(0)
	v_mfma_f32_16x16x32_bf16 v[60:63], v[132:135], v[190:193], v[60:63]
	v_mfma_f32_16x16x32_bf16 v[56:59], v[140:143], v[190:193], v[56:59]
	v_mfma_f32_16x16x32_bf16 v[44:47], v[132:135], v[198:201], v[44:47]
	v_mfma_f32_16x16x32_bf16 v[40:43], v[140:143], v[198:201], v[40:43]
	v_mfma_f32_16x16x32_bf16 v[28:31], v[132:135], v[218:221], v[28:31]
	v_mfma_f32_16x16x32_bf16 v[24:27], v[140:143], v[218:221], v[24:27]
	v_mfma_f32_16x16x32_bf16 v[12:15], v[132:135], v[242:245], v[12:15]
	v_mfma_f32_16x16x32_bf16 v[8:11], v[140:143], v[242:245], v[8:11]
	v_mfma_f32_16x16x32_bf16 v[60:63], v[136:139], v[194:197], v[60:63]
	v_mfma_f32_16x16x32_bf16 v[56:59], v[158:161], v[194:197], v[56:59]
	v_mfma_f32_16x16x32_bf16 v[44:47], v[136:139], v[204:207], v[44:47]
	v_mfma_f32_16x16x32_bf16 v[40:43], v[158:161], v[204:207], v[40:43]
	v_mfma_f32_16x16x32_bf16 v[28:31], v[136:139], v[238:241], v[28:31]
	v_mfma_f32_16x16x32_bf16 v[24:27], v[158:161], v[238:241], v[24:27]
	v_mfma_f32_16x16x32_bf16 v[12:15], v[136:139], v[246:249], v[12:15]
	v_mfma_f32_16x16x32_bf16 v[8:11], v[158:161], v[246:249], v[8:11]
	s_setprio 0
	s_setprio 1
	v_mfma_f32_16x16x32_bf16 v[52:55], v[162:165], v[190:193], v[52:55]
	v_mfma_f32_16x16x32_bf16 v[48:51], v[182:185], v[190:193], v[48:51]
	v_mfma_f32_16x16x32_bf16 v[36:39], v[162:165], v[198:201], v[36:39]
	v_mfma_f32_16x16x32_bf16 v[32:35], v[182:185], v[198:201], v[32:35]
	v_mfma_f32_16x16x32_bf16 v[20:23], v[162:165], v[218:221], v[20:23]
	v_mfma_f32_16x16x32_bf16 v[16:19], v[182:185], v[218:221], v[16:19]
	v_mfma_f32_16x16x32_bf16 v[4:7], v[162:165], v[242:245], v[4:7]
	v_mfma_f32_16x16x32_bf16 v[0:3], v[182:185], v[242:245], v[0:3]
	v_mfma_f32_16x16x32_bf16 v[52:55], v[166:169], v[194:197], v[52:55]
	v_mfma_f32_16x16x32_bf16 v[48:51], v[186:189], v[194:197], v[48:51]
	v_mfma_f32_16x16x32_bf16 v[36:39], v[166:169], v[204:207], v[36:39]
	v_mfma_f32_16x16x32_bf16 v[32:35], v[186:189], v[204:207], v[32:35]
	v_mfma_f32_16x16x32_bf16 v[20:23], v[166:169], v[238:241], v[20:23]
	v_mfma_f32_16x16x32_bf16 v[16:19], v[186:189], v[238:241], v[16:19]
	v_mfma_f32_16x16x32_bf16 v[4:7], v[166:169], v[246:249], v[4:7]
	v_mfma_f32_16x16x32_bf16 v[0:3], v[186:189], v[246:249], v[0:3]
	v_lshl_add_u64 v[222:223], s[28:29], 0, v[144:145]
	s_mov_b32 m0, s60
	s_nop 0
	global_load_lds_dwordx4 v[222:223], off
	v_lshl_add_u64 v[222:223], s[28:29], 0, v[148:149]
	s_mov_b32 m0, s61
	s_nop 0
	global_load_lds_dwordx4 v[222:223], off
	s_setprio 0
	s_barrier
	s_add_i32 s84, s84, 2
	s_add_u32 s2, s2, 0x100
	s_addc_u32 s3, s3, 0
	s_cmp_gt_u32 s84, 13
	s_cbranch_scc0 .LBB0_380
	s_and_b64 vcc, exec, s[30:31]
	s_cbranch_vccz .LBB0_385
	s_barrier
	s_and_b64 s[28:29], s[20:21], s[44:45]
	s_and_saveexec_b64 s[2:3], s[28:29]
	s_cbranch_execnz .LBB0_386

;     __device__ __forceinline__ const char* tile(const Unit& u, int t) const { return A + (size_t)u.pm * 2 * hstep() + (size_t)t * (BK * 2); }
;     __device__ __forceinline__ const char* tile(const Unit& u, int t) const { return U + (long)(t >> 2) * xoff + (size_t)u.pn * (1024 * 512) + (size_t)u.pm * 2 * hstep() + (size_t)(t & 3) * (BK * 2); }
; #define PG8_STAGE(bufoff, gbase, voff) do { _Pragma("unroll") for (int _i = 0; _i < 2; ++_i) \
;         __builtin_amdgcn_global_load_lds((const unsigned*)((const char*)(gbase) + (voff)[_i]), (PG8_LAS unsigned*)(lds + (bufoff) + ldsw + _i * 8192), 16, 0, 0); } while (0)
; #define PG8_LDA(dst, b, h) do { _Pragma("unroll") for (int m = 0; m < 4; ++m) _Pragma("unroll") for (int k = 0; k < 2; ++k) dst[m][k] = *(const PG8_LAS bf16x8*)(lds + PG8_SA(b, h) + aoff + m * 2048 + k * 1024); } while (0)
; #define PG8_LDB(dst, b, h) do { _Pragma("unroll") for (int n = 0; n < 2; ++n) _Pragma("unroll") for (int k = 0; k < 2; ++k) dst[n][k] = *(const PG8_LAS bf16x8*)(lds + PG8_SB(b, h) + boff + n * 2048 + k * 1024); } while (0)
; #define PG8_MMA(ai, bj, At, Bt) do { __builtin_amdgcn_s_setprio(1); _Pragma("unroll") for (int m = 0; m < 4; ++m) _Pragma("unroll") for (int n = 0; n < 2; ++n) _Pragma("unroll") for (int k = 0; k < 2; ++k) \
;         acc[ai][bj][m][n] = __builtin_amdgcn_mfma_f32_16x16x32_bf16(Bt[n][k], At[m][k], acc[ai][bj][m][n], 0, 0, 0); __builtin_amdgcn_s_setprio(0); } while (0)
; #define PG8_WAIT_V(n) asm volatile("s_waitcnt vmcnt(" #n ")" ::: "memory")
;     ...
;             const bool last = (t == nt - 2);
;             const char* a1 = AS.tile(cur, t + 1);
;             const char* a2 = last ? AS.tile(nu, 0) : AS.tile(cur, t + 2); const char* b2 = last ? nB : cB + (size_t)(t + 2) * kstep;
;             const char* a3 = last ? AS.tile(nu, 1) : AS.tile(cur, t + 3); const char* b3 = b2 + kstep;
;             PG8_LDB(B0, 0, 0); PG8_LDB(B1, 0, 1); PG8_SCHED; PG8_LDA(At, 0, 0); PG8_STAGE(PG8_SA(1, 1), a1 + hstepA, voffA);
;             PG8_WAIT_V(8); PG8_WAIT_L(0); PG8_BAR; PG8_MMA(0, 0, At, B0); PG8_MMA(0, 1, At, B1); PG8_BAR; PG8_SCHED;
;             PG8_LDA(At, 0, 1); PG8_STAGE(PG8_SB(0, 0), b2, voffB); PG8_STAGE(PG8_SB(0, 1), b2 + hstepB, voffB); PG8_STAGE(PG8_SA(0, 0), a2, voffA);
;             PG8_WAIT_V(8); PG8_WAIT_L(0); PG8_BAR; PG8_MMA(1, 0, At, B0); PG8_MMA(1, 1, At, B1); PG8_BAR; PG8_SCHED;
.LBB0_451:
	s_add_u32 s20, s61, s18
	s_addc_u32 s21, s64, s19
	s_add_u32 s26, s20, 0x3600100
	s_addc_u32 s27, s21, 0
	s_add_u32 s24, s65, s18
	s_addc_u32 s25, s66, s19
	s_add_u32 s20, s20, 0x3600180
	s_addc_u32 s21, s21, 0
	s_add_i32 s68, 0, 0x10000
	s_add_i32 s70, 0, 0x14000
	v_add_u32_e32 v144, s68, v203
	v_add_u32_e32 v174, s70, v203
	ds_read_b128 v[132:135], v144
	ds_read_b128 v[136:139], v144 offset:1024
	ds_read_b128 v[140:143], v144 offset:2048
	ds_read_b128 v[144:147], v144 offset:3072
	ds_read_b128 v[148:151], v174
	ds_read_b128 v[152:155], v174 offset:1024
	ds_read_b128 v[170:173], v174 offset:2048
	ds_read_b128 v[174:177], v174 offset:3072
	s_cmpk_eq_i32 s18, 0x700
	s_cselect_b32 s21, s60, s21
	s_cselect_b32 s20, s59, s20
	s_cselect_b32 s25, s57, s25
	s_cselect_b32 s24, s56, s24
	s_cselect_b32 s27, s58, s27
	s_cselect_b32 s26, s3, s26
	v_lshl_add_u64 v[238:239], v[112:113], 0, s[18:19]
	s_add_i32 m0, s35, 0xc000
	ds_read_b128 v[178:181], v211
	ds_read_b128 v[182:185], v211 offset:1024
	ds_read_b128 v[186:189], v211 offset:2048
	ds_read_b128 v[190:193], v211 offset:3072
	ds_read_b128 v[194:197], v211 offset:4096
	ds_read_b128 v[198:201], v211 offset:5120
	ds_read_b128 v[218:221], v211 offset:6144
	ds_read_b128 v[222:225], v211 offset:7168
	global_load_lds_dwordx4 v[238:239], off
	v_lshl_add_u64 v[238:239], v[114:115], 0, s[18:19]
	s_add_i32 m0, s35, 0xe000
	s_nop 0
	global_load_lds_dwordx4 v[238:239], off
	s_waitcnt vmcnt(8)
	s_waitcnt lgkmcnt(0)
	s_barrier
	s_setprio 1
	s_waitcnt lgkmcnt(0)
	v_mfma_f32_16x16x32_bf16 v[120:123], v[132:135], v[178:181], v[120:123]
	v_mfma_f32_16x16x32_bf16 v[116:119], v[140:143], v[178:181], v[116:119]
	v_mfma_f32_16x16x32_bf16 v[108:111], v[132:135], v[186:189], v[108:111]
	v_mfma_f32_16x16x32_bf16 v[104:107], v[140:143], v[186:189], v[104:107]
	v_mfma_f32_16x16x32_bf16 v[92:95], v[132:135], v[194:197], v[92:95]
	v_mfma_f32_16x16x32_bf16 v[88:91], v[140:143], v[194:197], v[88:91]
	v_mfma_f32_16x16x32_bf16 v[76:79], v[132:135], v[218:221], v[76:79]
	v_mfma_f32_16x16x32_bf16 v[72:75], v[140:143], v[218:221], v[72:75]
	v_mfma_f32_16x16x32_bf16 v[120:123], v[136:139], v[182:185], v[120:123]
	v_mfma_f32_16x16x32_bf16 v[116:119], v[144:147], v[182:185], v[116:119]
	v_mfma_f32_16x16x32_bf16 v[108:111], v[136:139], v[190:193], v[108:111]
	v_mfma_f32_16x16x32_bf16 v[104:107], v[144:147], v[190:193], v[104:107]
	v_mfma_f32_16x16x32_bf16 v[92:95], v[136:139], v[198:201], v[92:95]
	v_mfma_f32_16x16x32_bf16 v[88:91], v[144:147], v[198:201], v[88:91]
	v_mfma_f32_16x16x32_bf16 v[76:79], v[136:139], v[222:225], v[76:79]
	v_mfma_f32_16x16x32_bf16 v[72:75], v[144:147], v[222:225], v[72:75]
	s_setprio 0
	s_setprio 1
	v_mfma_f32_16x16x32_bf16 v[128:131], v[148:151], v[178:181], v[128:131]
	v_mfma_f32_16x16x32_bf16 v[124:127], v[170:173], v[178:181], v[124:127]
	v_mfma_f32_16x16x32_bf16 v[100:103], v[148:151], v[186:189], v[100:103]
	v_mfma_f32_16x16x32_bf16 v[96:99], v[170:173], v[186:189], v[96:99]
	v_mfma_f32_16x16x32_bf16 v[84:87], v[148:151], v[194:197], v[84:87]
	v_mfma_f32_16x16x32_bf16 v[80:83], v[170:173], v[194:197], v[80:83]
	v_mfma_f32_16x16x32_bf16 v[68:71], v[148:151], v[218:221], v[68:71]
	v_mfma_f32_16x16x32_bf16 v[64:67], v[170:173], v[218:221], v[64:67]
	v_mfma_f32_16x16x32_bf16 v[128:131], v[152:155], v[182:185], v[128:131]
	v_mfma_f32_16x16x32_bf16 v[124:127], v[174:177], v[182:185], v[124:127]
	v_mfma_f32_16x16x32_bf16 v[100:103], v[152:155], v[190:193], v[100:103]
	v_mfma_f32_16x16x32_bf16 v[96:99], v[174:177], v[190:193], v[96:99]
	v_mfma_f32_16x16x32_bf16 v[84:87], v[152:155], v[198:201], v[84:87]
	v_mfma_f32_16x16x32_bf16 v[80:83], v[174:177], v[198:201], v[80:83]
	v_mfma_f32_16x16x32_bf16 v[68:71], v[152:155], v[222:225], v[68:71]
	v_mfma_f32_16x16x32_bf16 v[64:67], v[174:177], v[222:225], v[64:67]
	s_setprio 0
	s_barrier
	s_add_i32 s68, s68, s31
	v_lshl_add_u64 v[238:239], s[24:25], 0, v[208:209]
	s_mov_b32 m0, s68
	ds_read_b128 v[178:181], v211 offset:16384
	ds_read_b128 v[182:185], v211 offset:17408
	ds_read_b128 v[186:189], v211 offset:18432
	ds_read_b128 v[190:193], v211 offset:19456
	ds_read_b128 v[194:197], v211 offset:20480
	ds_read_b128 v[198:201], v211 offset:21504
	ds_read_b128 v[218:221], v211 offset:22528
	ds_read_b128 v[222:225], v211 offset:23552
	global_load_lds_dwordx4 v[238:239], off
	s_add_i32 m0, s68, 0x2000
	s_add_u32 s68, s24, 0x40000
	v_lshl_add_u64 v[240:241], s[24:25], 0, v[156:157]
	s_addc_u32 s69, s25, 0
	s_add_i32 s70, s70, s31
	global_load_lds_dwordx4 v[240:241], off
	v_lshl_add_u64 v[242:243], s[68:69], 0, v[208:209]
	s_mov_b32 m0, s70
	s_nop 0
	global_load_lds_dwordx4 v[242:243], off
	v_lshl_add_u64 v[242:243], s[68:69], 0, v[156:157]
	s_add_i32 m0, s70, 0x2000
	s_nop 0
	global_load_lds_dwordx4 v[242:243], off
	s_waitcnt vmcnt(6)
	s_waitcnt lgkmcnt(0)
	s_barrier
; #define PG8_STAGE(bufoff, gbase, voff) do { _Pragma("unroll") for (int _i = 0; _i < 2; ++_i) \
;         __builtin_amdgcn_global_load_lds((const unsigned*)((const char*)(gbase) + (voff)[_i]), (PG8_LAS unsigned*)(lds + (bufoff) + ldsw + _i * 8192), 16, 0, 0); } while (0)
; #define PG8_LDA(dst, b, h) do { _Pragma("unroll") for (int m = 0; m < 4; ++m) _Pragma("unroll") for (int k = 0; k < 2; ++k) dst[m][k] = *(const PG8_LAS bf16x8*)(lds + PG8_SA(b, h) + aoff + m * 2048 + k * 1024); } while (0)
; #define PG8_LDB(dst, b, h) do { _Pragma("unroll") for (int n = 0; n < 2; ++n) _Pragma("unroll") for (int k = 0; k < 2; ++k) dst[n][k] = *(const PG8_LAS bf16x8*)(lds + PG8_SB(b, h) + boff + n * 2048 + k * 1024); } while (0)
; #define PG8_MMA(ai, bj, At, Bt) do { __builtin_amdgcn_s_setprio(1); _Pragma("unroll") for (int m = 0; m < 4; ++m) _Pragma("unroll") for (int n = 0; n < 2; ++n) _Pragma("unroll") for (int k = 0; k < 2; ++k) \
;         acc[ai][bj][m][n] = __builtin_amdgcn_mfma_f32_16x16x32_bf16(Bt[n][k], At[m][k], acc[ai][bj][m][n], 0, 0, 0); __builtin_amdgcn_s_setprio(0); } while (0)
; #define PG8_WAIT_V(n) asm volatile("s_waitcnt vmcnt(" #n ")" ::: "memory")
; #define PG8_WAIT_L(n) asm volatile("s_waitcnt lgkmcnt(" #n ")" ::: "memory")
; #define PG8_BAR __builtin_amdgcn_s_barrier()
; #define PG8_SCHED __builtin_amdgcn_sched_barrier(0)
;     ...
;             PG8_LDA(At, 0, 1); PG8_STAGE(PG8_SB(0, 0), b2, voffB); PG8_STAGE(PG8_SB(0, 1), b2 + hstepB, voffB); PG8_STAGE(PG8_SA(0, 0), a2, voffA);
;             PG8_WAIT_V(8); PG8_WAIT_L(0); PG8_BAR; PG8_MMA(1, 0, At, B0); PG8_MMA(1, 1, At, B1); PG8_BAR; PG8_SCHED;
;             PG8_LDB(B0, 1, 0); PG8_LDB(B1, 1, 1); PG8_SCHED; PG8_LDA(At, 1, 0); PG8_STAGE(PG8_SA(0, 1), a2 + hstepA, voffA);
;             PG8_WAIT_V(8); PG8_WAIT_L(0); PG8_BAR; PG8_MMA(0, 0, At, B0); PG8_MMA(0, 1, At, B1); PG8_BAR; PG8_SCHED;
	s_setprio 1
	s_waitcnt lgkmcnt(0)
	v_mfma_f32_16x16x32_bf16 v[60:63], v[132:135], v[178:181], v[60:63]
	v_mfma_f32_16x16x32_bf16 v[56:59], v[140:143], v[178:181], v[56:59]
	v_mfma_f32_16x16x32_bf16 v[44:47], v[132:135], v[186:189], v[44:47]
	v_mfma_f32_16x16x32_bf16 v[40:43], v[140:143], v[186:189], v[40:43]
	v_mfma_f32_16x16x32_bf16 v[28:31], v[132:135], v[194:197], v[28:31]
	v_mfma_f32_16x16x32_bf16 v[24:27], v[140:143], v[194:197], v[24:27]
	v_mfma_f32_16x16x32_bf16 v[12:15], v[132:135], v[218:221], v[12:15]
	v_mfma_f32_16x16x32_bf16 v[8:11], v[140:143], v[218:221], v[8:11]
	v_mfma_f32_16x16x32_bf16 v[60:63], v[136:139], v[182:185], v[60:63]
	v_mfma_f32_16x16x32_bf16 v[56:59], v[144:147], v[182:185], v[56:59]
	v_mfma_f32_16x16x32_bf16 v[44:47], v[136:139], v[190:193], v[44:47]
	v_mfma_f32_16x16x32_bf16 v[40:43], v[144:147], v[190:193], v[40:43]
	v_mfma_f32_16x16x32_bf16 v[28:31], v[136:139], v[198:201], v[28:31]
	v_mfma_f32_16x16x32_bf16 v[24:27], v[144:147], v[198:201], v[24:27]
	v_mfma_f32_16x16x32_bf16 v[12:15], v[136:139], v[222:225], v[12:15]
	v_mfma_f32_16x16x32_bf16 v[8:11], v[144:147], v[222:225], v[8:11]
	s_setprio 0
	s_setprio 1
	v_mfma_f32_16x16x32_bf16 v[52:55], v[148:151], v[178:181], v[52:55]
	v_mfma_f32_16x16x32_bf16 v[48:51], v[170:173], v[178:181], v[48:51]
	v_mfma_f32_16x16x32_bf16 v[36:39], v[148:151], v[186:189], v[36:39]
	v_mfma_f32_16x16x32_bf16 v[32:35], v[170:173], v[186:189], v[32:35]
	v_mfma_f32_16x16x32_bf16 v[20:23], v[148:151], v[194:197], v[20:23]
	v_mfma_f32_16x16x32_bf16 v[16:19], v[170:173], v[194:197], v[16:19]
	v_mfma_f32_16x16x32_bf16 v[4:7], v[148:151], v[218:221], v[4:7]
	v_mfma_f32_16x16x32_bf16 v[0:3], v[170:173], v[218:221], v[0:3]
	v_mfma_f32_16x16x32_bf16 v[52:55], v[152:155], v[182:185], v[52:55]
	v_mfma_f32_16x16x32_bf16 v[48:51], v[174:177], v[182:185], v[48:51]
	v_mfma_f32_16x16x32_bf16 v[36:39], v[152:155], v[190:193], v[36:39]
	v_mfma_f32_16x16x32_bf16 v[32:35], v[174:177], v[190:193], v[32:35]
	v_mfma_f32_16x16x32_bf16 v[20:23], v[152:155], v[198:201], v[20:23]
	v_mfma_f32_16x16x32_bf16 v[16:19], v[174:177], v[198:201], v[16:19]
	v_mfma_f32_16x16x32_bf16 v[4:7], v[152:155], v[222:225], v[4:7]
	v_mfma_f32_16x16x32_bf16 v[0:3], v[174:177], v[222:225], v[0:3]
	v_lshl_add_u64 v[242:243], s[26:27], 0, v[160:161]
	s_mov_b32 m0, s35
	s_nop 0
	global_load_lds_dwordx4 v[242:243], off
	v_lshl_add_u64 v[242:243], s[26:27], 0, v[158:159]
	s_mov_b32 m0, s44
	s_nop 0
	global_load_lds_dwordx4 v[242:243], off
	s_setprio 0
	s_barrier
	s_add_i32 s68, 0, 0x18000
	s_add_i32 s69, 0, 0x1c000
	v_add_u32_e32 v144, s68, v203
	v_add_u32_e32 v174, s69, v203
	ds_read_b128 v[132:135], v144
	ds_read_b128 v[136:139], v144 offset:1024
	ds_read_b128 v[140:143], v144 offset:2048
	ds_read_b128 v[144:147], v144 offset:3072
	ds_read_b128 v[148:151], v174
	ds_read_b128 v[152:155], v174 offset:1024
	ds_read_b128 v[170:173], v174 offset:2048
	ds_read_b128 v[174:177], v174 offset:3072
	s_add_u32 s26, s26, 0x40000
	s_addc_u32 s27, s27, 0
	s_mov_b32 m0, s45
	v_lshl_add_u64 v[242:243], s[26:27], 0, v[160:161]
	ds_read_b128 v[178:181], v211 offset:32768
	ds_read_b128 v[182:185], v211 offset:33792
	ds_read_b128 v[186:189], v211 offset:34816
	ds_read_b128 v[190:193], v211 offset:35840
	ds_read_b128 v[194:197], v211 offset:36864
	ds_read_b128 v[198:201], v211 offset:37888
	ds_read_b128 v[218:221], v211 offset:38912
	ds_read_b128 v[222:225], v211 offset:39936
	global_load_lds_dwordx4 v[242:243], off
	v_lshl_add_u64 v[242:243], s[26:27], 0, v[158:159]
	s_mov_b32 m0, s46
	s_nop 0
	global_load_lds_dwordx4 v[242:243], off
	s_waitcnt vmcnt(8)
	s_waitcnt lgkmcnt(0)
	s_barrier
	s_setprio 1
	s_waitcnt lgkmcnt(0)
	v_mfma_f32_16x16x32_bf16 v[120:123], v[132:135], v[178:181], v[120:123]
	v_mfma_f32_16x16x32_bf16 v[116:119], v[140:143], v[178:181], v[116:119]
	v_mfma_f32_16x16x32_bf16 v[108:111], v[132:135], v[186:189], v[108:111]
	v_mfma_f32_16x16x32_bf16 v[104:107], v[140:143], v[186:189], v[104:107]
	v_mfma_f32_16x16x32_bf16 v[92:95], v[132:135], v[194:197], v[92:95]
	v_mfma_f32_16x16x32_bf16 v[88:91], v[140:143], v[194:197], v[88:91]
	v_mfma_f32_16x16x32_bf16 v[76:79], v[132:135], v[218:221], v[76:79]
	v_mfma_f32_16x16x32_bf16 v[72:75], v[140:143], v[218:221], v[72:75]
	v_mfma_f32_16x16x32_bf16 v[120:123], v[136:139], v[182:185], v[120:123]
	v_mfma_f32_16x16x32_bf16 v[116:119], v[144:147], v[182:185], v[116:119]
	v_mfma_f32_16x16x32_bf16 v[108:111], v[136:139], v[190:193], v[108:111]
	v_mfma_f32_16x16x32_bf16 v[104:107], v[144:147], v[190:193], v[104:107]
	v_mfma_f32_16x16x32_bf16 v[92:95], v[136:139], v[198:201], v[92:95]
	v_mfma_f32_16x16x32_bf16 v[88:91], v[144:147], v[198:201], v[88:91]
	v_mfma_f32_16x16x32_bf16 v[76:79], v[136:139], v[222:225], v[76:79]
	v_mfma_f32_16x16x32_bf16 v[72:75], v[144:147], v[222:225], v[72:75]
	s_setprio 0
	s_setprio 1
	v_mfma_f32_16x16x32_bf16 v[128:131], v[148:151], v[178:181], v[128:131]
	v_mfma_f32_16x16x32_bf16 v[124:127], v[170:173], v[178:181], v[124:127]
	v_mfma_f32_16x16x32_bf16 v[100:103], v[148:151], v[186:189], v[100:103]
	v_mfma_f32_16x16x32_bf16 v[96:99], v[170:173], v[186:189], v[96:99]
	v_mfma_f32_16x16x32_bf16 v[84:87], v[148:151], v[194:197], v[84:87]
	v_mfma_f32_16x16x32_bf16 v[80:83], v[170:173], v[194:197], v[80:83]
	v_mfma_f32_16x16x32_bf16 v[68:71], v[148:151], v[218:221], v[68:71]
	v_mfma_f32_16x16x32_bf16 v[64:67], v[170:173], v[218:221], v[64:67]
	v_mfma_f32_16x16x32_bf16 v[128:131], v[152:155], v[182:185], v[128:131]
	v_mfma_f32_16x16x32_bf16 v[124:127], v[174:177], v[182:185], v[124:127]
	v_mfma_f32_16x16x32_bf16 v[100:103], v[152:155], v[190:193], v[100:103]
	v_mfma_f32_16x16x32_bf16 v[96:99], v[174:177], v[190:193], v[96:99]
	v_mfma_f32_16x16x32_bf16 v[84:87], v[152:155], v[198:201], v[84:87]
	v_mfma_f32_16x16x32_bf16 v[80:83], v[174:177], v[198:201], v[80:83]
	v_mfma_f32_16x16x32_bf16 v[68:71], v[152:155], v[222:225], v[68:71]
	v_mfma_f32_16x16x32_bf16 v[64:67], v[174:177], v[222:225], v[64:67]
	s_setprio 0
	s_barrier
; #define PG8_STAGE(bufoff, gbase, voff) do { _Pragma("unroll") for (int _i = 0; _i < 2; ++_i) \
;         __builtin_amdgcn_global_load_lds((const unsigned*)((const char*)(gbase) + (voff)[_i]), (PG8_LAS unsigned*)(lds + (bufoff) + ldsw + _i * 8192), 16, 0, 0); } while (0)
; #define PG8_LDA(dst, b, h) do { _Pragma("unroll") for (int m = 0; m < 4; ++m) _Pragma("unroll") for (int k = 0; k < 2; ++k) dst[m][k] = *(const PG8_LAS bf16x8*)(lds + PG8_SA(b, h) + aoff + m * 2048 + k * 1024); } while (0)
; #define PG8_MMA(ai, bj, At, Bt) do { __builtin_amdgcn_s_setprio(1); _Pragma("unroll") for (int m = 0; m < 4; ++m) _Pragma("unroll") for (int n = 0; n < 2; ++n) _Pragma("unroll") for (int k = 0; k < 2; ++k) \
;         acc[ai][bj][m][n] = __builtin_amdgcn_mfma_f32_16x16x32_bf16(Bt[n][k], At[m][k], acc[ai][bj][m][n], 0, 0, 0); __builtin_amdgcn_s_setprio(0); } while (0)
; #define PG8_WAIT_V(n) asm volatile("s_waitcnt vmcnt(" #n ")" ::: "memory")
; #define PG8_WAIT_L(n) asm volatile("s_waitcnt lgkmcnt(" #n ")" ::: "memory")
; #define PG8_BAR __builtin_amdgcn_s_barrier()
; #define PG8_SCHED __builtin_amdgcn_sched_barrier(0)
;     ...
;             PG8_LDA(At, 1, 1); PG8_STAGE(PG8_SB(1, 0), b3, voffB); PG8_STAGE(PG8_SB(1, 1), b3 + hstepB, voffB); PG8_STAGE(PG8_SA(1, 0), a3, voffA);
;             PG8_WAIT_V(8); PG8_WAIT_L(0); PG8_BAR; PG8_MMA(1, 0, At, B0); PG8_MMA(1, 1, At, B1); PG8_BAR; PG8_SCHED;
;         }
;         if (wr == 0) PG8_BAR;
;         if (!has_next && wmat && gtid * 128u < wbytes) asm volatile("global_load_dword %0, %1, off" : "+v"(warmm) : "v"(wmat + (size_t)gtid * 128u) : "memory");
	s_add_i32 s26, s68, s31
	v_lshl_add_u64 v[238:239], v[238:239], 0, s[72:73]
	s_mov_b32 m0, s26
	ds_read_b128 v[178:181], v211 offset:49152
	ds_read_b128 v[182:185], v211 offset:50176
	ds_read_b128 v[186:189], v211 offset:51200
	ds_read_b128 v[190:193], v211 offset:52224
	ds_read_b128 v[194:197], v211 offset:53248
	ds_read_b128 v[198:201], v211 offset:54272
	ds_read_b128 v[218:221], v211 offset:55296
	ds_read_b128 v[222:225], v211 offset:56320
	global_load_lds_dwordx4 v[238:239], off
	s_add_i32 m0, s26, 0x2000
	s_add_u32 s24, s24, 0x40080
	v_lshl_add_u64 v[238:239], v[240:241], 0, s[72:73]
	s_addc_u32 s25, s25, 0
	s_add_i32 s26, s69, s31
	global_load_lds_dwordx4 v[238:239], off
	v_lshl_add_u64 v[238:239], s[24:25], 0, v[208:209]
	s_mov_b32 m0, s26
	s_nop 0
	global_load_lds_dwordx4 v[238:239], off
	v_lshl_add_u64 v[238:239], s[24:25], 0, v[156:157]
	s_add_i32 m0, s26, 0x2000
	s_nop 0
	global_load_lds_dwordx4 v[238:239], off
	s_waitcnt vmcnt(6)
	s_waitcnt lgkmcnt(0)
	s_barrier
	s_setprio 1
	s_waitcnt lgkmcnt(0)
	v_mfma_f32_16x16x32_bf16 v[60:63], v[132:135], v[178:181], v[60:63]
	v_mfma_f32_16x16x32_bf16 v[56:59], v[140:143], v[178:181], v[56:59]
	v_mfma_f32_16x16x32_bf16 v[44:47], v[132:135], v[186:189], v[44:47]
	v_mfma_f32_16x16x32_bf16 v[40:43], v[140:143], v[186:189], v[40:43]
	v_mfma_f32_16x16x32_bf16 v[28:31], v[132:135], v[194:197], v[28:31]
	v_mfma_f32_16x16x32_bf16 v[24:27], v[140:143], v[194:197], v[24:27]
	v_mfma_f32_16x16x32_bf16 v[12:15], v[132:135], v[218:221], v[12:15]
	v_mfma_f32_16x16x32_bf16 v[8:11], v[140:143], v[218:221], v[8:11]
	v_mfma_f32_16x16x32_bf16 v[60:63], v[136:139], v[182:185], v[60:63]
	v_mfma_f32_16x16x32_bf16 v[56:59], v[144:147], v[182:185], v[56:59]
	v_mfma_f32_16x16x32_bf16 v[44:47], v[136:139], v[190:193], v[44:47]
	v_mfma_f32_16x16x32_bf16 v[40:43], v[144:147], v[190:193], v[40:43]
	v_mfma_f32_16x16x32_bf16 v[28:31], v[136:139], v[198:201], v[28:31]
	v_mfma_f32_16x16x32_bf16 v[24:27], v[144:147], v[198:201], v[24:27]
	v_mfma_f32_16x16x32_bf16 v[12:15], v[136:139], v[222:225], v[12:15]
	v_mfma_f32_16x16x32_bf16 v[8:11], v[144:147], v[222:225], v[8:11]
	s_setprio 0
	s_setprio 1
	v_mfma_f32_16x16x32_bf16 v[52:55], v[148:151], v[178:181], v[52:55]
	v_mfma_f32_16x16x32_bf16 v[48:51], v[170:173], v[178:181], v[48:51]
	v_mfma_f32_16x16x32_bf16 v[36:39], v[148:151], v[186:189], v[36:39]
	v_mfma_f32_16x16x32_bf16 v[32:35], v[170:173], v[186:189], v[32:35]
	v_mfma_f32_16x16x32_bf16 v[20:23], v[148:151], v[194:197], v[20:23]
	v_mfma_f32_16x16x32_bf16 v[16:19], v[170:173], v[194:197], v[16:19]
	v_mfma_f32_16x16x32_bf16 v[4:7], v[148:151], v[218:221], v[4:7]
	v_mfma_f32_16x16x32_bf16 v[0:3], v[170:173], v[218:221], v[0:3]
	v_mfma_f32_16x16x32_bf16 v[52:55], v[152:155], v[182:185], v[52:55]
	v_mfma_f32_16x16x32_bf16 v[48:51], v[174:177], v[182:185], v[48:51]
	v_mfma_f32_16x16x32_bf16 v[36:39], v[152:155], v[190:193], v[36:39]
	v_mfma_f32_16x16x32_bf16 v[32:35], v[174:177], v[190:193], v[32:35]
	v_mfma_f32_16x16x32_bf16 v[20:23], v[152:155], v[198:201], v[20:23]
	v_mfma_f32_16x16x32_bf16 v[16:19], v[174:177], v[198:201], v[16:19]
	v_mfma_f32_16x16x32_bf16 v[4:7], v[152:155], v[222:225], v[4:7]
	v_mfma_f32_16x16x32_bf16 v[0:3], v[174:177], v[222:225], v[0:3]
	v_lshl_add_u64 v[238:239], s[20:21], 0, v[160:161]
	s_mov_b32 m0, s47
	s_nop 0
	global_load_lds_dwordx4 v[238:239], off
	v_lshl_add_u64 v[238:239], s[20:21], 0, v[158:159]
	s_mov_b32 m0, s48
	s_nop 0
	global_load_lds_dwordx4 v[238:239], off
	s_setprio 0
	s_barrier
	s_add_i32 s67, s67, 2
	s_add_u32 s18, s18, 0x100
	s_addc_u32 s19, s19, 0
	s_cmp_gt_u32 s67, 13
	s_cbranch_scc0 .LBB0_451
	s_and_b64 vcc, exec, s[16:17]
	s_cbranch_vccz .LBB0_473
	s_barrier
	s_nor_b64 s[20:21], s[36:37], s[40:41]
	s_and_saveexec_b64 s[18:19], s[20:21]
	s_cbranch_execnz .LBB0_474

;     __device__ __forceinline__ const char* tile(const Unit& u, int t) const { return A + (size_t)u.pm * 2 * hstep() + (size_t)t * (BK * 2); }
;     __device__ __forceinline__ const char* tile(const Unit& u, int t) const { return U + (long)(t >> 2) * xoff + (size_t)u.pn * (1024 * 512) + (size_t)u.pm * 2 * hstep() + (size_t)(t & 3) * (BK * 2); }
; #define PG8_STAGE(bufoff, gbase, voff) do { _Pragma("unroll") for (int _i = 0; _i < 2; ++_i) \
;         __builtin_amdgcn_global_load_lds((const unsigned*)((const char*)(gbase) + (voff)[_i]), (PG8_LAS unsigned*)(lds + (bufoff) + ldsw + _i * 8192), 16, 0, 0); } while (0)
; #define PG8_LDA(dst, b, h) do { _Pragma("unroll") for (int m = 0; m < 4; ++m) _Pragma("unroll") for (int k = 0; k < 2; ++k) dst[m][k] = *(const PG8_LAS bf16x8*)(lds + PG8_SA(b, h) + aoff + m * 2048 + k * 1024); } while (0)
; #define PG8_LDB(dst, b, h) do { _Pragma("unroll") for (int n = 0; n < 2; ++n) _Pragma("unroll") for (int k = 0; k < 2; ++k) dst[n][k] = *(const PG8_LAS bf16x8*)(lds + PG8_SB(b, h) + boff + n * 2048 + k * 1024); } while (0)
; #define PG8_MMA(ai, bj, At, Bt) do { __builtin_amdgcn_s_setprio(1); _Pragma("unroll") for (int m = 0; m < 4; ++m) _Pragma("unroll") for (int n = 0; n < 2; ++n) _Pragma("unroll") for (int k = 0; k < 2; ++k) \
;         acc[ai][bj][m][n] = __builtin_amdgcn_mfma_f32_16x16x32_bf16(Bt[n][k], At[m][k], acc[ai][bj][m][n], 0, 0, 0); __builtin_amdgcn_s_setprio(0); } while (0)
; #define PG8_WAIT_V(n) asm volatile("s_waitcnt vmcnt(" #n ")" ::: "memory")
;     ...
;             const bool last = (t == nt - 2);
;             const char* a1 = AS.tile(cur, t + 1);
;             const char* a2 = last ? AS.tile(nu, 0) : AS.tile(cur, t + 2); const char* b2 = last ? nB : cB + (size_t)(t + 2) * kstep;
;             const char* a3 = last ? AS.tile(nu, 1) : AS.tile(cur, t + 3); const char* b3 = b2 + kstep;
;             PG8_LDB(B0, 0, 0); PG8_LDB(B1, 0, 1); PG8_SCHED; PG8_LDA(At, 0, 0); PG8_STAGE(PG8_SA(1, 1), a1 + hstepA, voffA);
;             PG8_WAIT_V(8); PG8_WAIT_L(0); PG8_BAR; PG8_MMA(0, 0, At, B0); PG8_MMA(0, 1, At, B1); PG8_BAR; PG8_SCHED;
;             PG8_LDA(At, 0, 1); PG8_STAGE(PG8_SB(0, 0), b2, voffB); PG8_STAGE(PG8_SB(0, 1), b2 + hstepB, voffB); PG8_STAGE(PG8_SA(0, 0), a2, voffA);
;             PG8_WAIT_V(8); PG8_WAIT_L(0); PG8_BAR; PG8_MMA(1, 0, At, B0); PG8_MMA(1, 1, At, B1); PG8_BAR; PG8_SCHED;
.LBB0_504:
	s_add_u32 s14, s52, s12
	s_addc_u32 s15, s53, s13
	s_add_u32 s18, s14, 0x400100
	s_addc_u32 s19, s15, 0
	s_add_u32 s16, s54, s12
	s_addc_u32 s17, s55, s13
	s_add_u32 s14, s14, 0x400180
	s_addc_u32 s15, s15, 0
	s_add_i32 s57, 0, 0x10000
	s_add_i32 s60, 0, 0x14000
	v_add_u32_e32 v146, s57, v149
	ds_read_b128 v[156:159], v146
	ds_read_b128 v[160:163], v146 offset:1024
	ds_read_b128 v[164:167], v146 offset:2048
	ds_read_b128 v[168:171], v146 offset:3072
	v_add_u32_e32 v146, s60, v149
	ds_read_b128 v[172:175], v146
	ds_read_b128 v[176:179], v146 offset:1024
	ds_read_b128 v[180:183], v146 offset:2048
	ds_read_b128 v[184:187], v146 offset:3072
	s_cmpk_eq_i32 s12, 0x700
	s_cselect_b32 s15, s51, s15
	s_cselect_b32 s14, s50, s14
	s_cselect_b32 s17, s48, s17
	s_cselect_b32 s16, s47, s16
	s_cselect_b32 s19, s49, s19
	s_cselect_b32 s18, s11, s18
	v_lshl_add_u64 v[146:147], v[142:143], 0, s[12:13]
	s_add_i32 m0, s26, 0xc000
	ds_read_b128 v[188:191], v152
	ds_read_b128 v[192:195], v152 offset:1024
	ds_read_b128 v[196:199], v152 offset:2048
	ds_read_b128 v[200:203], v152 offset:3072
	ds_read_b128 v[204:207], v152 offset:4096
	ds_read_b128 v[218:221], v152 offset:5120
	ds_read_b128 v[222:225], v152 offset:6144
	ds_read_b128 v[238:241], v152 offset:7168
	global_load_lds_dwordx4 v[146:147], off
	v_lshl_add_u64 v[146:147], v[144:145], 0, s[12:13]
	s_add_i32 m0, s26, 0xe000
	s_nop 0
	global_load_lds_dwordx4 v[146:147], off
	s_waitcnt vmcnt(8)
	s_waitcnt lgkmcnt(0)
	s_barrier
	s_setprio 1
	s_waitcnt lgkmcnt(0)
	v_mfma_f32_16x16x32_bf16 v[124:127], v[156:159], v[188:191], v[124:127]
	v_mfma_f32_16x16x32_bf16 v[120:123], v[164:167], v[188:191], v[120:123]
	v_mfma_f32_16x16x32_bf16 v[108:111], v[156:159], v[196:199], v[108:111]
	v_mfma_f32_16x16x32_bf16 v[104:107], v[164:167], v[196:199], v[104:107]
	v_mfma_f32_16x16x32_bf16 v[92:95], v[156:159], v[204:207], v[92:95]
	v_mfma_f32_16x16x32_bf16 v[88:91], v[164:167], v[204:207], v[88:91]
	v_mfma_f32_16x16x32_bf16 v[76:79], v[156:159], v[222:225], v[76:79]
	v_mfma_f32_16x16x32_bf16 v[72:75], v[164:167], v[222:225], v[72:75]
	v_mfma_f32_16x16x32_bf16 v[124:127], v[160:163], v[192:195], v[124:127]
	v_mfma_f32_16x16x32_bf16 v[120:123], v[168:171], v[192:195], v[120:123]
	v_mfma_f32_16x16x32_bf16 v[108:111], v[160:163], v[200:203], v[108:111]
	v_mfma_f32_16x16x32_bf16 v[104:107], v[168:171], v[200:203], v[104:107]
	v_mfma_f32_16x16x32_bf16 v[92:95], v[160:163], v[218:221], v[92:95]
	v_mfma_f32_16x16x32_bf16 v[88:91], v[168:171], v[218:221], v[88:91]
	v_mfma_f32_16x16x32_bf16 v[76:79], v[160:163], v[238:241], v[76:79]
	v_mfma_f32_16x16x32_bf16 v[72:75], v[168:171], v[238:241], v[72:75]
	s_setprio 0
	s_setprio 1
	v_mfma_f32_16x16x32_bf16 v[116:119], v[172:175], v[188:191], v[116:119]
	v_mfma_f32_16x16x32_bf16 v[112:115], v[180:183], v[188:191], v[112:115]
	v_mfma_f32_16x16x32_bf16 v[100:103], v[172:175], v[196:199], v[100:103]
	v_mfma_f32_16x16x32_bf16 v[96:99], v[180:183], v[196:199], v[96:99]
	v_mfma_f32_16x16x32_bf16 v[84:87], v[172:175], v[204:207], v[84:87]
	v_mfma_f32_16x16x32_bf16 v[80:83], v[180:183], v[204:207], v[80:83]
	v_mfma_f32_16x16x32_bf16 v[68:71], v[172:175], v[222:225], v[68:71]
	v_mfma_f32_16x16x32_bf16 v[64:67], v[180:183], v[222:225], v[64:67]
	v_mfma_f32_16x16x32_bf16 v[116:119], v[176:179], v[192:195], v[116:119]
	v_mfma_f32_16x16x32_bf16 v[112:115], v[184:187], v[192:195], v[112:115]
	v_mfma_f32_16x16x32_bf16 v[100:103], v[176:179], v[200:203], v[100:103]
	v_mfma_f32_16x16x32_bf16 v[96:99], v[184:187], v[200:203], v[96:99]
	v_mfma_f32_16x16x32_bf16 v[84:87], v[176:179], v[218:221], v[84:87]
	v_mfma_f32_16x16x32_bf16 v[80:83], v[184:187], v[218:221], v[80:83]
	v_mfma_f32_16x16x32_bf16 v[68:71], v[176:179], v[238:241], v[68:71]
	v_mfma_f32_16x16x32_bf16 v[64:67], v[184:187], v[238:241], v[64:67]
	s_setprio 0
	s_barrier
	s_add_i32 s57, s57, s25
	v_lshl_add_u64 v[146:147], s[16:17], 0, v[208:209]
	s_mov_b32 m0, s57
	ds_read_b128 v[188:191], v152 offset:16384
	ds_read_b128 v[192:195], v152 offset:17408
	ds_read_b128 v[196:199], v152 offset:18432
	ds_read_b128 v[200:203], v152 offset:19456
	ds_read_b128 v[204:207], v152 offset:20480
	ds_read_b128 v[218:221], v152 offset:21504
	ds_read_b128 v[222:225], v152 offset:22528
	ds_read_b128 v[238:241], v152 offset:23552
	global_load_lds_dwordx4 v[146:147], off
	s_add_i32 m0, s57, 0x2000
	s_add_u32 s58, s16, 0x40000
	v_lshl_add_u64 v[242:243], s[16:17], 0, v[128:129]
	s_addc_u32 s59, s17, 0
	s_add_i32 s57, s60, s25
	global_load_lds_dwordx4 v[242:243], off
	v_lshl_add_u64 v[244:245], s[58:59], 0, v[208:209]
	s_mov_b32 m0, s57
	s_nop 0
	global_load_lds_dwordx4 v[244:245], off
	v_lshl_add_u64 v[244:245], s[58:59], 0, v[128:129]
	s_add_i32 m0, s57, 0x2000
	s_nop 0
	global_load_lds_dwordx4 v[244:245], off
	s_waitcnt vmcnt(6)
	s_waitcnt lgkmcnt(0)
	s_barrier
; #define PG8_STAGE(bufoff, gbase, voff) do { _Pragma("unroll") for (int _i = 0; _i < 2; ++_i) \
;         __builtin_amdgcn_global_load_lds((const unsigned*)((const char*)(gbase) + (voff)[_i]), (PG8_LAS unsigned*)(lds + (bufoff) + ldsw + _i * 8192), 16, 0, 0); } while (0)
; #define PG8_LDA(dst, b, h) do { _Pragma("unroll") for (int m = 0; m < 4; ++m) _Pragma("unroll") for (int k = 0; k < 2; ++k) dst[m][k] = *(const PG8_LAS bf16x8*)(lds + PG8_SA(b, h) + aoff + m * 2048 + k * 1024); } while (0)
; #define PG8_LDB(dst, b, h) do { _Pragma("unroll") for (int n = 0; n < 2; ++n) _Pragma("unroll") for (int k = 0; k < 2; ++k) dst[n][k] = *(const PG8_LAS bf16x8*)(lds + PG8_SB(b, h) + boff + n * 2048 + k * 1024); } while (0)
; #define PG8_MMA(ai, bj, At, Bt) do { __builtin_amdgcn_s_setprio(1); _Pragma("unroll") for (int m = 0; m < 4; ++m) _Pragma("unroll") for (int n = 0; n < 2; ++n) _Pragma("unroll") for (int k = 0; k < 2; ++k) \
;         acc[ai][bj][m][n] = __builtin_amdgcn_mfma_f32_16x16x32_bf16(Bt[n][k], At[m][k], acc[ai][bj][m][n], 0, 0, 0); __builtin_amdgcn_s_setprio(0); } while (0)
; #define PG8_WAIT_V(n) asm volatile("s_waitcnt vmcnt(" #n ")" ::: "memory")
; #define PG8_WAIT_L(n) asm volatile("s_waitcnt lgkmcnt(" #n ")" ::: "memory")
; #define PG8_BAR __builtin_amdgcn_s_barrier()
; #define PG8_SCHED __builtin_amdgcn_sched_barrier(0)
;     ...
;             PG8_WAIT_V(8); PG8_WAIT_L(0); PG8_BAR; PG8_MMA(1, 0, At, B0); PG8_MMA(1, 1, At, B1); PG8_BAR; PG8_SCHED;
;             PG8_LDB(B0, 1, 0); PG8_LDB(B1, 1, 1); PG8_SCHED; PG8_LDA(At, 1, 0); PG8_STAGE(PG8_SA(0, 1), a2 + hstepA, voffA);
;             PG8_WAIT_V(8); PG8_WAIT_L(0); PG8_BAR; PG8_MMA(0, 0, At, B0); PG8_MMA(0, 1, At, B1); PG8_BAR; PG8_SCHED;
	s_setprio 1
	s_waitcnt lgkmcnt(0)
	v_mfma_f32_16x16x32_bf16 v[60:63], v[156:159], v[188:191], v[60:63]
	v_mfma_f32_16x16x32_bf16 v[56:59], v[164:167], v[188:191], v[56:59]
	v_mfma_f32_16x16x32_bf16 v[44:47], v[156:159], v[196:199], v[44:47]
	v_mfma_f32_16x16x32_bf16 v[40:43], v[164:167], v[196:199], v[40:43]
	v_mfma_f32_16x16x32_bf16 v[28:31], v[156:159], v[204:207], v[28:31]
	v_mfma_f32_16x16x32_bf16 v[24:27], v[164:167], v[204:207], v[24:27]
	v_mfma_f32_16x16x32_bf16 v[12:15], v[156:159], v[222:225], v[12:15]
	v_mfma_f32_16x16x32_bf16 v[8:11], v[164:167], v[222:225], v[8:11]
	v_mfma_f32_16x16x32_bf16 v[60:63], v[160:163], v[192:195], v[60:63]
	v_mfma_f32_16x16x32_bf16 v[56:59], v[168:171], v[192:195], v[56:59]
	v_mfma_f32_16x16x32_bf16 v[44:47], v[160:163], v[200:203], v[44:47]
	v_mfma_f32_16x16x32_bf16 v[40:43], v[168:171], v[200:203], v[40:43]
	v_mfma_f32_16x16x32_bf16 v[28:31], v[160:163], v[218:221], v[28:31]
	v_mfma_f32_16x16x32_bf16 v[24:27], v[168:171], v[218:221], v[24:27]
	v_mfma_f32_16x16x32_bf16 v[12:15], v[160:163], v[238:241], v[12:15]
	v_mfma_f32_16x16x32_bf16 v[8:11], v[168:171], v[238:241], v[8:11]
	s_setprio 0
	s_setprio 1
	v_mfma_f32_16x16x32_bf16 v[52:55], v[172:175], v[188:191], v[52:55]
	v_mfma_f32_16x16x32_bf16 v[48:51], v[180:183], v[188:191], v[48:51]
	v_mfma_f32_16x16x32_bf16 v[36:39], v[172:175], v[196:199], v[36:39]
	v_mfma_f32_16x16x32_bf16 v[32:35], v[180:183], v[196:199], v[32:35]
	v_mfma_f32_16x16x32_bf16 v[20:23], v[172:175], v[204:207], v[20:23]
	v_mfma_f32_16x16x32_bf16 v[16:19], v[180:183], v[204:207], v[16:19]
	v_mfma_f32_16x16x32_bf16 v[4:7], v[172:175], v[222:225], v[4:7]
	v_mfma_f32_16x16x32_bf16 v[0:3], v[180:183], v[222:225], v[0:3]
	v_mfma_f32_16x16x32_bf16 v[52:55], v[176:179], v[192:195], v[52:55]
	v_mfma_f32_16x16x32_bf16 v[48:51], v[184:187], v[192:195], v[48:51]
	v_mfma_f32_16x16x32_bf16 v[36:39], v[176:179], v[200:203], v[36:39]
	v_mfma_f32_16x16x32_bf16 v[32:35], v[184:187], v[200:203], v[32:35]
	v_mfma_f32_16x16x32_bf16 v[20:23], v[176:179], v[218:221], v[20:23]
	v_mfma_f32_16x16x32_bf16 v[16:19], v[184:187], v[218:221], v[16:19]
	v_mfma_f32_16x16x32_bf16 v[4:7], v[176:179], v[238:241], v[4:7]
	v_mfma_f32_16x16x32_bf16 v[0:3], v[184:187], v[238:241], v[0:3]
	v_lshl_add_u64 v[244:245], s[18:19], 0, v[132:133]
	s_mov_b32 m0, s26
	s_nop 0
	global_load_lds_dwordx4 v[244:245], off
	v_lshl_add_u64 v[244:245], s[18:19], 0, v[130:131]
	s_mov_b32 m0, s27
	s_nop 0
	global_load_lds_dwordx4 v[244:245], off
	s_setprio 0
	s_barrier
	s_add_i32 s57, 0, 0x18000
	v_add_u32_e32 v155, s57, v149
	s_add_i32 s58, 0, 0x1c000
	ds_read_b128 v[156:159], v155
	ds_read_b128 v[160:163], v155 offset:1024
	ds_read_b128 v[164:167], v155 offset:2048
	ds_read_b128 v[168:171], v155 offset:3072
	v_add_u32_e32 v155, s58, v149
	ds_read_b128 v[172:175], v155
	ds_read_b128 v[176:179], v155 offset:1024
	ds_read_b128 v[180:183], v155 offset:2048
	ds_read_b128 v[184:187], v155 offset:3072
	s_add_u32 s18, s18, 0x40000
	s_addc_u32 s19, s19, 0
	s_mov_b32 m0, s28
	v_lshl_add_u64 v[244:245], s[18:19], 0, v[132:133]
	ds_read_b128 v[188:191], v152 offset:32768
	ds_read_b128 v[192:195], v152 offset:33792
	ds_read_b128 v[196:199], v152 offset:34816
	ds_read_b128 v[200:203], v152 offset:35840
	ds_read_b128 v[204:207], v152 offset:36864
	ds_read_b128 v[218:221], v152 offset:37888
	ds_read_b128 v[222:225], v152 offset:38912
	ds_read_b128 v[238:241], v152 offset:39936
	global_load_lds_dwordx4 v[244:245], off
	v_lshl_add_u64 v[244:245], s[18:19], 0, v[130:131]
	s_mov_b32 m0, s29
	s_nop 0
	global_load_lds_dwordx4 v[244:245], off
	s_waitcnt vmcnt(8)
	s_waitcnt lgkmcnt(0)
	s_barrier
	s_setprio 1
	s_waitcnt lgkmcnt(0)
	v_mfma_f32_16x16x32_bf16 v[124:127], v[156:159], v[188:191], v[124:127]
	v_mfma_f32_16x16x32_bf16 v[120:123], v[164:167], v[188:191], v[120:123]
	v_mfma_f32_16x16x32_bf16 v[108:111], v[156:159], v[196:199], v[108:111]
	v_mfma_f32_16x16x32_bf16 v[104:107], v[164:167], v[196:199], v[104:107]
	v_mfma_f32_16x16x32_bf16 v[92:95], v[156:159], v[204:207], v[92:95]
	v_mfma_f32_16x16x32_bf16 v[88:91], v[164:167], v[204:207], v[88:91]
	v_mfma_f32_16x16x32_bf16 v[76:79], v[156:159], v[222:225], v[76:79]
	v_mfma_f32_16x16x32_bf16 v[72:75], v[164:167], v[222:225], v[72:75]
	v_mfma_f32_16x16x32_bf16 v[124:127], v[160:163], v[192:195], v[124:127]
	v_mfma_f32_16x16x32_bf16 v[120:123], v[168:171], v[192:195], v[120:123]
	v_mfma_f32_16x16x32_bf16 v[108:111], v[160:163], v[200:203], v[108:111]
	v_mfma_f32_16x16x32_bf16 v[104:107], v[168:171], v[200:203], v[104:107]
	v_mfma_f32_16x16x32_bf16 v[92:95], v[160:163], v[218:221], v[92:95]
	v_mfma_f32_16x16x32_bf16 v[88:91], v[168:171], v[218:221], v[88:91]
	v_mfma_f32_16x16x32_bf16 v[76:79], v[160:163], v[238:241], v[76:79]
	v_mfma_f32_16x16x32_bf16 v[72:75], v[168:171], v[238:241], v[72:75]
	s_setprio 0
	s_setprio 1
	v_mfma_f32_16x16x32_bf16 v[116:119], v[172:175], v[188:191], v[116:119]
	v_mfma_f32_16x16x32_bf16 v[112:115], v[180:183], v[188:191], v[112:115]
	v_mfma_f32_16x16x32_bf16 v[100:103], v[172:175], v[196:199], v[100:103]
	v_mfma_f32_16x16x32_bf16 v[96:99], v[180:183], v[196:199], v[96:99]
	v_mfma_f32_16x16x32_bf16 v[84:87], v[172:175], v[204:207], v[84:87]
	v_mfma_f32_16x16x32_bf16 v[80:83], v[180:183], v[204:207], v[80:83]
	v_mfma_f32_16x16x32_bf16 v[68:71], v[172:175], v[222:225], v[68:71]
	v_mfma_f32_16x16x32_bf16 v[64:67], v[180:183], v[222:225], v[64:67]
	v_mfma_f32_16x16x32_bf16 v[116:119], v[176:179], v[192:195], v[116:119]
	v_mfma_f32_16x16x32_bf16 v[112:115], v[184:187], v[192:195], v[112:115]
	v_mfma_f32_16x16x32_bf16 v[100:103], v[176:179], v[200:203], v[100:103]
	v_mfma_f32_16x16x32_bf16 v[96:99], v[184:187], v[200:203], v[96:99]
	v_mfma_f32_16x16x32_bf16 v[84:87], v[176:179], v[218:221], v[84:87]
	v_mfma_f32_16x16x32_bf16 v[80:83], v[184:187], v[218:221], v[80:83]
	v_mfma_f32_16x16x32_bf16 v[68:71], v[176:179], v[238:241], v[68:71]
	v_mfma_f32_16x16x32_bf16 v[64:67], v[184:187], v[238:241], v[64:67]
	s_setprio 0
	s_barrier
; #define PG8_STAGE(bufoff, gbase, voff) do { _Pragma("unroll") for (int _i = 0; _i < 2; ++_i) \
;         __builtin_amdgcn_global_load_lds((const unsigned*)((const char*)(gbase) + (voff)[_i]), (PG8_LAS unsigned*)(lds + (bufoff) + ldsw + _i * 8192), 16, 0, 0); } while (0)
; #define PG8_LDA(dst, b, h) do { _Pragma("unroll") for (int m = 0; m < 4; ++m) _Pragma("unroll") for (int k = 0; k < 2; ++k) dst[m][k] = *(const PG8_LAS bf16x8*)(lds + PG8_SA(b, h) + aoff + m * 2048 + k * 1024); } while (0)
; #define PG8_MMA(ai, bj, At, Bt) do { __builtin_amdgcn_s_setprio(1); _Pragma("unroll") for (int m = 0; m < 4; ++m) _Pragma("unroll") for (int n = 0; n < 2; ++n) _Pragma("unroll") for (int k = 0; k < 2; ++k) \
;         acc[ai][bj][m][n] = __builtin_amdgcn_mfma_f32_16x16x32_bf16(Bt[n][k], At[m][k], acc[ai][bj][m][n], 0, 0, 0); __builtin_amdgcn_s_setprio(0); } while (0)
; #define PG8_WAIT_V(n) asm volatile("s_waitcnt vmcnt(" #n ")" ::: "memory")
; #define PG8_WAIT_L(n) asm volatile("s_waitcnt lgkmcnt(" #n ")" ::: "memory")
; #define PG8_BAR __builtin_amdgcn_s_barrier()
; #define PG8_SCHED __builtin_amdgcn_sched_barrier(0)
;     ...
;             PG8_LDA(At, 1, 1); PG8_STAGE(PG8_SB(1, 0), b3, voffB); PG8_STAGE(PG8_SB(1, 1), b3 + hstepB, voffB); PG8_STAGE(PG8_SA(1, 0), a3, voffA);
;             PG8_WAIT_V(8); PG8_WAIT_L(0); PG8_BAR; PG8_MMA(1, 0, At, B0); PG8_MMA(1, 1, At, B1); PG8_BAR; PG8_SCHED;
;         }
;         if (wr == 0) PG8_BAR;
;         if (!has_next && wmat && gtid * 128u < wbytes) asm volatile("global_load_dword %0, %1, off" : "+v"(warmm) : "v"(wmat + (size_t)gtid * 128u) : "memory");
	s_add_i32 s18, s57, s25
	v_lshl_add_u64 v[146:147], v[146:147], 0, s[64:65]
	s_mov_b32 m0, s18
	ds_read_b128 v[188:191], v152 offset:49152
	ds_read_b128 v[192:195], v152 offset:50176
	ds_read_b128 v[196:199], v152 offset:51200
	ds_read_b128 v[200:203], v152 offset:52224
	ds_read_b128 v[204:207], v152 offset:53248
	ds_read_b128 v[218:221], v152 offset:54272
	ds_read_b128 v[222:225], v152 offset:55296
	ds_read_b128 v[238:241], v152 offset:56320
	global_load_lds_dwordx4 v[146:147], off
	s_add_i32 m0, s18, 0x2000
	s_add_u32 s16, s16, 0x40080
	v_lshl_add_u64 v[146:147], v[242:243], 0, s[64:65]
	s_addc_u32 s17, s17, 0
	s_add_i32 s18, s58, s25
	global_load_lds_dwordx4 v[146:147], off
	v_lshl_add_u64 v[146:147], s[16:17], 0, v[208:209]
	s_mov_b32 m0, s18
	s_nop 0
	global_load_lds_dwordx4 v[146:147], off
	v_lshl_add_u64 v[146:147], s[16:17], 0, v[128:129]
	s_add_i32 m0, s18, 0x2000
	s_nop 0
	global_load_lds_dwordx4 v[146:147], off
	s_waitcnt vmcnt(6)
	s_waitcnt lgkmcnt(0)
	s_barrier
	s_setprio 1
	s_waitcnt lgkmcnt(0)
	v_mfma_f32_16x16x32_bf16 v[60:63], v[156:159], v[188:191], v[60:63]
	v_mfma_f32_16x16x32_bf16 v[56:59], v[164:167], v[188:191], v[56:59]
	v_mfma_f32_16x16x32_bf16 v[44:47], v[156:159], v[196:199], v[44:47]
	v_mfma_f32_16x16x32_bf16 v[40:43], v[164:167], v[196:199], v[40:43]
	v_mfma_f32_16x16x32_bf16 v[28:31], v[156:159], v[204:207], v[28:31]
	v_mfma_f32_16x16x32_bf16 v[24:27], v[164:167], v[204:207], v[24:27]
	v_mfma_f32_16x16x32_bf16 v[12:15], v[156:159], v[222:225], v[12:15]
	v_mfma_f32_16x16x32_bf16 v[8:11], v[164:167], v[222:225], v[8:11]
	v_mfma_f32_16x16x32_bf16 v[60:63], v[160:163], v[192:195], v[60:63]
	v_mfma_f32_16x16x32_bf16 v[56:59], v[168:171], v[192:195], v[56:59]
	v_mfma_f32_16x16x32_bf16 v[44:47], v[160:163], v[200:203], v[44:47]
	v_mfma_f32_16x16x32_bf16 v[40:43], v[168:171], v[200:203], v[40:43]
	v_mfma_f32_16x16x32_bf16 v[28:31], v[160:163], v[218:221], v[28:31]
	v_mfma_f32_16x16x32_bf16 v[24:27], v[168:171], v[218:221], v[24:27]
	v_mfma_f32_16x16x32_bf16 v[12:15], v[160:163], v[238:241], v[12:15]
	v_mfma_f32_16x16x32_bf16 v[8:11], v[168:171], v[238:241], v[8:11]
	s_setprio 0
	s_setprio 1
	v_mfma_f32_16x16x32_bf16 v[52:55], v[172:175], v[188:191], v[52:55]
	v_mfma_f32_16x16x32_bf16 v[48:51], v[180:183], v[188:191], v[48:51]
	v_mfma_f32_16x16x32_bf16 v[36:39], v[172:175], v[196:199], v[36:39]
	v_mfma_f32_16x16x32_bf16 v[32:35], v[180:183], v[196:199], v[32:35]
	v_mfma_f32_16x16x32_bf16 v[20:23], v[172:175], v[204:207], v[20:23]
	v_mfma_f32_16x16x32_bf16 v[16:19], v[180:183], v[204:207], v[16:19]
	v_mfma_f32_16x16x32_bf16 v[4:7], v[172:175], v[222:225], v[4:7]
	v_mfma_f32_16x16x32_bf16 v[0:3], v[180:183], v[222:225], v[0:3]
	v_mfma_f32_16x16x32_bf16 v[52:55], v[176:179], v[192:195], v[52:55]
	v_mfma_f32_16x16x32_bf16 v[48:51], v[184:187], v[192:195], v[48:51]
	v_mfma_f32_16x16x32_bf16 v[36:39], v[176:179], v[200:203], v[36:39]
	v_mfma_f32_16x16x32_bf16 v[32:35], v[184:187], v[200:203], v[32:35]
	v_mfma_f32_16x16x32_bf16 v[20:23], v[176:179], v[218:221], v[20:23]
	v_mfma_f32_16x16x32_bf16 v[16:19], v[184:187], v[218:221], v[16:19]
	v_mfma_f32_16x16x32_bf16 v[4:7], v[176:179], v[238:241], v[4:7]
	v_mfma_f32_16x16x32_bf16 v[0:3], v[184:187], v[238:241], v[0:3]
	v_lshl_add_u64 v[146:147], s[14:15], 0, v[132:133]
	s_mov_b32 m0, s30
	s_nop 0
	global_load_lds_dwordx4 v[146:147], off
	v_lshl_add_u64 v[146:147], s[14:15], 0, v[130:131]
	s_mov_b32 m0, s31
	s_nop 0
	global_load_lds_dwordx4 v[146:147], off
	s_setprio 0
	s_barrier
	s_add_i32 s56, s56, 2
	s_add_u32 s12, s12, 0x100
	s_addc_u32 s13, s13, 0
	s_cmp_gt_u32 s56, 13
	s_cbranch_scc0 .LBB0_504
	s_and_b64 vcc, exec, s[6:7]
	s_cbranch_vccz .LBB0_515
	s_barrier
	s_nor_b64 s[14:15], s[36:37], s[38:39]
	s_and_saveexec_b64 s[12:13], s[14:15]
	s_cbranch_execnz .LBB0_516

;     __device__ __forceinline__ const char* tile(const Unit& u, int t) const { return A + (size_t)u.pm * 2 * hstep() + (size_t)t * (BK * 2); }
;     __device__ __forceinline__ const char* tile(const Unit& u, int t) const { return U + (long)(t >> 2) * xoff + (size_t)u.pn * (1024 * 512) + (size_t)u.pm * 2 * hstep() + (size_t)(t & 3) * (BK * 2); }
; #define PG8_STAGE(bufoff, gbase, voff) do { _Pragma("unroll") for (int _i = 0; _i < 2; ++_i) \
;         __builtin_amdgcn_global_load_lds((const unsigned*)((const char*)(gbase) + (voff)[_i]), (PG8_LAS unsigned*)(lds + (bufoff) + ldsw + _i * 8192), 16, 0, 0); } while (0)
; #define PG8_LDA(dst, b, h) do { _Pragma("unroll") for (int m = 0; m < 4; ++m) _Pragma("unroll") for (int k = 0; k < 2; ++k) dst[m][k] = *(const PG8_LAS bf16x8*)(lds + PG8_SA(b, h) + aoff + m * 2048 + k * 1024); } while (0)
; #define PG8_LDB(dst, b, h) do { _Pragma("unroll") for (int n = 0; n < 2; ++n) _Pragma("unroll") for (int k = 0; k < 2; ++k) dst[n][k] = *(const PG8_LAS bf16x8*)(lds + PG8_SB(b, h) + boff + n * 2048 + k * 1024); } while (0)
; #define PG8_MMA(ai, bj, At, Bt) do { __builtin_amdgcn_s_setprio(1); _Pragma("unroll") for (int m = 0; m < 4; ++m) _Pragma("unroll") for (int n = 0; n < 2; ++n) _Pragma("unroll") for (int k = 0; k < 2; ++k) \
;         acc[ai][bj][m][n] = __builtin_amdgcn_mfma_f32_16x16x32_bf16(Bt[n][k], At[m][k], acc[ai][bj][m][n], 0, 0, 0); __builtin_amdgcn_s_setprio(0); } while (0)
; #define PG8_WAIT_V(n) asm volatile("s_waitcnt vmcnt(" #n ")" ::: "memory")
;     ...
;             const bool last = (t == nt - 2);
;             const char* a1 = AS.tile(cur, t + 1);
;             const char* a2 = last ? AS.tile(nu, 0) : AS.tile(cur, t + 2); const char* b2 = last ? nB : cB + (size_t)(t + 2) * kstep;
;             const char* a3 = last ? AS.tile(nu, 1) : AS.tile(cur, t + 3); const char* b3 = b2 + kstep;
;             PG8_LDB(B0, 0, 0); PG8_LDB(B1, 0, 1); PG8_SCHED; PG8_LDA(At, 0, 0); PG8_STAGE(PG8_SA(1, 1), a1 + hstepA, voffA);
;             PG8_WAIT_V(8); PG8_WAIT_L(0); PG8_BAR; PG8_MMA(0, 0, At, B0); PG8_MMA(0, 1, At, B1); PG8_BAR; PG8_SCHED;
;             PG8_LDA(At, 0, 1); PG8_STAGE(PG8_SB(0, 0), b2, voffB); PG8_STAGE(PG8_SB(0, 1), b2 + hstepB, voffB); PG8_STAGE(PG8_SA(0, 0), a2, voffA);
;             PG8_WAIT_V(8); PG8_WAIT_L(0); PG8_BAR; PG8_MMA(1, 0, At, B0); PG8_MMA(1, 1, At, B1); PG8_BAR; PG8_SCHED;
.LBB0_534:
	s_add_i32 s68, s2, 2
	s_add_u32 s3, s82, s64
	s_addc_u32 s20, s83, s65
	s_add_u32 s69, s3, 0x100
	s_addc_u32 s21, s20, 0
	s_add_u32 s70, s82, s66
	s_addc_u32 s71, s83, s67
	s_add_u32 s72, s3, 0x180
	s_addc_u32 s3, s20, 0
	s_add_i32 s73, 0, 0x10000
	s_add_i32 s74, 0, 0x14000
	v_add_u32_e32 v108, s73, v212
	v_add_u32_e32 v152, s74, v212
	ds_read_b128 v[76:79], v108
	ds_read_b128 v[88:91], v108 offset:1024
	ds_read_b128 v[100:103], v108 offset:2048
	ds_read_b128 v[108:111], v108 offset:3072
	ds_read_b128 v[124:127], v152
	ds_read_b128 v[128:131], v152 offset:1024
	ds_read_b128 v[144:147], v152 offset:2048
	ds_read_b128 v[152:155], v152 offset:3072
	s_cmp_eq_u32 s51, s2
	s_cselect_b32 s2, s60, s72
	s_cselect_b32 s3, s61, s3
	s_cselect_b32 s71, s41, s71
	s_cselect_b32 s70, s40, s70
	s_cselect_b32 s21, s59, s21
	s_cselect_b32 s20, s1, s69
	v_lshl_add_u64 v[222:223], s[82:83], 0, v[64:65]
	s_add_i32 m0, s35, 0xc000
	ds_read_b128 v[156:159], v241
	ds_read_b128 v[168:171], v241 offset:1024
	ds_read_b128 v[172:175], v241 offset:2048
	ds_read_b128 v[176:179], v241 offset:3072
	ds_read_b128 v[180:183], v241 offset:4096
	ds_read_b128 v[184:187], v241 offset:5120
	ds_read_b128 v[188:191], v241 offset:6144
	ds_read_b128 v[218:221], v241 offset:7168
	global_load_lds_dwordx4 v[222:223], off
	v_lshl_add_u64 v[222:223], s[82:83], 0, v[66:67]
	s_add_i32 m0, s35, 0xe000
	s_nop 0
	global_load_lds_dwordx4 v[222:223], off
	s_waitcnt vmcnt(8)
	s_waitcnt lgkmcnt(0)
	s_barrier
	s_setprio 1
	s_waitcnt lgkmcnt(0)
	v_mfma_f32_16x16x32_bf16 v[164:167], v[76:79], v[156:159], v[164:167]
	v_mfma_f32_16x16x32_bf16 v[160:163], v[100:103], v[156:159], v[160:163]
	v_mfma_f32_16x16x32_bf16 v[136:139], v[76:79], v[172:175], v[136:139]
	v_mfma_f32_16x16x32_bf16 v[132:135], v[100:103], v[172:175], v[132:135]
	v_mfma_f32_16x16x32_bf16 v[112:115], v[76:79], v[180:183], v[112:115]
	v_mfma_f32_16x16x32_bf16 v[104:107], v[100:103], v[180:183], v[104:107]
	v_mfma_f32_16x16x32_bf16 v[84:87], v[76:79], v[188:191], v[84:87]
	v_mfma_f32_16x16x32_bf16 v[80:83], v[100:103], v[188:191], v[80:83]
	v_mfma_f32_16x16x32_bf16 v[164:167], v[88:91], v[168:171], v[164:167]
	v_mfma_f32_16x16x32_bf16 v[160:163], v[108:111], v[168:171], v[160:163]
	v_mfma_f32_16x16x32_bf16 v[136:139], v[88:91], v[176:179], v[136:139]
	v_mfma_f32_16x16x32_bf16 v[132:135], v[108:111], v[176:179], v[132:135]
	v_mfma_f32_16x16x32_bf16 v[112:115], v[88:91], v[184:187], v[112:115]
	v_mfma_f32_16x16x32_bf16 v[104:107], v[108:111], v[184:187], v[104:107]
	v_mfma_f32_16x16x32_bf16 v[84:87], v[88:91], v[218:221], v[84:87]
	v_mfma_f32_16x16x32_bf16 v[80:83], v[108:111], v[218:221], v[80:83]
	s_setprio 0
	s_setprio 1
	v_mfma_f32_16x16x32_bf16 v[148:151], v[124:127], v[156:159], v[148:151]
	v_mfma_f32_16x16x32_bf16 v[140:143], v[144:147], v[156:159], v[140:143]
	v_mfma_f32_16x16x32_bf16 v[120:123], v[124:127], v[172:175], v[120:123]
	v_mfma_f32_16x16x32_bf16 v[116:119], v[144:147], v[172:175], v[116:119]
	v_mfma_f32_16x16x32_bf16 v[96:99], v[124:127], v[180:183], v[96:99]
	v_mfma_f32_16x16x32_bf16 v[92:95], v[144:147], v[180:183], v[92:95]
	v_mfma_f32_16x16x32_bf16 v[72:75], v[124:127], v[188:191], v[72:75]
	v_mfma_f32_16x16x32_bf16 v[68:71], v[144:147], v[188:191], v[68:71]
	v_mfma_f32_16x16x32_bf16 v[148:151], v[128:131], v[168:171], v[148:151]
	v_mfma_f32_16x16x32_bf16 v[140:143], v[152:155], v[168:171], v[140:143]
	v_mfma_f32_16x16x32_bf16 v[120:123], v[128:131], v[176:179], v[120:123]
	v_mfma_f32_16x16x32_bf16 v[116:119], v[152:155], v[176:179], v[116:119]
	v_mfma_f32_16x16x32_bf16 v[96:99], v[128:131], v[184:187], v[96:99]
	v_mfma_f32_16x16x32_bf16 v[92:95], v[152:155], v[184:187], v[92:95]
	v_mfma_f32_16x16x32_bf16 v[72:75], v[128:131], v[218:221], v[72:75]
	v_mfma_f32_16x16x32_bf16 v[68:71], v[152:155], v[218:221], v[68:71]
	s_setprio 0
	s_barrier
	s_add_i32 s69, s73, s25
	v_lshl_add_u64 v[222:223], s[70:71], 0, v[196:197]
	s_mov_b32 m0, s69
	ds_read_b128 v[156:159], v241 offset:16384
	ds_read_b128 v[168:171], v241 offset:17408
	ds_read_b128 v[172:175], v241 offset:18432
	ds_read_b128 v[176:179], v241 offset:19456
	ds_read_b128 v[180:183], v241 offset:20480
	ds_read_b128 v[184:187], v241 offset:21504
	ds_read_b128 v[188:191], v241 offset:22528
	ds_read_b128 v[218:221], v241 offset:23552
	global_load_lds_dwordx4 v[222:223], off
	s_add_i32 m0, s69, 0x2000
	v_lshl_add_u64 v[224:225], s[70:71], 0, v[192:193]
	s_add_u32 s70, s70, s24
	s_addc_u32 s71, s71, 0
	s_add_i32 s69, s74, s25
	global_load_lds_dwordx4 v[224:225], off
	v_lshl_add_u64 v[244:245], s[70:71], 0, v[196:197]
	s_mov_b32 m0, s69
	v_lshl_add_u64 v[246:247], s[70:71], 0, v[192:193]
	global_load_lds_dwordx4 v[244:245], off
	s_add_i32 m0, s69, 0x2000
	v_lshl_add_u64 v[248:249], s[20:21], 0, v[198:199]
	global_load_lds_dwordx4 v[246:247], off
	s_waitcnt vmcnt(6)
	s_waitcnt lgkmcnt(0)
	s_barrier
; #define PG8_STAGE(bufoff, gbase, voff) do { _Pragma("unroll") for (int _i = 0; _i < 2; ++_i) \
;         __builtin_amdgcn_global_load_lds((const unsigned*)((const char*)(gbase) + (voff)[_i]), (PG8_LAS unsigned*)(lds + (bufoff) + ldsw + _i * 8192), 16, 0, 0); } while (0)
; #define PG8_LDA(dst, b, h) do { _Pragma("unroll") for (int m = 0; m < 4; ++m) _Pragma("unroll") for (int k = 0; k < 2; ++k) dst[m][k] = *(const PG8_LAS bf16x8*)(lds + PG8_SA(b, h) + aoff + m * 2048 + k * 1024); } while (0)
; #define PG8_LDB(dst, b, h) do { _Pragma("unroll") for (int n = 0; n < 2; ++n) _Pragma("unroll") for (int k = 0; k < 2; ++k) dst[n][k] = *(const PG8_LAS bf16x8*)(lds + PG8_SB(b, h) + boff + n * 2048 + k * 1024); } while (0)
; #define PG8_MMA(ai, bj, At, Bt) do { __builtin_amdgcn_s_setprio(1); _Pragma("unroll") for (int m = 0; m < 4; ++m) _Pragma("unroll") for (int n = 0; n < 2; ++n) _Pragma("unroll") for (int k = 0; k < 2; ++k) \
;         acc[ai][bj][m][n] = __builtin_amdgcn_mfma_f32_16x16x32_bf16(Bt[n][k], At[m][k], acc[ai][bj][m][n], 0, 0, 0); __builtin_amdgcn_s_setprio(0); } while (0)
; #define PG8_WAIT_V(n) asm volatile("s_waitcnt vmcnt(" #n ")" ::: "memory")
; #define PG8_WAIT_L(n) asm volatile("s_waitcnt lgkmcnt(" #n ")" ::: "memory")
; #define PG8_BAR __builtin_amdgcn_s_barrier()
; #define PG8_SCHED __builtin_amdgcn_sched_barrier(0)
;     ...
;             PG8_WAIT_V(8); PG8_WAIT_L(0); PG8_BAR; PG8_MMA(1, 0, At, B0); PG8_MMA(1, 1, At, B1); PG8_BAR; PG8_SCHED;
;             PG8_LDB(B0, 1, 0); PG8_LDB(B1, 1, 1); PG8_SCHED; PG8_LDA(At, 1, 0); PG8_STAGE(PG8_SA(0, 1), a2 + hstepA, voffA);
;             PG8_WAIT_V(8); PG8_WAIT_L(0); PG8_BAR; PG8_MMA(0, 0, At, B0); PG8_MMA(0, 1, At, B1); PG8_BAR; PG8_SCHED;
	s_setprio 1
	s_waitcnt lgkmcnt(0)
	v_mfma_f32_16x16x32_bf16 v[60:63], v[76:79], v[156:159], v[60:63]
	v_mfma_f32_16x16x32_bf16 v[56:59], v[100:103], v[156:159], v[56:59]
	v_mfma_f32_16x16x32_bf16 v[44:47], v[76:79], v[172:175], v[44:47]
	v_mfma_f32_16x16x32_bf16 v[40:43], v[100:103], v[172:175], v[40:43]
	v_mfma_f32_16x16x32_bf16 v[28:31], v[76:79], v[180:183], v[28:31]
	v_mfma_f32_16x16x32_bf16 v[24:27], v[100:103], v[180:183], v[24:27]
	v_mfma_f32_16x16x32_bf16 v[12:15], v[76:79], v[188:191], v[12:15]
	v_mfma_f32_16x16x32_bf16 v[8:11], v[100:103], v[188:191], v[8:11]
	v_mfma_f32_16x16x32_bf16 v[60:63], v[88:91], v[168:171], v[60:63]
	v_mfma_f32_16x16x32_bf16 v[56:59], v[108:111], v[168:171], v[56:59]
	v_mfma_f32_16x16x32_bf16 v[44:47], v[88:91], v[176:179], v[44:47]
	v_mfma_f32_16x16x32_bf16 v[40:43], v[108:111], v[176:179], v[40:43]
	v_mfma_f32_16x16x32_bf16 v[28:31], v[88:91], v[184:187], v[28:31]
	v_mfma_f32_16x16x32_bf16 v[24:27], v[108:111], v[184:187], v[24:27]
	v_mfma_f32_16x16x32_bf16 v[12:15], v[88:91], v[218:221], v[12:15]
	v_mfma_f32_16x16x32_bf16 v[8:11], v[108:111], v[218:221], v[8:11]
	s_setprio 0
	s_setprio 1
	v_mfma_f32_16x16x32_bf16 v[52:55], v[124:127], v[156:159], v[52:55]
	v_mfma_f32_16x16x32_bf16 v[48:51], v[144:147], v[156:159], v[48:51]
	v_mfma_f32_16x16x32_bf16 v[36:39], v[124:127], v[172:175], v[36:39]
	v_mfma_f32_16x16x32_bf16 v[32:35], v[144:147], v[172:175], v[32:35]
	v_mfma_f32_16x16x32_bf16 v[20:23], v[124:127], v[180:183], v[20:23]
	v_mfma_f32_16x16x32_bf16 v[16:19], v[144:147], v[180:183], v[16:19]
	v_mfma_f32_16x16x32_bf16 v[4:7], v[124:127], v[188:191], v[4:7]
	v_mfma_f32_16x16x32_bf16 v[0:3], v[144:147], v[188:191], v[0:3]
	v_mfma_f32_16x16x32_bf16 v[52:55], v[128:131], v[168:171], v[52:55]
	v_mfma_f32_16x16x32_bf16 v[48:51], v[152:155], v[168:171], v[48:51]
	v_mfma_f32_16x16x32_bf16 v[36:39], v[128:131], v[176:179], v[36:39]
	v_mfma_f32_16x16x32_bf16 v[32:35], v[152:155], v[176:179], v[32:35]
	v_mfma_f32_16x16x32_bf16 v[20:23], v[128:131], v[184:187], v[20:23]
	v_mfma_f32_16x16x32_bf16 v[16:19], v[152:155], v[184:187], v[16:19]
	v_mfma_f32_16x16x32_bf16 v[4:7], v[128:131], v[218:221], v[4:7]
	v_mfma_f32_16x16x32_bf16 v[0:3], v[152:155], v[218:221], v[0:3]
	s_mov_b32 m0, s35
	s_nop 0
	global_load_lds_dwordx4 v[248:249], off
	v_lshl_add_u64 v[248:249], s[20:21], 0, v[194:195]
	s_mov_b32 m0, s44
	s_nop 0
	global_load_lds_dwordx4 v[248:249], off
	s_setprio 0
	s_barrier
	s_add_i32 s69, 0, 0x18000
	s_add_i32 s70, 0, 0x1c000
	v_add_u32_e32 v108, s69, v212
	v_add_u32_e32 v152, s70, v212
	ds_read_b128 v[76:79], v108
	ds_read_b128 v[88:91], v108 offset:1024
	ds_read_b128 v[100:103], v108 offset:2048
	ds_read_b128 v[108:111], v108 offset:3072
	ds_read_b128 v[124:127], v152
	ds_read_b128 v[128:131], v152 offset:1024
	ds_read_b128 v[144:147], v152 offset:2048
	ds_read_b128 v[152:155], v152 offset:3072
	s_add_u32 s20, s20, s24
	s_addc_u32 s21, s21, 0
	s_mov_b32 m0, s45
	v_lshl_add_u64 v[248:249], s[20:21], 0, v[198:199]
	ds_read_b128 v[156:159], v241 offset:32768
	ds_read_b128 v[168:171], v241 offset:33792
	ds_read_b128 v[172:175], v241 offset:34816
	ds_read_b128 v[176:179], v241 offset:35840
	ds_read_b128 v[180:183], v241 offset:36864
	ds_read_b128 v[184:187], v241 offset:37888
	ds_read_b128 v[188:191], v241 offset:38912
	ds_read_b128 v[218:221], v241 offset:39936
	global_load_lds_dwordx4 v[248:249], off
	v_lshl_add_u64 v[248:249], s[20:21], 0, v[194:195]
	s_mov_b32 m0, s46
	s_nop 0
	global_load_lds_dwordx4 v[248:249], off
	s_waitcnt vmcnt(8)
	s_waitcnt lgkmcnt(0)
	s_barrier
	s_setprio 1
	s_waitcnt lgkmcnt(0)
	v_mfma_f32_16x16x32_bf16 v[164:167], v[76:79], v[156:159], v[164:167]
	v_mfma_f32_16x16x32_bf16 v[160:163], v[100:103], v[156:159], v[160:163]
	v_mfma_f32_16x16x32_bf16 v[136:139], v[76:79], v[172:175], v[136:139]
	v_mfma_f32_16x16x32_bf16 v[132:135], v[100:103], v[172:175], v[132:135]
	v_mfma_f32_16x16x32_bf16 v[112:115], v[76:79], v[180:183], v[112:115]
	v_mfma_f32_16x16x32_bf16 v[104:107], v[100:103], v[180:183], v[104:107]
	v_mfma_f32_16x16x32_bf16 v[84:87], v[76:79], v[188:191], v[84:87]
	v_mfma_f32_16x16x32_bf16 v[80:83], v[100:103], v[188:191], v[80:83]
	v_mfma_f32_16x16x32_bf16 v[164:167], v[88:91], v[168:171], v[164:167]
	v_mfma_f32_16x16x32_bf16 v[160:163], v[108:111], v[168:171], v[160:163]
	v_mfma_f32_16x16x32_bf16 v[136:139], v[88:91], v[176:179], v[136:139]
	v_mfma_f32_16x16x32_bf16 v[132:135], v[108:111], v[176:179], v[132:135]
	v_mfma_f32_16x16x32_bf16 v[112:115], v[88:91], v[184:187], v[112:115]
	v_mfma_f32_16x16x32_bf16 v[104:107], v[108:111], v[184:187], v[104:107]
	v_mfma_f32_16x16x32_bf16 v[84:87], v[88:91], v[218:221], v[84:87]
	v_mfma_f32_16x16x32_bf16 v[80:83], v[108:111], v[218:221], v[80:83]
	s_setprio 0
	s_setprio 1
	v_mfma_f32_16x16x32_bf16 v[148:151], v[124:127], v[156:159], v[148:151]
	v_mfma_f32_16x16x32_bf16 v[140:143], v[144:147], v[156:159], v[140:143]
	v_mfma_f32_16x16x32_bf16 v[120:123], v[124:127], v[172:175], v[120:123]
	v_mfma_f32_16x16x32_bf16 v[116:119], v[144:147], v[172:175], v[116:119]
	v_mfma_f32_16x16x32_bf16 v[96:99], v[124:127], v[180:183], v[96:99]
	v_mfma_f32_16x16x32_bf16 v[92:95], v[144:147], v[180:183], v[92:95]
	v_mfma_f32_16x16x32_bf16 v[72:75], v[124:127], v[188:191], v[72:75]
	v_mfma_f32_16x16x32_bf16 v[68:71], v[144:147], v[188:191], v[68:71]
	v_mfma_f32_16x16x32_bf16 v[148:151], v[128:131], v[168:171], v[148:151]
	v_mfma_f32_16x16x32_bf16 v[140:143], v[152:155], v[168:171], v[140:143]
	v_mfma_f32_16x16x32_bf16 v[120:123], v[128:131], v[176:179], v[120:123]
	v_mfma_f32_16x16x32_bf16 v[116:119], v[152:155], v[176:179], v[116:119]
	v_mfma_f32_16x16x32_bf16 v[96:99], v[128:131], v[184:187], v[96:99]
	v_mfma_f32_16x16x32_bf16 v[92:95], v[152:155], v[184:187], v[92:95]
	v_mfma_f32_16x16x32_bf16 v[72:75], v[128:131], v[218:221], v[72:75]
	v_mfma_f32_16x16x32_bf16 v[68:71], v[152:155], v[218:221], v[68:71]
	s_setprio 0
	s_barrier
; #define PG8_STAGE(bufoff, gbase, voff) do { _Pragma("unroll") for (int _i = 0; _i < 2; ++_i) \
;         __builtin_amdgcn_global_load_lds((const unsigned*)((const char*)(gbase) + (voff)[_i]), (PG8_LAS unsigned*)(lds + (bufoff) + ldsw + _i * 8192), 16, 0, 0); } while (0)
; #define PG8_LDA(dst, b, h) do { _Pragma("unroll") for (int m = 0; m < 4; ++m) _Pragma("unroll") for (int k = 0; k < 2; ++k) dst[m][k] = *(const PG8_LAS bf16x8*)(lds + PG8_SA(b, h) + aoff + m * 2048 + k * 1024); } while (0)
; #define PG8_MMA(ai, bj, At, Bt) do { __builtin_amdgcn_s_setprio(1); _Pragma("unroll") for (int m = 0; m < 4; ++m) _Pragma("unroll") for (int n = 0; n < 2; ++n) _Pragma("unroll") for (int k = 0; k < 2; ++k) \
;         acc[ai][bj][m][n] = __builtin_amdgcn_mfma_f32_16x16x32_bf16(Bt[n][k], At[m][k], acc[ai][bj][m][n], 0, 0, 0); __builtin_amdgcn_s_setprio(0); } while (0)
; #define PG8_WAIT_V(n) asm volatile("s_waitcnt vmcnt(" #n ")" ::: "memory")
; #define PG8_WAIT_L(n) asm volatile("s_waitcnt lgkmcnt(" #n ")" ::: "memory")
; #define PG8_BAR __builtin_amdgcn_s_barrier()
; #define PG8_SCHED __builtin_amdgcn_sched_barrier(0)
;     ...
;             PG8_LDA(At, 1, 1); PG8_STAGE(PG8_SB(1, 0), b3, voffB); PG8_STAGE(PG8_SB(1, 1), b3 + hstepB, voffB); PG8_STAGE(PG8_SA(1, 0), a3, voffA);
;             PG8_WAIT_V(8); PG8_WAIT_L(0); PG8_BAR; PG8_MMA(1, 0, At, B0); PG8_MMA(1, 1, At, B1); PG8_BAR; PG8_SCHED;
;         }
;         if (wr == 0) PG8_BAR;
;         if (!has_next && wmat && gtid * 128u < wbytes) asm volatile("global_load_dword %0, %1, off" : "+v"(warmm) : "v"(wmat + (size_t)gtid * 128u) : "memory");
	s_add_i32 s20, s69, s25
	v_lshl_add_u64 v[222:223], v[222:223], 0, s[76:77]
	s_mov_b32 m0, s20
	ds_read_b128 v[156:159], v241 offset:49152
	ds_read_b128 v[168:171], v241 offset:50176
	ds_read_b128 v[172:175], v241 offset:51200
	ds_read_b128 v[176:179], v241 offset:52224
	ds_read_b128 v[180:183], v241 offset:53248
	ds_read_b128 v[184:187], v241 offset:54272
	ds_read_b128 v[188:191], v241 offset:55296
	ds_read_b128 v[218:221], v241 offset:56320
	global_load_lds_dwordx4 v[222:223], off
	v_lshl_add_u64 v[222:223], v[224:225], 0, s[76:77]
	s_add_i32 m0, s20, 0x2000
	s_add_i32 s20, s70, s25
	global_load_lds_dwordx4 v[222:223], off
	v_lshl_add_u64 v[222:223], v[244:245], 0, s[76:77]
	s_mov_b32 m0, s20
	s_nop 0
	global_load_lds_dwordx4 v[222:223], off
	v_lshl_add_u64 v[222:223], v[246:247], 0, s[76:77]
	s_add_i32 m0, s20, 0x2000
	s_nop 0
	global_load_lds_dwordx4 v[222:223], off
	s_waitcnt vmcnt(6)
	s_waitcnt lgkmcnt(0)
	s_barrier
	s_setprio 1
	s_waitcnt lgkmcnt(0)
	v_mfma_f32_16x16x32_bf16 v[60:63], v[76:79], v[156:159], v[60:63]
	v_mfma_f32_16x16x32_bf16 v[56:59], v[100:103], v[156:159], v[56:59]
	v_mfma_f32_16x16x32_bf16 v[44:47], v[76:79], v[172:175], v[44:47]
	v_mfma_f32_16x16x32_bf16 v[40:43], v[100:103], v[172:175], v[40:43]
	v_mfma_f32_16x16x32_bf16 v[28:31], v[76:79], v[180:183], v[28:31]
	v_mfma_f32_16x16x32_bf16 v[24:27], v[100:103], v[180:183], v[24:27]
	v_mfma_f32_16x16x32_bf16 v[12:15], v[76:79], v[188:191], v[12:15]
	v_mfma_f32_16x16x32_bf16 v[8:11], v[100:103], v[188:191], v[8:11]
	v_mfma_f32_16x16x32_bf16 v[60:63], v[88:91], v[168:171], v[60:63]
	v_mfma_f32_16x16x32_bf16 v[56:59], v[108:111], v[168:171], v[56:59]
	v_mfma_f32_16x16x32_bf16 v[44:47], v[88:91], v[176:179], v[44:47]
	v_mfma_f32_16x16x32_bf16 v[40:43], v[108:111], v[176:179], v[40:43]
	v_mfma_f32_16x16x32_bf16 v[28:31], v[88:91], v[184:187], v[28:31]
	v_mfma_f32_16x16x32_bf16 v[24:27], v[108:111], v[184:187], v[24:27]
	v_mfma_f32_16x16x32_bf16 v[12:15], v[88:91], v[218:221], v[12:15]
	v_mfma_f32_16x16x32_bf16 v[8:11], v[108:111], v[218:221], v[8:11]
	s_setprio 0
	s_setprio 1
	v_mfma_f32_16x16x32_bf16 v[52:55], v[124:127], v[156:159], v[52:55]
	v_mfma_f32_16x16x32_bf16 v[48:51], v[144:147], v[156:159], v[48:51]
	v_mfma_f32_16x16x32_bf16 v[36:39], v[124:127], v[172:175], v[36:39]
	v_mfma_f32_16x16x32_bf16 v[32:35], v[144:147], v[172:175], v[32:35]
	v_mfma_f32_16x16x32_bf16 v[20:23], v[124:127], v[180:183], v[20:23]
	v_mfma_f32_16x16x32_bf16 v[16:19], v[144:147], v[180:183], v[16:19]
	v_mfma_f32_16x16x32_bf16 v[4:7], v[124:127], v[188:191], v[4:7]
	v_mfma_f32_16x16x32_bf16 v[0:3], v[144:147], v[188:191], v[0:3]
	v_mfma_f32_16x16x32_bf16 v[52:55], v[128:131], v[168:171], v[52:55]
	v_mfma_f32_16x16x32_bf16 v[48:51], v[152:155], v[168:171], v[48:51]
	v_mfma_f32_16x16x32_bf16 v[36:39], v[128:131], v[176:179], v[36:39]
	v_mfma_f32_16x16x32_bf16 v[32:35], v[152:155], v[176:179], v[32:35]
	v_mfma_f32_16x16x32_bf16 v[20:23], v[128:131], v[184:187], v[20:23]
	v_mfma_f32_16x16x32_bf16 v[16:19], v[152:155], v[184:187], v[16:19]
	v_mfma_f32_16x16x32_bf16 v[4:7], v[128:131], v[218:221], v[4:7]
	v_mfma_f32_16x16x32_bf16 v[0:3], v[152:155], v[218:221], v[0:3]
	v_lshl_add_u64 v[222:223], s[2:3], 0, v[198:199]
	s_mov_b32 m0, s47
	s_nop 0
	global_load_lds_dwordx4 v[222:223], off
	v_lshl_add_u64 v[222:223], s[2:3], 0, v[194:195]
	s_mov_b32 m0, s48
	s_nop 0
	global_load_lds_dwordx4 v[222:223], off
	s_setprio 0
	s_barrier
	s_add_u32 s64, s64, 0x100
	s_addc_u32 s65, s65, 0
	s_add_u32 s66, s66, 0x100
	s_addc_u32 s67, s67, 0
	v_lshl_add_u64 v[64:65], v[64:65], 0, s[78:79]
	v_lshl_add_u64 v[66:67], v[66:67], 0, s[78:79]
	s_cmp_ge_u32 s68, s50
	s_mov_b32 s2, s68
	s_cbranch_scc0 .LBB0_534
	s_and_b64 vcc, exec, s[12:13]
	s_cbranch_vccz .LBB0_541
	s_barrier
	s_nor_b64 s[20:21], s[14:15], s[38:39]
	s_and_saveexec_b64 s[2:3], s[20:21]
	s_cbranch_execnz .LBB0_542

;     __device__ __forceinline__ const char* tile(const Unit& u, int t) const { return A + (size_t)u.pm * 2 * hstep() + (size_t)t * (BK * 2); }
;     __device__ __forceinline__ const char* tile(const Unit& u, int t) const { return U + (long)(t >> 2) * xoff + (size_t)u.pn * (1024 * 512) + (size_t)u.pm * 2 * hstep() + (size_t)(t & 3) * (BK * 2); }
; #define PG8_STAGE(bufoff, gbase, voff) do { _Pragma("unroll") for (int _i = 0; _i < 2; ++_i) \
;         __builtin_amdgcn_global_load_lds((const unsigned*)((const char*)(gbase) + (voff)[_i]), (PG8_LAS unsigned*)(lds + (bufoff) + ldsw + _i * 8192), 16, 0, 0); } while (0)
; #define PG8_LDA(dst, b, h) do { _Pragma("unroll") for (int m = 0; m < 4; ++m) _Pragma("unroll") for (int k = 0; k < 2; ++k) dst[m][k] = *(const PG8_LAS bf16x8*)(lds + PG8_SA(b, h) + aoff + m * 2048 + k * 1024); } while (0)
; #define PG8_LDB(dst, b, h) do { _Pragma("unroll") for (int n = 0; n < 2; ++n) _Pragma("unroll") for (int k = 0; k < 2; ++k) dst[n][k] = *(const PG8_LAS bf16x8*)(lds + PG8_SB(b, h) + boff + n * 2048 + k * 1024); } while (0)
; #define PG8_MMA(ai, bj, At, Bt) do { __builtin_amdgcn_s_setprio(1); _Pragma("unroll") for (int m = 0; m < 4; ++m) _Pragma("unroll") for (int n = 0; n < 2; ++n) _Pragma("unroll") for (int k = 0; k < 2; ++k) \
;         acc[ai][bj][m][n] = __builtin_amdgcn_mfma_f32_16x16x32_bf16(Bt[n][k], At[m][k], acc[ai][bj][m][n], 0, 0, 0); __builtin_amdgcn_s_setprio(0); } while (0)
; #define PG8_WAIT_V(n) asm volatile("s_waitcnt vmcnt(" #n ")" ::: "memory")
;     ...
;             const bool last = (t == nt - 2);
;             const char* a1 = AS.tile(cur, t + 1);
;             const char* a2 = last ? AS.tile(nu, 0) : AS.tile(cur, t + 2); const char* b2 = last ? nB : cB + (size_t)(t + 2) * kstep;
;             const char* a3 = last ? AS.tile(nu, 1) : AS.tile(cur, t + 3); const char* b3 = b2 + kstep;
;             PG8_LDB(B0, 0, 0); PG8_LDB(B1, 0, 1); PG8_SCHED; PG8_LDA(At, 0, 0); PG8_STAGE(PG8_SA(1, 1), a1 + hstepA, voffA);
;             PG8_WAIT_V(8); PG8_WAIT_L(0); PG8_BAR; PG8_MMA(0, 0, At, B0); PG8_MMA(0, 1, At, B1); PG8_BAR; PG8_SCHED;
;             PG8_LDA(At, 0, 1); PG8_STAGE(PG8_SB(0, 0), b2, voffB); PG8_STAGE(PG8_SB(0, 1), b2 + hstepB, voffB); PG8_STAGE(PG8_SA(0, 0), a2, voffA);
;             PG8_WAIT_V(8); PG8_WAIT_L(0); PG8_BAR; PG8_MMA(1, 0, At, B0); PG8_MMA(1, 1, At, B1); PG8_BAR; PG8_SCHED;
.LBB0_702:
	s_add_u32 s20, s40, s2
	s_addc_u32 s21, s41, s3
	s_add_u32 s26, s20, 0x400100
	s_addc_u32 s27, s21, 0
	s_add_u32 s24, s42, s2
	s_addc_u32 s25, s43, s3
	s_add_u32 s20, s20, 0x400180
	s_addc_u32 s21, s21, 0
	s_add_i32 s63, 0, 0x10000
	s_add_i32 s66, 0, 0x14000
	v_add_u32_e32 v156, s63, v185
	v_add_u32_e32 v172, s66, v185
	ds_read_b128 v[132:135], v156
	ds_read_b128 v[136:139], v156 offset:1024
	ds_read_b128 v[140:143], v156 offset:2048
	ds_read_b128 v[156:159], v156 offset:3072
	ds_read_b128 v[160:163], v172
	ds_read_b128 v[164:167], v172 offset:1024
	ds_read_b128 v[168:171], v172 offset:2048
	ds_read_b128 v[172:175], v172 offset:3072
	s_cmpk_eq_i32 s2, 0x700
	s_cselect_b32 s21, s31, s21
	s_cselect_b32 s20, s30, s20
	s_cselect_b32 s25, s28, s25
	s_cselect_b32 s24, s1, s24
	s_cselect_b32 s27, s29, s27
	s_cselect_b32 s26, s19, s26
	v_lshl_add_u64 v[238:239], v[128:129], 0, s[2:3]
	s_add_i32 m0, s49, 0xc000
	ds_read_b128 v[176:179], v190
	ds_read_b128 v[180:183], v190 offset:1024
	ds_read_b128 v[192:195], v190 offset:2048
	ds_read_b128 v[196:199], v190 offset:3072
	ds_read_b128 v[200:203], v190 offset:4096
	ds_read_b128 v[204:207], v190 offset:5120
	ds_read_b128 v[218:221], v190 offset:6144
	ds_read_b128 v[222:225], v190 offset:7168
	global_load_lds_dwordx4 v[238:239], off
	v_lshl_add_u64 v[238:239], v[130:131], 0, s[2:3]
	s_add_i32 m0, s49, 0xe000
	s_nop 0
	global_load_lds_dwordx4 v[238:239], off
	s_waitcnt vmcnt(8)
	s_waitcnt lgkmcnt(0)
	s_barrier
	s_setprio 1
	s_waitcnt lgkmcnt(0)
	v_mfma_f32_16x16x32_bf16 v[124:127], v[132:135], v[176:179], v[124:127]
	v_mfma_f32_16x16x32_bf16 v[120:123], v[140:143], v[176:179], v[120:123]
	v_mfma_f32_16x16x32_bf16 v[112:115], v[132:135], v[192:195], v[112:115]
	v_mfma_f32_16x16x32_bf16 v[104:107], v[140:143], v[192:195], v[104:107]
	v_mfma_f32_16x16x32_bf16 v[96:99], v[132:135], v[200:203], v[96:99]
	v_mfma_f32_16x16x32_bf16 v[88:91], v[140:143], v[200:203], v[88:91]
	v_mfma_f32_16x16x32_bf16 v[80:83], v[132:135], v[218:221], v[80:83]
	v_mfma_f32_16x16x32_bf16 v[72:75], v[140:143], v[218:221], v[72:75]
	v_mfma_f32_16x16x32_bf16 v[124:127], v[136:139], v[180:183], v[124:127]
	v_mfma_f32_16x16x32_bf16 v[120:123], v[156:159], v[180:183], v[120:123]
	v_mfma_f32_16x16x32_bf16 v[112:115], v[136:139], v[196:199], v[112:115]
	v_mfma_f32_16x16x32_bf16 v[104:107], v[156:159], v[196:199], v[104:107]
	v_mfma_f32_16x16x32_bf16 v[96:99], v[136:139], v[204:207], v[96:99]
	v_mfma_f32_16x16x32_bf16 v[88:91], v[156:159], v[204:207], v[88:91]
	v_mfma_f32_16x16x32_bf16 v[80:83], v[136:139], v[222:225], v[80:83]
	v_mfma_f32_16x16x32_bf16 v[72:75], v[156:159], v[222:225], v[72:75]
	s_setprio 0
	s_setprio 1
	v_mfma_f32_16x16x32_bf16 v[116:119], v[160:163], v[176:179], v[116:119]
	v_mfma_f32_16x16x32_bf16 v[108:111], v[168:171], v[176:179], v[108:111]
	v_mfma_f32_16x16x32_bf16 v[100:103], v[160:163], v[192:195], v[100:103]
	v_mfma_f32_16x16x32_bf16 v[92:95], v[168:171], v[192:195], v[92:95]
	v_mfma_f32_16x16x32_bf16 v[84:87], v[160:163], v[200:203], v[84:87]
	v_mfma_f32_16x16x32_bf16 v[76:79], v[168:171], v[200:203], v[76:79]
	v_mfma_f32_16x16x32_bf16 v[68:71], v[160:163], v[218:221], v[68:71]
	v_mfma_f32_16x16x32_bf16 v[64:67], v[168:171], v[218:221], v[64:67]
	v_mfma_f32_16x16x32_bf16 v[116:119], v[164:167], v[180:183], v[116:119]
	v_mfma_f32_16x16x32_bf16 v[108:111], v[172:175], v[180:183], v[108:111]
	v_mfma_f32_16x16x32_bf16 v[100:103], v[164:167], v[196:199], v[100:103]
	v_mfma_f32_16x16x32_bf16 v[92:95], v[172:175], v[196:199], v[92:95]
	v_mfma_f32_16x16x32_bf16 v[84:87], v[164:167], v[204:207], v[84:87]
	v_mfma_f32_16x16x32_bf16 v[76:79], v[172:175], v[204:207], v[76:79]
	v_mfma_f32_16x16x32_bf16 v[68:71], v[164:167], v[222:225], v[68:71]
	v_mfma_f32_16x16x32_bf16 v[64:67], v[172:175], v[222:225], v[64:67]
	s_setprio 0
	s_barrier
	s_add_i32 s63, s63, s48
	v_lshl_add_u64 v[238:239], s[24:25], 0, v[148:149]
	s_mov_b32 m0, s63
	ds_read_b128 v[176:179], v190 offset:16384
	ds_read_b128 v[180:183], v190 offset:17408
	ds_read_b128 v[192:195], v190 offset:18432
	ds_read_b128 v[196:199], v190 offset:19456
	ds_read_b128 v[200:203], v190 offset:20480
	ds_read_b128 v[204:207], v190 offset:21504
	ds_read_b128 v[218:221], v190 offset:22528
	ds_read_b128 v[222:225], v190 offset:23552
	global_load_lds_dwordx4 v[238:239], off
	s_add_i32 m0, s63, 0x2000
	s_add_u32 s64, s24, 0x40000
	v_lshl_add_u64 v[240:241], s[24:25], 0, v[144:145]
	s_addc_u32 s65, s25, 0
	s_add_i32 s63, s66, s48
	global_load_lds_dwordx4 v[240:241], off
	v_lshl_add_u64 v[242:243], s[64:65], 0, v[148:149]
	s_mov_b32 m0, s63
	s_nop 0
	global_load_lds_dwordx4 v[242:243], off
	v_lshl_add_u64 v[242:243], s[64:65], 0, v[144:145]
	s_add_i32 m0, s63, 0x2000
	s_nop 0
	global_load_lds_dwordx4 v[242:243], off
	s_waitcnt vmcnt(6)
	s_waitcnt lgkmcnt(0)
	s_barrier
; #define PG8_STAGE(bufoff, gbase, voff) do { _Pragma("unroll") for (int _i = 0; _i < 2; ++_i) \
;         __builtin_amdgcn_global_load_lds((const unsigned*)((const char*)(gbase) + (voff)[_i]), (PG8_LAS unsigned*)(lds + (bufoff) + ldsw + _i * 8192), 16, 0, 0); } while (0)
; #define PG8_LDA(dst, b, h) do { _Pragma("unroll") for (int m = 0; m < 4; ++m) _Pragma("unroll") for (int k = 0; k < 2; ++k) dst[m][k] = *(const PG8_LAS bf16x8*)(lds + PG8_SA(b, h) + aoff + m * 2048 + k * 1024); } while (0)
; #define PG8_LDB(dst, b, h) do { _Pragma("unroll") for (int n = 0; n < 2; ++n) _Pragma("unroll") for (int k = 0; k < 2; ++k) dst[n][k] = *(const PG8_LAS bf16x8*)(lds + PG8_SB(b, h) + boff + n * 2048 + k * 1024); } while (0)
; #define PG8_MMA(ai, bj, At, Bt) do { __builtin_amdgcn_s_setprio(1); _Pragma("unroll") for (int m = 0; m < 4; ++m) _Pragma("unroll") for (int n = 0; n < 2; ++n) _Pragma("unroll") for (int k = 0; k < 2; ++k) \
;         acc[ai][bj][m][n] = __builtin_amdgcn_mfma_f32_16x16x32_bf16(Bt[n][k], At[m][k], acc[ai][bj][m][n], 0, 0, 0); __builtin_amdgcn_s_setprio(0); } while (0)
; #define PG8_WAIT_V(n) asm volatile("s_waitcnt vmcnt(" #n ")" ::: "memory")
; #define PG8_WAIT_L(n) asm volatile("s_waitcnt lgkmcnt(" #n ")" ::: "memory")
; #define PG8_BAR __builtin_amdgcn_s_barrier()
; #define PG8_SCHED __builtin_amdgcn_sched_barrier(0)
;     ...
;             PG8_WAIT_V(8); PG8_WAIT_L(0); PG8_BAR; PG8_MMA(1, 0, At, B0); PG8_MMA(1, 1, At, B1); PG8_BAR; PG8_SCHED;
;             PG8_LDB(B0, 1, 0); PG8_LDB(B1, 1, 1); PG8_SCHED; PG8_LDA(At, 1, 0); PG8_STAGE(PG8_SA(0, 1), a2 + hstepA, voffA);
;             PG8_WAIT_V(8); PG8_WAIT_L(0); PG8_BAR; PG8_MMA(0, 0, At, B0); PG8_MMA(0, 1, At, B1); PG8_BAR; PG8_SCHED;
	s_setprio 1
	s_waitcnt lgkmcnt(0)
	v_mfma_f32_16x16x32_bf16 v[60:63], v[132:135], v[176:179], v[60:63]
	v_mfma_f32_16x16x32_bf16 v[56:59], v[140:143], v[176:179], v[56:59]
	v_mfma_f32_16x16x32_bf16 v[48:51], v[132:135], v[192:195], v[48:51]
	v_mfma_f32_16x16x32_bf16 v[40:43], v[140:143], v[192:195], v[40:43]
	v_mfma_f32_16x16x32_bf16 v[32:35], v[132:135], v[200:203], v[32:35]
	v_mfma_f32_16x16x32_bf16 v[24:27], v[140:143], v[200:203], v[24:27]
	v_mfma_f32_16x16x32_bf16 v[16:19], v[132:135], v[218:221], v[16:19]
	v_mfma_f32_16x16x32_bf16 v[8:11], v[140:143], v[218:221], v[8:11]
	v_mfma_f32_16x16x32_bf16 v[60:63], v[136:139], v[180:183], v[60:63]
	v_mfma_f32_16x16x32_bf16 v[56:59], v[156:159], v[180:183], v[56:59]
	v_mfma_f32_16x16x32_bf16 v[48:51], v[136:139], v[196:199], v[48:51]
	v_mfma_f32_16x16x32_bf16 v[40:43], v[156:159], v[196:199], v[40:43]
	v_mfma_f32_16x16x32_bf16 v[32:35], v[136:139], v[204:207], v[32:35]
	v_mfma_f32_16x16x32_bf16 v[24:27], v[156:159], v[204:207], v[24:27]
	v_mfma_f32_16x16x32_bf16 v[16:19], v[136:139], v[222:225], v[16:19]
	v_mfma_f32_16x16x32_bf16 v[8:11], v[156:159], v[222:225], v[8:11]
	s_setprio 0
	s_setprio 1
	v_mfma_f32_16x16x32_bf16 v[52:55], v[160:163], v[176:179], v[52:55]
	v_mfma_f32_16x16x32_bf16 v[44:47], v[168:171], v[176:179], v[44:47]
	v_mfma_f32_16x16x32_bf16 v[36:39], v[160:163], v[192:195], v[36:39]
	v_mfma_f32_16x16x32_bf16 v[28:31], v[168:171], v[192:195], v[28:31]
	v_mfma_f32_16x16x32_bf16 v[20:23], v[160:163], v[200:203], v[20:23]
	v_mfma_f32_16x16x32_bf16 v[12:15], v[168:171], v[200:203], v[12:15]
	v_mfma_f32_16x16x32_bf16 v[4:7], v[160:163], v[218:221], v[4:7]
	v_mfma_f32_16x16x32_bf16 v[0:3], v[168:171], v[218:221], v[0:3]
	v_mfma_f32_16x16x32_bf16 v[52:55], v[164:167], v[180:183], v[52:55]
	v_mfma_f32_16x16x32_bf16 v[44:47], v[172:175], v[180:183], v[44:47]
	v_mfma_f32_16x16x32_bf16 v[36:39], v[164:167], v[196:199], v[36:39]
	v_mfma_f32_16x16x32_bf16 v[28:31], v[172:175], v[196:199], v[28:31]
	v_mfma_f32_16x16x32_bf16 v[20:23], v[164:167], v[204:207], v[20:23]
	v_mfma_f32_16x16x32_bf16 v[12:15], v[172:175], v[204:207], v[12:15]
	v_mfma_f32_16x16x32_bf16 v[4:7], v[164:167], v[222:225], v[4:7]
	v_mfma_f32_16x16x32_bf16 v[0:3], v[172:175], v[222:225], v[0:3]
	v_lshl_add_u64 v[242:243], s[26:27], 0, v[150:151]
	s_mov_b32 m0, s49
	s_nop 0
	global_load_lds_dwordx4 v[242:243], off
	v_lshl_add_u64 v[242:243], s[26:27], 0, v[146:147]
	s_mov_b32 m0, s50
	s_nop 0
	global_load_lds_dwordx4 v[242:243], off
	s_setprio 0
	s_barrier
	s_add_i32 s63, 0, 0x18000
	s_add_i32 s64, 0, 0x1c000
	v_add_u32_e32 v156, s63, v185
	v_add_u32_e32 v172, s64, v185
	ds_read_b128 v[132:135], v156
	ds_read_b128 v[136:139], v156 offset:1024
	ds_read_b128 v[140:143], v156 offset:2048
	ds_read_b128 v[156:159], v156 offset:3072
	ds_read_b128 v[160:163], v172
	ds_read_b128 v[164:167], v172 offset:1024
	ds_read_b128 v[168:171], v172 offset:2048
	ds_read_b128 v[172:175], v172 offset:3072
	s_add_u32 s26, s26, 0x40000
	s_addc_u32 s27, s27, 0
	s_mov_b32 m0, s51
	v_lshl_add_u64 v[242:243], s[26:27], 0, v[150:151]
	ds_read_b128 v[176:179], v190 offset:32768
	ds_read_b128 v[180:183], v190 offset:33792
	ds_read_b128 v[192:195], v190 offset:34816
	ds_read_b128 v[196:199], v190 offset:35840
	ds_read_b128 v[200:203], v190 offset:36864
	ds_read_b128 v[204:207], v190 offset:37888
	ds_read_b128 v[218:221], v190 offset:38912
	ds_read_b128 v[222:225], v190 offset:39936
	global_load_lds_dwordx4 v[242:243], off
	v_lshl_add_u64 v[242:243], s[26:27], 0, v[146:147]
	s_mov_b32 m0, s52
	s_nop 0
	global_load_lds_dwordx4 v[242:243], off
	s_waitcnt vmcnt(8)
	s_waitcnt lgkmcnt(0)
	s_barrier
	s_setprio 1
	s_waitcnt lgkmcnt(0)
	v_mfma_f32_16x16x32_bf16 v[124:127], v[132:135], v[176:179], v[124:127]
	v_mfma_f32_16x16x32_bf16 v[120:123], v[140:143], v[176:179], v[120:123]
	v_mfma_f32_16x16x32_bf16 v[112:115], v[132:135], v[192:195], v[112:115]
	v_mfma_f32_16x16x32_bf16 v[104:107], v[140:143], v[192:195], v[104:107]
	v_mfma_f32_16x16x32_bf16 v[96:99], v[132:135], v[200:203], v[96:99]
	v_mfma_f32_16x16x32_bf16 v[88:91], v[140:143], v[200:203], v[88:91]
	v_mfma_f32_16x16x32_bf16 v[80:83], v[132:135], v[218:221], v[80:83]
	v_mfma_f32_16x16x32_bf16 v[72:75], v[140:143], v[218:221], v[72:75]
	v_mfma_f32_16x16x32_bf16 v[124:127], v[136:139], v[180:183], v[124:127]
	v_mfma_f32_16x16x32_bf16 v[120:123], v[156:159], v[180:183], v[120:123]
	v_mfma_f32_16x16x32_bf16 v[112:115], v[136:139], v[196:199], v[112:115]
	v_mfma_f32_16x16x32_bf16 v[104:107], v[156:159], v[196:199], v[104:107]
	v_mfma_f32_16x16x32_bf16 v[96:99], v[136:139], v[204:207], v[96:99]
	v_mfma_f32_16x16x32_bf16 v[88:91], v[156:159], v[204:207], v[88:91]
	v_mfma_f32_16x16x32_bf16 v[80:83], v[136:139], v[222:225], v[80:83]
	v_mfma_f32_16x16x32_bf16 v[72:75], v[156:159], v[222:225], v[72:75]
	s_setprio 0
	s_setprio 1
	v_mfma_f32_16x16x32_bf16 v[116:119], v[160:163], v[176:179], v[116:119]
	v_mfma_f32_16x16x32_bf16 v[108:111], v[168:171], v[176:179], v[108:111]
	v_mfma_f32_16x16x32_bf16 v[100:103], v[160:163], v[192:195], v[100:103]
	v_mfma_f32_16x16x32_bf16 v[92:95], v[168:171], v[192:195], v[92:95]
	v_mfma_f32_16x16x32_bf16 v[84:87], v[160:163], v[200:203], v[84:87]
	v_mfma_f32_16x16x32_bf16 v[76:79], v[168:171], v[200:203], v[76:79]
	v_mfma_f32_16x16x32_bf16 v[68:71], v[160:163], v[218:221], v[68:71]
	v_mfma_f32_16x16x32_bf16 v[64:67], v[168:171], v[218:221], v[64:67]
	v_mfma_f32_16x16x32_bf16 v[116:119], v[164:167], v[180:183], v[116:119]
	v_mfma_f32_16x16x32_bf16 v[108:111], v[172:175], v[180:183], v[108:111]
	v_mfma_f32_16x16x32_bf16 v[100:103], v[164:167], v[196:199], v[100:103]
	v_mfma_f32_16x16x32_bf16 v[92:95], v[172:175], v[196:199], v[92:95]
	v_mfma_f32_16x16x32_bf16 v[84:87], v[164:167], v[204:207], v[84:87]
	v_mfma_f32_16x16x32_bf16 v[76:79], v[172:175], v[204:207], v[76:79]
	v_mfma_f32_16x16x32_bf16 v[68:71], v[164:167], v[222:225], v[68:71]
	v_mfma_f32_16x16x32_bf16 v[64:67], v[172:175], v[222:225], v[64:67]
	s_setprio 0
	s_barrier
; #define PG8_STAGE(bufoff, gbase, voff) do { _Pragma("unroll") for (int _i = 0; _i < 2; ++_i) \
;         __builtin_amdgcn_global_load_lds((const unsigned*)((const char*)(gbase) + (voff)[_i]), (PG8_LAS unsigned*)(lds + (bufoff) + ldsw + _i * 8192), 16, 0, 0); } while (0)
; #define PG8_LDA(dst, b, h) do { _Pragma("unroll") for (int m = 0; m < 4; ++m) _Pragma("unroll") for (int k = 0; k < 2; ++k) dst[m][k] = *(const PG8_LAS bf16x8*)(lds + PG8_SA(b, h) + aoff + m * 2048 + k * 1024); } while (0)
; #define PG8_MMA(ai, bj, At, Bt) do { __builtin_amdgcn_s_setprio(1); _Pragma("unroll") for (int m = 0; m < 4; ++m) _Pragma("unroll") for (int n = 0; n < 2; ++n) _Pragma("unroll") for (int k = 0; k < 2; ++k) \
;         acc[ai][bj][m][n] = __builtin_amdgcn_mfma_f32_16x16x32_bf16(Bt[n][k], At[m][k], acc[ai][bj][m][n], 0, 0, 0); __builtin_amdgcn_s_setprio(0); } while (0)
; #define PG8_WAIT_V(n) asm volatile("s_waitcnt vmcnt(" #n ")" ::: "memory")
; #define PG8_WAIT_L(n) asm volatile("s_waitcnt lgkmcnt(" #n ")" ::: "memory")
; #define PG8_BAR __builtin_amdgcn_s_barrier()
; #define PG8_SCHED __builtin_amdgcn_sched_barrier(0)
;     ...
;             PG8_LDA(At, 1, 1); PG8_STAGE(PG8_SB(1, 0), b3, voffB); PG8_STAGE(PG8_SB(1, 1), b3 + hstepB, voffB); PG8_STAGE(PG8_SA(1, 0), a3, voffA);
;             PG8_WAIT_V(8); PG8_WAIT_L(0); PG8_BAR; PG8_MMA(1, 0, At, B0); PG8_MMA(1, 1, At, B1); PG8_BAR; PG8_SCHED;
;         }
;         if (wr == 0) PG8_BAR;
	s_add_i32 s26, s63, s48
	v_lshl_add_u64 v[238:239], v[238:239], 0, s[68:69]
	s_mov_b32 m0, s26
	ds_read_b128 v[176:179], v190 offset:49152
	ds_read_b128 v[180:183], v190 offset:50176
	ds_read_b128 v[192:195], v190 offset:51200
	ds_read_b128 v[196:199], v190 offset:52224
	ds_read_b128 v[200:203], v190 offset:53248
	ds_read_b128 v[204:207], v190 offset:54272
	ds_read_b128 v[218:221], v190 offset:55296
	ds_read_b128 v[222:225], v190 offset:56320
	global_load_lds_dwordx4 v[238:239], off
	s_add_i32 m0, s26, 0x2000
	s_add_u32 s24, s24, 0x40080
	v_lshl_add_u64 v[238:239], v[240:241], 0, s[68:69]
	s_addc_u32 s25, s25, 0
	s_add_i32 s26, s64, s48
	global_load_lds_dwordx4 v[238:239], off
	v_lshl_add_u64 v[238:239], s[24:25], 0, v[148:149]
	s_mov_b32 m0, s26
	s_nop 0
	global_load_lds_dwordx4 v[238:239], off
	v_lshl_add_u64 v[238:239], s[24:25], 0, v[144:145]
	s_add_i32 m0, s26, 0x2000
	s_nop 0
	global_load_lds_dwordx4 v[238:239], off
	s_waitcnt vmcnt(6)
	s_waitcnt lgkmcnt(0)
	s_barrier
	s_setprio 1
	s_waitcnt lgkmcnt(0)
	v_mfma_f32_16x16x32_bf16 v[60:63], v[132:135], v[176:179], v[60:63]
	v_mfma_f32_16x16x32_bf16 v[56:59], v[140:143], v[176:179], v[56:59]
	v_mfma_f32_16x16x32_bf16 v[48:51], v[132:135], v[192:195], v[48:51]
	v_mfma_f32_16x16x32_bf16 v[40:43], v[140:143], v[192:195], v[40:43]
	v_mfma_f32_16x16x32_bf16 v[32:35], v[132:135], v[200:203], v[32:35]
	v_mfma_f32_16x16x32_bf16 v[24:27], v[140:143], v[200:203], v[24:27]
	v_mfma_f32_16x16x32_bf16 v[16:19], v[132:135], v[218:221], v[16:19]
	v_mfma_f32_16x16x32_bf16 v[8:11], v[140:143], v[218:221], v[8:11]
	v_mfma_f32_16x16x32_bf16 v[60:63], v[136:139], v[180:183], v[60:63]
	v_mfma_f32_16x16x32_bf16 v[56:59], v[156:159], v[180:183], v[56:59]
	v_mfma_f32_16x16x32_bf16 v[48:51], v[136:139], v[196:199], v[48:51]
	v_mfma_f32_16x16x32_bf16 v[40:43], v[156:159], v[196:199], v[40:43]
	v_mfma_f32_16x16x32_bf16 v[32:35], v[136:139], v[204:207], v[32:35]
	v_mfma_f32_16x16x32_bf16 v[24:27], v[156:159], v[204:207], v[24:27]
	v_mfma_f32_16x16x32_bf16 v[16:19], v[136:139], v[222:225], v[16:19]
	v_mfma_f32_16x16x32_bf16 v[8:11], v[156:159], v[222:225], v[8:11]
	s_setprio 0
	s_setprio 1
	v_mfma_f32_16x16x32_bf16 v[52:55], v[160:163], v[176:179], v[52:55]
	v_mfma_f32_16x16x32_bf16 v[44:47], v[168:171], v[176:179], v[44:47]
	v_mfma_f32_16x16x32_bf16 v[36:39], v[160:163], v[192:195], v[36:39]
	v_mfma_f32_16x16x32_bf16 v[28:31], v[168:171], v[192:195], v[28:31]
	v_mfma_f32_16x16x32_bf16 v[20:23], v[160:163], v[200:203], v[20:23]
	v_mfma_f32_16x16x32_bf16 v[12:15], v[168:171], v[200:203], v[12:15]
	v_mfma_f32_16x16x32_bf16 v[4:7], v[160:163], v[218:221], v[4:7]
	v_mfma_f32_16x16x32_bf16 v[0:3], v[168:171], v[218:221], v[0:3]
	v_mfma_f32_16x16x32_bf16 v[52:55], v[164:167], v[180:183], v[52:55]
	v_mfma_f32_16x16x32_bf16 v[44:47], v[172:175], v[180:183], v[44:47]
	v_mfma_f32_16x16x32_bf16 v[36:39], v[164:167], v[196:199], v[36:39]
	v_mfma_f32_16x16x32_bf16 v[28:31], v[172:175], v[196:199], v[28:31]
	v_mfma_f32_16x16x32_bf16 v[20:23], v[164:167], v[204:207], v[20:23]
	v_mfma_f32_16x16x32_bf16 v[12:15], v[172:175], v[204:207], v[12:15]
	v_mfma_f32_16x16x32_bf16 v[4:7], v[164:167], v[222:225], v[4:7]
	v_mfma_f32_16x16x32_bf16 v[0:3], v[172:175], v[222:225], v[0:3]
	v_lshl_add_u64 v[238:239], s[20:21], 0, v[150:151]
	s_mov_b32 m0, s53
	s_nop 0
	global_load_lds_dwordx4 v[238:239], off
	v_lshl_add_u64 v[238:239], s[20:21], 0, v[146:147]
	s_mov_b32 m0, s54
	s_nop 0
	global_load_lds_dwordx4 v[238:239], off
	s_setprio 0
	s_barrier
	s_add_i32 s62, s62, 2
	s_add_u32 s2, s2, 0x100
	s_addc_u32 s3, s3, 0
	s_cmp_gt_u32 s62, 13
	s_cbranch_scc0 .LBB0_702
	s_and_b64 vcc, exec, s[12:13]
	s_cbranch_vccz .LBB0_705
	s_barrier

;     __device__ __forceinline__ size_t hstep() const { return (size_t)HALF * K * 2; }
;     __device__ __forceinline__ const char* tile(const Unit& u, int t) const { return A + (size_t)u.pm * 2 * hstep() + (size_t)t * (BK * 2); }
;     __device__ __forceinline__ size_t hstep() const { return (size_t)HALF * 512; }
; #define PG8_STAGE(bufoff, gbase, voff) do { _Pragma("unroll") for (int _i = 0; _i < 2; ++_i) \
;         __builtin_amdgcn_global_load_lds((const unsigned*)((const char*)(gbase) + (voff)[_i]), (PG8_LAS unsigned*)(lds + (bufoff) + ldsw + _i * 8192), 16, 0, 0); } while (0)
; #define PG8_LDA(dst, b, h) do { _Pragma("unroll") for (int m = 0; m < 4; ++m) _Pragma("unroll") for (int k = 0; k < 2; ++k) dst[m][k] = *(const PG8_LAS bf16x8*)(lds + PG8_SA(b, h) + aoff + m * 2048 + k * 1024); } while (0)
; #define PG8_LDB(dst, b, h) do { _Pragma("unroll") for (int n = 0; n < 2; ++n) _Pragma("unroll") for (int k = 0; k < 2; ++k) dst[n][k] = *(const PG8_LAS bf16x8*)(lds + PG8_SB(b, h) + boff + n * 2048 + k * 1024); } while (0)
; #define PG8_WAIT_V(n) asm volatile("s_waitcnt vmcnt(" #n ")" ::: "memory")
; #define PG8_WAIT_L(n) asm volatile("s_waitcnt lgkmcnt(" #n ")" ::: "memory")
; #define PG8_BAR __builtin_amdgcn_s_barrier()
; #define PG8_SCHED __builtin_amdgcn_sched_barrier(0)
;     __device__ __forceinline__ const char* tile(const Unit& u, int t) const { return U + (long)(t >> 2) * xoff + (size_t)u.pn * (1024 * 512) + (size_t)u.pm * 2 * hstep() + (size_t)(t & 3) * (BK * 2); }
;     ...
;             const bool last = (t == nt - 2);
;             const char* a1 = AS.tile(cur, t + 1);
;             const char* a2 = last ? AS.tile(nu, 0) : AS.tile(cur, t + 2); const char* b2 = last ? nB : cB + (size_t)(t + 2) * kstep;
;             const char* a3 = last ? AS.tile(nu, 1) : AS.tile(cur, t + 3); const char* b3 = b2 + kstep;
;             PG8_LDB(B0, 0, 0); PG8_LDB(B1, 0, 1); PG8_SCHED; PG8_LDA(At, 0, 0); PG8_STAGE(PG8_SA(1, 1), a1 + hstepA, voffA);
;             PG8_WAIT_V(8); PG8_WAIT_L(0); PG8_BAR; PG8_MMA(0, 0, At, B0); PG8_MMA(0, 1, At, B1); PG8_BAR; PG8_SCHED;
;             PG8_LDA(At, 0, 1); PG8_STAGE(PG8_SB(0, 0), b2, voffB); PG8_STAGE(PG8_SB(0, 1), b2 + hstepB, voffB); PG8_STAGE(PG8_SA(0, 0), a2, voffA);
;             PG8_WAIT_V(8); PG8_WAIT_L(0); PG8_BAR; PG8_MMA(1, 0, At, B0); PG8_MMA(1, 1, At, B1); PG8_BAR; PG8_SCHED;
.LBB0_785:
	s_add_u32 s24, s9, s14
	s_addc_u32 s25, s47, 0
	s_xor_b32 s15, s14, 0x100
	s_add_u32 s15, s9, s15
	s_addc_u32 s20, s47, 0
	s_and_b64 s[18:19], s[16:17], exec
	s_cselect_b32 s21, s49, s20
	s_cselect_b32 s20, s48, s15
	s_add_u32 s15, s52, s14
	s_addc_u32 s18, s53, 0
	s_add_u32 s15, s15, 0x100
	s_addc_u32 s22, s18, 0
	s_and_b64 s[18:19], s[16:17], exec
	s_cselect_b32 s23, s46, s22
	s_cselect_b32 s22, s45, s15
	s_addk_i32 s14, 0x180
	s_and_b32 s14, s14, 0x180
	s_add_u32 s18, s9, s14
	s_addc_u32 s19, s47, 0
	s_and_b64 s[14:15], s[16:17], exec
	s_cselect_b32 s14, s50, s18
	s_cselect_b32 s15, s51, s19
	s_add_i32 s17, 0, 0x10000
	s_add_i32 s62, 0, 0x14000
	s_add_u32 s26, s24, 0x10080
	s_addc_u32 s27, s25, 0
	s_add_i32 s61, s17, s30
	s_add_i32 m0, s31, 0xc000
	s_add_i32 s64, s31, 0xe000
	s_add_i32 s58, s61, 0x2000
	v_add_u32_e32 v140, s17, v159
	s_add_u32 s24, s22, 0x10000
	ds_read_b128 v[162:165], v140
	ds_read_b128 v[166:169], v140 offset:1024
	ds_read_b128 v[170:173], v140 offset:2048
	ds_read_b128 v[174:177], v140 offset:3072
	v_add_u32_e32 v140, s62, v159
	s_addc_u32 s25, s23, 0
	s_add_i32 s60, s62, s30
	ds_read_b128 v[178:181], v140
	ds_read_b128 v[182:185], v140 offset:1024
	ds_read_b128 v[186:189], v140 offset:2048
	ds_read_b128 v[190:193], v140 offset:3072
	s_add_i32 s59, s60, 0x2000
	s_add_i32 s57, 0, 0x18000
	s_add_i32 s56, 0, 0x1c000
	s_add_u32 s18, s20, 0x10000
	s_addc_u32 s19, s21, 0
	s_add_i32 s55, s57, s30
	s_add_i32 s54, s55, 0x2000
	s_add_u32 s16, s22, 0x10080
	s_addc_u32 s17, s23, 0
	s_add_i32 s63, s56, s30
	s_add_i32 s62, s63, 0x2000
	v_lshl_add_u64 v[140:141], s[26:27], 0, v[128:129]
	ds_read_b128 v[194:197], v160
	ds_read_b128 v[198:201], v160 offset:1024
	ds_read_b128 v[202:205], v160 offset:2048
	ds_read_b128 v[218:221], v160 offset:3072
	ds_read_b128 v[222:225], v160 offset:4096
	ds_read_b128 v[238:241], v160 offset:5120
	ds_read_b128 v[242:245], v160 offset:6144
	ds_read_b128 v[246:249], v160 offset:7168
	global_load_lds_dwordx4 v[140:141], off
	v_lshl_add_u64 v[140:141], s[26:27], 0, v[130:131]
	s_mov_b32 m0, s64
	s_nop 0
	global_load_lds_dwordx4 v[140:141], off
	s_waitcnt vmcnt(8)
	s_waitcnt lgkmcnt(0)
	s_barrier
	s_setprio 1
	s_waitcnt lgkmcnt(0)
	v_mfma_f32_16x16x32_bf16 v[124:127], v[162:165], v[194:197], v[124:127]
	v_mfma_f32_16x16x32_bf16 v[120:123], v[170:173], v[194:197], v[120:123]
	v_mfma_f32_16x16x32_bf16 v[116:119], v[162:165], v[202:205], v[116:119]
	v_mfma_f32_16x16x32_bf16 v[108:111], v[170:173], v[202:205], v[108:111]
	v_mfma_f32_16x16x32_bf16 v[100:103], v[162:165], v[222:225], v[100:103]
	v_mfma_f32_16x16x32_bf16 v[92:95], v[170:173], v[222:225], v[92:95]
	v_mfma_f32_16x16x32_bf16 v[84:87], v[162:165], v[242:245], v[84:87]
	v_mfma_f32_16x16x32_bf16 v[76:79], v[170:173], v[242:245], v[76:79]
	v_mfma_f32_16x16x32_bf16 v[124:127], v[166:169], v[198:201], v[124:127]
	v_mfma_f32_16x16x32_bf16 v[120:123], v[174:177], v[198:201], v[120:123]
	v_mfma_f32_16x16x32_bf16 v[116:119], v[166:169], v[218:221], v[116:119]
	v_mfma_f32_16x16x32_bf16 v[108:111], v[174:177], v[218:221], v[108:111]
	v_mfma_f32_16x16x32_bf16 v[100:103], v[166:169], v[238:241], v[100:103]
	v_mfma_f32_16x16x32_bf16 v[92:95], v[174:177], v[238:241], v[92:95]
	v_mfma_f32_16x16x32_bf16 v[84:87], v[166:169], v[246:249], v[84:87]
	v_mfma_f32_16x16x32_bf16 v[76:79], v[174:177], v[246:249], v[76:79]
	s_setprio 0
	s_setprio 1
	v_mfma_f32_16x16x32_bf16 v[112:115], v[178:181], v[194:197], v[112:115]
	v_mfma_f32_16x16x32_bf16 v[104:107], v[186:189], v[194:197], v[104:107]
	v_mfma_f32_16x16x32_bf16 v[96:99], v[178:181], v[202:205], v[96:99]
	v_mfma_f32_16x16x32_bf16 v[88:91], v[186:189], v[202:205], v[88:91]
	v_mfma_f32_16x16x32_bf16 v[80:83], v[178:181], v[222:225], v[80:83]
	v_mfma_f32_16x16x32_bf16 v[72:75], v[186:189], v[222:225], v[72:75]
	v_mfma_f32_16x16x32_bf16 v[68:71], v[178:181], v[242:245], v[68:71]
	v_mfma_f32_16x16x32_bf16 v[64:67], v[186:189], v[242:245], v[64:67]
	v_mfma_f32_16x16x32_bf16 v[112:115], v[182:185], v[198:201], v[112:115]
	v_mfma_f32_16x16x32_bf16 v[104:107], v[190:193], v[198:201], v[104:107]
	v_mfma_f32_16x16x32_bf16 v[96:99], v[182:185], v[218:221], v[96:99]
	v_mfma_f32_16x16x32_bf16 v[88:91], v[190:193], v[218:221], v[88:91]
	v_mfma_f32_16x16x32_bf16 v[80:83], v[182:185], v[238:241], v[80:83]
	v_mfma_f32_16x16x32_bf16 v[72:75], v[190:193], v[238:241], v[72:75]
	v_mfma_f32_16x16x32_bf16 v[68:71], v[182:185], v[246:249], v[68:71]
	v_mfma_f32_16x16x32_bf16 v[64:67], v[190:193], v[246:249], v[64:67]
	s_setprio 0
	s_barrier
	s_mov_b32 m0, s61
	v_lshl_add_u64 v[140:141], s[22:23], 0, v[134:135]
	ds_read_b128 v[194:197], v160 offset:16384
	ds_read_b128 v[198:201], v160 offset:17408
	ds_read_b128 v[202:205], v160 offset:18432
	ds_read_b128 v[218:221], v160 offset:19456
	ds_read_b128 v[222:225], v160 offset:20480
	ds_read_b128 v[238:241], v160 offset:21504
	ds_read_b128 v[242:245], v160 offset:22528
	ds_read_b128 v[246:249], v160 offset:23552
	global_load_lds_dwordx4 v[140:141], off
	v_lshl_add_u64 v[206:207], s[22:23], 0, v[132:133]
	s_mov_b32 m0, s58
	v_lshl_add_u64 v[250:251], s[24:25], 0, v[134:135]
	global_load_lds_dwordx4 v[206:207], off
	s_mov_b32 m0, s60
	s_nop 0
	global_load_lds_dwordx4 v[250:251], off
	v_lshl_add_u64 v[250:251], s[24:25], 0, v[132:133]
	s_mov_b32 m0, s59
	s_nop 0
	global_load_lds_dwordx4 v[250:251], off
	s_waitcnt vmcnt(6)
	s_waitcnt lgkmcnt(0)
	s_barrier
; #define PG8_STAGE(bufoff, gbase, voff) do { _Pragma("unroll") for (int _i = 0; _i < 2; ++_i) \
;         __builtin_amdgcn_global_load_lds((const unsigned*)((const char*)(gbase) + (voff)[_i]), (PG8_LAS unsigned*)(lds + (bufoff) + ldsw + _i * 8192), 16, 0, 0); } while (0)
; #define PG8_LDA(dst, b, h) do { _Pragma("unroll") for (int m = 0; m < 4; ++m) _Pragma("unroll") for (int k = 0; k < 2; ++k) dst[m][k] = *(const PG8_LAS bf16x8*)(lds + PG8_SA(b, h) + aoff + m * 2048 + k * 1024); } while (0)
; #define PG8_LDB(dst, b, h) do { _Pragma("unroll") for (int n = 0; n < 2; ++n) _Pragma("unroll") for (int k = 0; k < 2; ++k) dst[n][k] = *(const PG8_LAS bf16x8*)(lds + PG8_SB(b, h) + boff + n * 2048 + k * 1024); } while (0)
; #define PG8_MMA(ai, bj, At, Bt) do { __builtin_amdgcn_s_setprio(1); _Pragma("unroll") for (int m = 0; m < 4; ++m) _Pragma("unroll") for (int n = 0; n < 2; ++n) _Pragma("unroll") for (int k = 0; k < 2; ++k) \
;         acc[ai][bj][m][n] = __builtin_amdgcn_mfma_f32_16x16x32_bf16(Bt[n][k], At[m][k], acc[ai][bj][m][n], 0, 0, 0); __builtin_amdgcn_s_setprio(0); } while (0)
; #define PG8_WAIT_V(n) asm volatile("s_waitcnt vmcnt(" #n ")" ::: "memory")
; #define PG8_WAIT_L(n) asm volatile("s_waitcnt lgkmcnt(" #n ")" ::: "memory")
; #define PG8_BAR __builtin_amdgcn_s_barrier()
; #define PG8_SCHED __builtin_amdgcn_sched_barrier(0)
;     ...
;             PG8_WAIT_V(8); PG8_WAIT_L(0); PG8_BAR; PG8_MMA(1, 0, At, B0); PG8_MMA(1, 1, At, B1); PG8_BAR; PG8_SCHED;
;             PG8_LDB(B0, 1, 0); PG8_LDB(B1, 1, 1); PG8_SCHED; PG8_LDA(At, 1, 0); PG8_STAGE(PG8_SA(0, 1), a2 + hstepA, voffA);
;             PG8_WAIT_V(8); PG8_WAIT_L(0); PG8_BAR; PG8_MMA(0, 0, At, B0); PG8_MMA(0, 1, At, B1); PG8_BAR; PG8_SCHED;
	s_setprio 1
	s_waitcnt lgkmcnt(0)
	v_mfma_f32_16x16x32_bf16 v[60:63], v[162:165], v[194:197], v[60:63]
	v_mfma_f32_16x16x32_bf16 v[56:59], v[170:173], v[194:197], v[56:59]
	v_mfma_f32_16x16x32_bf16 v[52:55], v[162:165], v[202:205], v[52:55]
	v_mfma_f32_16x16x32_bf16 v[44:47], v[170:173], v[202:205], v[44:47]
	v_mfma_f32_16x16x32_bf16 v[36:39], v[162:165], v[222:225], v[36:39]
	v_mfma_f32_16x16x32_bf16 v[28:31], v[170:173], v[222:225], v[28:31]
	v_mfma_f32_16x16x32_bf16 v[20:23], v[162:165], v[242:245], v[20:23]
	v_mfma_f32_16x16x32_bf16 v[12:15], v[170:173], v[242:245], v[12:15]
	v_mfma_f32_16x16x32_bf16 v[60:63], v[166:169], v[198:201], v[60:63]
	v_mfma_f32_16x16x32_bf16 v[56:59], v[174:177], v[198:201], v[56:59]
	v_mfma_f32_16x16x32_bf16 v[52:55], v[166:169], v[218:221], v[52:55]
	v_mfma_f32_16x16x32_bf16 v[44:47], v[174:177], v[218:221], v[44:47]
	v_mfma_f32_16x16x32_bf16 v[36:39], v[166:169], v[238:241], v[36:39]
	v_mfma_f32_16x16x32_bf16 v[28:31], v[174:177], v[238:241], v[28:31]
	v_mfma_f32_16x16x32_bf16 v[20:23], v[166:169], v[246:249], v[20:23]
	v_mfma_f32_16x16x32_bf16 v[12:15], v[174:177], v[246:249], v[12:15]
	s_setprio 0
	s_setprio 1
	v_mfma_f32_16x16x32_bf16 v[48:51], v[178:181], v[194:197], v[48:51]
	v_mfma_f32_16x16x32_bf16 v[40:43], v[186:189], v[194:197], v[40:43]
	v_mfma_f32_16x16x32_bf16 v[32:35], v[178:181], v[202:205], v[32:35]
	v_mfma_f32_16x16x32_bf16 v[24:27], v[186:189], v[202:205], v[24:27]
	v_mfma_f32_16x16x32_bf16 v[16:19], v[178:181], v[222:225], v[16:19]
	v_mfma_f32_16x16x32_bf16 v[8:11], v[186:189], v[222:225], v[8:11]
	v_mfma_f32_16x16x32_bf16 v[4:7], v[178:181], v[242:245], v[4:7]
	v_mfma_f32_16x16x32_bf16 v[0:3], v[186:189], v[242:245], v[0:3]
	v_mfma_f32_16x16x32_bf16 v[48:51], v[182:185], v[198:201], v[48:51]
	v_mfma_f32_16x16x32_bf16 v[40:43], v[190:193], v[198:201], v[40:43]
	v_mfma_f32_16x16x32_bf16 v[32:35], v[182:185], v[218:221], v[32:35]
	v_mfma_f32_16x16x32_bf16 v[24:27], v[190:193], v[218:221], v[24:27]
	v_mfma_f32_16x16x32_bf16 v[16:19], v[182:185], v[238:241], v[16:19]
	v_mfma_f32_16x16x32_bf16 v[8:11], v[190:193], v[238:241], v[8:11]
	v_mfma_f32_16x16x32_bf16 v[4:7], v[182:185], v[246:249], v[4:7]
	v_mfma_f32_16x16x32_bf16 v[0:3], v[190:193], v[246:249], v[0:3]
	v_lshl_add_u64 v[250:251], s[20:21], 0, v[128:129]
	s_mov_b32 m0, s31
	s_nop 0
	global_load_lds_dwordx4 v[250:251], off
	v_lshl_add_u64 v[250:251], s[20:21], 0, v[130:131]
	s_mov_b32 m0, s35
	s_nop 0
	global_load_lds_dwordx4 v[250:251], off
	s_setprio 0
	s_barrier
	v_add_u32_e32 v161, s57, v159
	ds_read_b128 v[162:165], v161
	ds_read_b128 v[166:169], v161 offset:1024
	ds_read_b128 v[170:173], v161 offset:2048
	ds_read_b128 v[174:177], v161 offset:3072
	v_add_u32_e32 v161, s56, v159
	ds_read_b128 v[178:181], v161
	ds_read_b128 v[182:185], v161 offset:1024
	ds_read_b128 v[186:189], v161 offset:2048
	ds_read_b128 v[190:193], v161 offset:3072
	s_mov_b32 m0, s36
	v_lshl_add_u64 v[250:251], s[18:19], 0, v[128:129]
	ds_read_b128 v[194:197], v160 offset:32768
	ds_read_b128 v[198:201], v160 offset:33792
	ds_read_b128 v[202:205], v160 offset:34816
	ds_read_b128 v[218:221], v160 offset:35840
	ds_read_b128 v[222:225], v160 offset:36864
	ds_read_b128 v[238:241], v160 offset:37888
	ds_read_b128 v[242:245], v160 offset:38912
	ds_read_b128 v[246:249], v160 offset:39936
	global_load_lds_dwordx4 v[250:251], off
	v_lshl_add_u64 v[250:251], s[18:19], 0, v[130:131]
	s_mov_b32 m0, s37
	s_nop 0
	global_load_lds_dwordx4 v[250:251], off
	s_waitcnt vmcnt(8)
	s_waitcnt lgkmcnt(0)
	s_barrier
	s_setprio 1
	s_waitcnt lgkmcnt(0)
	v_mfma_f32_16x16x32_bf16 v[124:127], v[162:165], v[194:197], v[124:127]
	v_mfma_f32_16x16x32_bf16 v[120:123], v[170:173], v[194:197], v[120:123]
	v_mfma_f32_16x16x32_bf16 v[116:119], v[162:165], v[202:205], v[116:119]
	v_mfma_f32_16x16x32_bf16 v[108:111], v[170:173], v[202:205], v[108:111]
	v_mfma_f32_16x16x32_bf16 v[100:103], v[162:165], v[222:225], v[100:103]
	v_mfma_f32_16x16x32_bf16 v[92:95], v[170:173], v[222:225], v[92:95]
	v_mfma_f32_16x16x32_bf16 v[84:87], v[162:165], v[242:245], v[84:87]
	v_mfma_f32_16x16x32_bf16 v[76:79], v[170:173], v[242:245], v[76:79]
	v_mfma_f32_16x16x32_bf16 v[124:127], v[166:169], v[198:201], v[124:127]
	v_mfma_f32_16x16x32_bf16 v[120:123], v[174:177], v[198:201], v[120:123]
	v_mfma_f32_16x16x32_bf16 v[116:119], v[166:169], v[218:221], v[116:119]
	v_mfma_f32_16x16x32_bf16 v[108:111], v[174:177], v[218:221], v[108:111]
	v_mfma_f32_16x16x32_bf16 v[100:103], v[166:169], v[238:241], v[100:103]
	v_mfma_f32_16x16x32_bf16 v[92:95], v[174:177], v[238:241], v[92:95]
	v_mfma_f32_16x16x32_bf16 v[84:87], v[166:169], v[246:249], v[84:87]
	v_mfma_f32_16x16x32_bf16 v[76:79], v[174:177], v[246:249], v[76:79]
	s_setprio 0
	s_setprio 1
	v_mfma_f32_16x16x32_bf16 v[112:115], v[178:181], v[194:197], v[112:115]
	v_mfma_f32_16x16x32_bf16 v[104:107], v[186:189], v[194:197], v[104:107]
	v_mfma_f32_16x16x32_bf16 v[96:99], v[178:181], v[202:205], v[96:99]
	v_mfma_f32_16x16x32_bf16 v[88:91], v[186:189], v[202:205], v[88:91]
	v_mfma_f32_16x16x32_bf16 v[80:83], v[178:181], v[222:225], v[80:83]
	v_mfma_f32_16x16x32_bf16 v[72:75], v[186:189], v[222:225], v[72:75]
	v_mfma_f32_16x16x32_bf16 v[68:71], v[178:181], v[242:245], v[68:71]
	v_mfma_f32_16x16x32_bf16 v[64:67], v[186:189], v[242:245], v[64:67]
	v_mfma_f32_16x16x32_bf16 v[112:115], v[182:185], v[198:201], v[112:115]
	v_mfma_f32_16x16x32_bf16 v[104:107], v[190:193], v[198:201], v[104:107]
	v_mfma_f32_16x16x32_bf16 v[96:99], v[182:185], v[218:221], v[96:99]
	v_mfma_f32_16x16x32_bf16 v[88:91], v[190:193], v[218:221], v[88:91]
	v_mfma_f32_16x16x32_bf16 v[80:83], v[182:185], v[238:241], v[80:83]
	v_mfma_f32_16x16x32_bf16 v[72:75], v[190:193], v[238:241], v[72:75]
	v_mfma_f32_16x16x32_bf16 v[68:71], v[182:185], v[246:249], v[68:71]
	v_mfma_f32_16x16x32_bf16 v[64:67], v[190:193], v[246:249], v[64:67]
	s_setprio 0
	s_barrier
; #define PG8_STAGE(bufoff, gbase, voff) do { _Pragma("unroll") for (int _i = 0; _i < 2; ++_i) \
;         __builtin_amdgcn_global_load_lds((const unsigned*)((const char*)(gbase) + (voff)[_i]), (PG8_LAS unsigned*)(lds + (bufoff) + ldsw + _i * 8192), 16, 0, 0); } while (0)
; #define PG8_LDA(dst, b, h) do { _Pragma("unroll") for (int m = 0; m < 4; ++m) _Pragma("unroll") for (int k = 0; k < 2; ++k) dst[m][k] = *(const PG8_LAS bf16x8*)(lds + PG8_SA(b, h) + aoff + m * 2048 + k * 1024); } while (0)
; #define PG8_MMA(ai, bj, At, Bt) do { __builtin_amdgcn_s_setprio(1); _Pragma("unroll") for (int m = 0; m < 4; ++m) _Pragma("unroll") for (int n = 0; n < 2; ++n) _Pragma("unroll") for (int k = 0; k < 2; ++k) \
;         acc[ai][bj][m][n] = __builtin_amdgcn_mfma_f32_16x16x32_bf16(Bt[n][k], At[m][k], acc[ai][bj][m][n], 0, 0, 0); __builtin_amdgcn_s_setprio(0); } while (0)
; #define PG8_WAIT_V(n) asm volatile("s_waitcnt vmcnt(" #n ")" ::: "memory")
; #define PG8_WAIT_L(n) asm volatile("s_waitcnt lgkmcnt(" #n ")" ::: "memory")
; #define PG8_BAR __builtin_amdgcn_s_barrier()
; #define PG8_SCHED __builtin_amdgcn_sched_barrier(0)
;     ...
;             PG8_LDA(At, 1, 1); PG8_STAGE(PG8_SB(1, 0), b3, voffB); PG8_STAGE(PG8_SB(1, 1), b3 + hstepB, voffB); PG8_STAGE(PG8_SA(1, 0), a3, voffA);
;             PG8_WAIT_V(8); PG8_WAIT_L(0); PG8_BAR; PG8_MMA(1, 0, At, B0); PG8_MMA(1, 1, At, B1); PG8_BAR; PG8_SCHED;
;         }
	s_mov_b32 m0, s55
	v_lshl_add_u64 v[140:141], v[140:141], 0, s[66:67]
	ds_read_b128 v[194:197], v160 offset:49152
	ds_read_b128 v[198:201], v160 offset:50176
	ds_read_b128 v[202:205], v160 offset:51200
	ds_read_b128 v[218:221], v160 offset:52224
	ds_read_b128 v[222:225], v160 offset:53248
	ds_read_b128 v[238:241], v160 offset:54272
	ds_read_b128 v[242:245], v160 offset:55296
	ds_read_b128 v[246:249], v160 offset:56320
	global_load_lds_dwordx4 v[140:141], off
	v_lshl_add_u64 v[140:141], v[206:207], 0, s[66:67]
	s_mov_b32 m0, s54
	s_nop 0
	global_load_lds_dwordx4 v[140:141], off
	v_lshl_add_u64 v[140:141], s[16:17], 0, v[134:135]
	s_mov_b32 m0, s63
	s_nop 0
	global_load_lds_dwordx4 v[140:141], off
	v_lshl_add_u64 v[140:141], s[16:17], 0, v[132:133]
	s_mov_b32 m0, s62
	s_nop 0
	global_load_lds_dwordx4 v[140:141], off
	s_waitcnt vmcnt(6)
	s_waitcnt lgkmcnt(0)
	s_barrier
	s_setprio 1
	s_waitcnt lgkmcnt(0)
	v_mfma_f32_16x16x32_bf16 v[60:63], v[162:165], v[194:197], v[60:63]
	v_mfma_f32_16x16x32_bf16 v[56:59], v[170:173], v[194:197], v[56:59]
	v_mfma_f32_16x16x32_bf16 v[52:55], v[162:165], v[202:205], v[52:55]
	v_mfma_f32_16x16x32_bf16 v[44:47], v[170:173], v[202:205], v[44:47]
	v_mfma_f32_16x16x32_bf16 v[36:39], v[162:165], v[222:225], v[36:39]
	v_mfma_f32_16x16x32_bf16 v[28:31], v[170:173], v[222:225], v[28:31]
	v_mfma_f32_16x16x32_bf16 v[20:23], v[162:165], v[242:245], v[20:23]
	v_mfma_f32_16x16x32_bf16 v[12:15], v[170:173], v[242:245], v[12:15]
	v_mfma_f32_16x16x32_bf16 v[60:63], v[166:169], v[198:201], v[60:63]
	v_mfma_f32_16x16x32_bf16 v[56:59], v[174:177], v[198:201], v[56:59]
	v_mfma_f32_16x16x32_bf16 v[52:55], v[166:169], v[218:221], v[52:55]
	v_mfma_f32_16x16x32_bf16 v[44:47], v[174:177], v[218:221], v[44:47]
	v_mfma_f32_16x16x32_bf16 v[36:39], v[166:169], v[238:241], v[36:39]
	v_mfma_f32_16x16x32_bf16 v[28:31], v[174:177], v[238:241], v[28:31]
	v_mfma_f32_16x16x32_bf16 v[20:23], v[166:169], v[246:249], v[20:23]
	v_mfma_f32_16x16x32_bf16 v[12:15], v[174:177], v[246:249], v[12:15]
	s_setprio 0
	s_setprio 1
	v_mfma_f32_16x16x32_bf16 v[48:51], v[178:181], v[194:197], v[48:51]
	v_mfma_f32_16x16x32_bf16 v[40:43], v[186:189], v[194:197], v[40:43]
	v_mfma_f32_16x16x32_bf16 v[32:35], v[178:181], v[202:205], v[32:35]
	v_mfma_f32_16x16x32_bf16 v[24:27], v[186:189], v[202:205], v[24:27]
	v_mfma_f32_16x16x32_bf16 v[16:19], v[178:181], v[222:225], v[16:19]
	v_mfma_f32_16x16x32_bf16 v[8:11], v[186:189], v[222:225], v[8:11]
	v_mfma_f32_16x16x32_bf16 v[4:7], v[178:181], v[242:245], v[4:7]
	v_mfma_f32_16x16x32_bf16 v[0:3], v[186:189], v[242:245], v[0:3]
	v_mfma_f32_16x16x32_bf16 v[48:51], v[182:185], v[198:201], v[48:51]
	v_mfma_f32_16x16x32_bf16 v[40:43], v[190:193], v[198:201], v[40:43]
	v_mfma_f32_16x16x32_bf16 v[32:35], v[182:185], v[218:221], v[32:35]
	v_mfma_f32_16x16x32_bf16 v[24:27], v[190:193], v[218:221], v[24:27]
	v_mfma_f32_16x16x32_bf16 v[16:19], v[182:185], v[238:241], v[16:19]
	v_mfma_f32_16x16x32_bf16 v[8:11], v[190:193], v[238:241], v[8:11]
	v_mfma_f32_16x16x32_bf16 v[4:7], v[182:185], v[246:249], v[4:7]
	v_mfma_f32_16x16x32_bf16 v[0:3], v[190:193], v[246:249], v[0:3]
	v_lshl_add_u64 v[140:141], s[14:15], 0, v[128:129]
	s_mov_b32 m0, s40
	s_nop 0
	global_load_lds_dwordx4 v[140:141], off
	v_lshl_add_u64 v[140:141], s[14:15], 0, v[130:131]
	s_mov_b32 m0, s41
	s_nop 0
	global_load_lds_dwordx4 v[140:141], off
	s_setprio 0
	s_barrier
	s_andn2_b64 vcc, exec, s[12:13]
	s_mov_b64 s[16:17], -1
	s_mov_b64 s[12:13], 0
	s_movk_i32 s14, 0x100
	s_cbranch_vccz .LBB0_785
	s_and_b64 vcc, exec, s[4:5]
	s_cbranch_vccz .LBB0_788
	s_barrier

;     __device__ __forceinline__ size_t hstep() const { return (size_t)HALF * K * 2; }
;     __device__ __forceinline__ const char* tile(const Unit& u, int t) const { return A + (size_t)u.pm * 2 * hstep() + (size_t)t * (BK * 2); }
;     __device__ __forceinline__ size_t hstep() const { return (size_t)HALF * 512; }
; #define PG8_STAGE(bufoff, gbase, voff) do { _Pragma("unroll") for (int _i = 0; _i < 2; ++_i) \
;         __builtin_amdgcn_global_load_lds((const unsigned*)((const char*)(gbase) + (voff)[_i]), (PG8_LAS unsigned*)(lds + (bufoff) + ldsw + _i * 8192), 16, 0, 0); } while (0)
; #define PG8_LDA(dst, b, h) do { _Pragma("unroll") for (int m = 0; m < 4; ++m) _Pragma("unroll") for (int k = 0; k < 2; ++k) dst[m][k] = *(const PG8_LAS bf16x8*)(lds + PG8_SA(b, h) + aoff + m * 2048 + k * 1024); } while (0)
; #define PG8_LDB(dst, b, h) do { _Pragma("unroll") for (int n = 0; n < 2; ++n) _Pragma("unroll") for (int k = 0; k < 2; ++k) dst[n][k] = *(const PG8_LAS bf16x8*)(lds + PG8_SB(b, h) + boff + n * 2048 + k * 1024); } while (0)
; #define PG8_WAIT_V(n) asm volatile("s_waitcnt vmcnt(" #n ")" ::: "memory")
; #define PG8_WAIT_L(n) asm volatile("s_waitcnt lgkmcnt(" #n ")" ::: "memory")
; #define PG8_BAR __builtin_amdgcn_s_barrier()
; #define PG8_SCHED __builtin_amdgcn_sched_barrier(0)
;     __device__ __forceinline__ const char* tile(const Unit& u, int t) const { return U + (long)(t >> 2) * xoff + (size_t)u.pn * (1024 * 512) + (size_t)u.pm * 2 * hstep() + (size_t)(t & 3) * (BK * 2); }
;     ...
;             const bool last = (t == nt - 2);
;             const char* a1 = AS.tile(cur, t + 1);
;             const char* a2 = last ? AS.tile(nu, 0) : AS.tile(cur, t + 2); const char* b2 = last ? nB : cB + (size_t)(t + 2) * kstep;
;             const char* a3 = last ? AS.tile(nu, 1) : AS.tile(cur, t + 3); const char* b3 = b2 + kstep;
;             PG8_LDB(B0, 0, 0); PG8_LDB(B1, 0, 1); PG8_SCHED; PG8_LDA(At, 0, 0); PG8_STAGE(PG8_SA(1, 1), a1 + hstepA, voffA);
;             PG8_WAIT_V(8); PG8_WAIT_L(0); PG8_BAR; PG8_MMA(0, 0, At, B0); PG8_MMA(0, 1, At, B1); PG8_BAR; PG8_SCHED;
;             PG8_LDA(At, 0, 1); PG8_STAGE(PG8_SB(0, 0), b2, voffB); PG8_STAGE(PG8_SB(0, 1), b2 + hstepB, voffB); PG8_STAGE(PG8_SA(0, 0), a2, voffA);
;             PG8_WAIT_V(8); PG8_WAIT_L(0); PG8_BAR; PG8_MMA(1, 0, At, B0); PG8_MMA(1, 1, At, B1); PG8_BAR; PG8_SCHED;
.LBB0_833:
	s_add_u32 s47, s44, s16
	s_addc_u32 s48, s45, s17
	s_and_b64 s[20:21], exec, s[20:21]
	s_cselect_b32 s21, s43, s48
	s_cselect_b32 s20, s42, s47
	s_add_i32 s47, s46, -3
	s_lshr_b32 s48, s47, 2
	s_mul_i32 s48, s48, 0x6000000
	s_add_u32 s48, s1, s48
	s_addc_u32 s49, s3, 0
	s_and_b32 s50, s16, 0x100
	s_add_u32 s48, s48, s50
	s_addc_u32 s49, s49, 0
	s_add_i32 s50, 0, 0x10000
	v_add_u32_e32 v137, s50, v144
	s_add_i32 s51, 0, 0x14000
	ds_read_b128 v[148:151], v137
	ds_read_b128 v[152:155], v137 offset:1024
	ds_read_b128 v[156:159], v137 offset:2048
	ds_read_b128 v[160:163], v137 offset:3072
	v_add_u32_e32 v137, s51, v144
	ds_read_b128 v[164:167], v137
	ds_read_b128 v[168:171], v137 offset:1024
	ds_read_b128 v[172:175], v137 offset:2048
	ds_read_b128 v[176:179], v137 offset:3072
	s_add_u32 s48, s48, 0x10080
	s_addc_u32 s49, s49, 0
	v_lshl_add_u64 v[140:141], s[48:49], 0, v[128:129]
	s_add_i32 m0, s27, 0xc000
	ds_read_b128 v[180:183], v142
	ds_read_b128 v[184:187], v142 offset:1024
	ds_read_b128 v[188:191], v142 offset:2048
	ds_read_b128 v[192:195], v142 offset:3072
	ds_read_b128 v[196:199], v142 offset:4096
	ds_read_b128 v[200:203], v142 offset:5120
	ds_read_b128 v[204:207], v142 offset:6144
	ds_read_b128 v[218:221], v142 offset:7168
	global_load_lds_dwordx4 v[140:141], off
	v_lshl_add_u64 v[140:141], s[48:49], 0, v[130:131]
	s_add_i32 m0, s27, 0xe000
	s_nop 0
	global_load_lds_dwordx4 v[140:141], off
	s_waitcnt vmcnt(8)
	s_waitcnt lgkmcnt(0)
	s_barrier
	s_setprio 1
	s_waitcnt lgkmcnt(0)
	v_mfma_f32_16x16x32_bf16 v[124:127], v[148:151], v[180:183], v[124:127]
	v_mfma_f32_16x16x32_bf16 v[120:123], v[156:159], v[180:183], v[120:123]
	v_mfma_f32_16x16x32_bf16 v[108:111], v[148:151], v[188:191], v[108:111]
	v_mfma_f32_16x16x32_bf16 v[104:107], v[156:159], v[188:191], v[104:107]
	v_mfma_f32_16x16x32_bf16 v[92:95], v[148:151], v[196:199], v[92:95]
	v_mfma_f32_16x16x32_bf16 v[88:91], v[156:159], v[196:199], v[88:91]
	v_mfma_f32_16x16x32_bf16 v[76:79], v[148:151], v[204:207], v[76:79]
	v_mfma_f32_16x16x32_bf16 v[72:75], v[156:159], v[204:207], v[72:75]
	v_mfma_f32_16x16x32_bf16 v[124:127], v[152:155], v[184:187], v[124:127]
	v_mfma_f32_16x16x32_bf16 v[120:123], v[160:163], v[184:187], v[120:123]
	v_mfma_f32_16x16x32_bf16 v[108:111], v[152:155], v[192:195], v[108:111]
	v_mfma_f32_16x16x32_bf16 v[104:107], v[160:163], v[192:195], v[104:107]
	v_mfma_f32_16x16x32_bf16 v[92:95], v[152:155], v[200:203], v[92:95]
	v_mfma_f32_16x16x32_bf16 v[88:91], v[160:163], v[200:203], v[88:91]
	v_mfma_f32_16x16x32_bf16 v[76:79], v[152:155], v[218:221], v[76:79]
	v_mfma_f32_16x16x32_bf16 v[72:75], v[160:163], v[218:221], v[72:75]
	s_setprio 0
	s_setprio 1
	v_mfma_f32_16x16x32_bf16 v[116:119], v[164:167], v[180:183], v[116:119]
	v_mfma_f32_16x16x32_bf16 v[112:115], v[172:175], v[180:183], v[112:115]
	v_mfma_f32_16x16x32_bf16 v[100:103], v[164:167], v[188:191], v[100:103]
	v_mfma_f32_16x16x32_bf16 v[96:99], v[172:175], v[188:191], v[96:99]
	v_mfma_f32_16x16x32_bf16 v[84:87], v[164:167], v[196:199], v[84:87]
	v_mfma_f32_16x16x32_bf16 v[80:83], v[172:175], v[196:199], v[80:83]
	v_mfma_f32_16x16x32_bf16 v[68:71], v[164:167], v[204:207], v[68:71]
	v_mfma_f32_16x16x32_bf16 v[64:67], v[172:175], v[204:207], v[64:67]
	v_mfma_f32_16x16x32_bf16 v[116:119], v[168:171], v[184:187], v[116:119]
	v_mfma_f32_16x16x32_bf16 v[112:115], v[176:179], v[184:187], v[112:115]
	v_mfma_f32_16x16x32_bf16 v[100:103], v[168:171], v[192:195], v[100:103]
	v_mfma_f32_16x16x32_bf16 v[96:99], v[176:179], v[192:195], v[96:99]
	v_mfma_f32_16x16x32_bf16 v[84:87], v[168:171], v[200:203], v[84:87]
	v_mfma_f32_16x16x32_bf16 v[80:83], v[176:179], v[200:203], v[80:83]
	v_mfma_f32_16x16x32_bf16 v[68:71], v[168:171], v[218:221], v[68:71]
	v_mfma_f32_16x16x32_bf16 v[64:67], v[176:179], v[218:221], v[64:67]
	s_setprio 0
	s_barrier
	s_add_i32 s48, s50, s26
	v_lshl_add_u64 v[140:141], s[20:21], 0, v[134:135]
	s_mov_b32 m0, s48
	ds_read_b128 v[180:183], v142 offset:16384
	ds_read_b128 v[184:187], v142 offset:17408
	ds_read_b128 v[188:191], v142 offset:18432
	ds_read_b128 v[192:195], v142 offset:19456
	ds_read_b128 v[196:199], v142 offset:20480
	ds_read_b128 v[200:203], v142 offset:21504
	ds_read_b128 v[204:207], v142 offset:22528
	ds_read_b128 v[218:221], v142 offset:23552
	global_load_lds_dwordx4 v[140:141], off
	s_add_i32 m0, s48, 0x2000
	s_add_u32 s48, s20, 0x20000
	v_lshl_add_u64 v[222:223], s[20:21], 0, v[132:133]
	s_addc_u32 s49, s21, 0
	s_add_i32 s50, s51, s26
	global_load_lds_dwordx4 v[222:223], off
	v_lshl_add_u64 v[224:225], s[48:49], 0, v[134:135]
	s_mov_b32 m0, s50
	s_nop 0
	global_load_lds_dwordx4 v[224:225], off
	v_lshl_add_u64 v[224:225], s[48:49], 0, v[132:133]
	s_add_i32 m0, s50, 0x2000
	s_nop 0
	global_load_lds_dwordx4 v[224:225], off
	s_waitcnt vmcnt(6)
	s_waitcnt lgkmcnt(0)
	s_barrier
; #define PG8_STAGE(bufoff, gbase, voff) do { _Pragma("unroll") for (int _i = 0; _i < 2; ++_i) \
;         __builtin_amdgcn_global_load_lds((const unsigned*)((const char*)(gbase) + (voff)[_i]), (PG8_LAS unsigned*)(lds + (bufoff) + ldsw + _i * 8192), 16, 0, 0); } while (0)
; #define PG8_LDA(dst, b, h) do { _Pragma("unroll") for (int m = 0; m < 4; ++m) _Pragma("unroll") for (int k = 0; k < 2; ++k) dst[m][k] = *(const PG8_LAS bf16x8*)(lds + PG8_SA(b, h) + aoff + m * 2048 + k * 1024); } while (0)
; #define PG8_LDB(dst, b, h) do { _Pragma("unroll") for (int n = 0; n < 2; ++n) _Pragma("unroll") for (int k = 0; k < 2; ++k) dst[n][k] = *(const PG8_LAS bf16x8*)(lds + PG8_SB(b, h) + boff + n * 2048 + k * 1024); } while (0)
; #define PG8_MMA(ai, bj, At, Bt) do { __builtin_amdgcn_s_setprio(1); _Pragma("unroll") for (int m = 0; m < 4; ++m) _Pragma("unroll") for (int n = 0; n < 2; ++n) _Pragma("unroll") for (int k = 0; k < 2; ++k) \
;         acc[ai][bj][m][n] = __builtin_amdgcn_mfma_f32_16x16x32_bf16(Bt[n][k], At[m][k], acc[ai][bj][m][n], 0, 0, 0); __builtin_amdgcn_s_setprio(0); } while (0)
; #define PG8_WAIT_V(n) asm volatile("s_waitcnt vmcnt(" #n ")" ::: "memory")
; #define PG8_WAIT_L(n) asm volatile("s_waitcnt lgkmcnt(" #n ")" ::: "memory")
; #define PG8_BAR __builtin_amdgcn_s_barrier()
; #define PG8_SCHED __builtin_amdgcn_sched_barrier(0)
;     ...
;             PG8_WAIT_V(8); PG8_WAIT_L(0); PG8_BAR; PG8_MMA(1, 0, At, B0); PG8_MMA(1, 1, At, B1); PG8_BAR; PG8_SCHED;
;             PG8_LDB(B0, 1, 0); PG8_LDB(B1, 1, 1); PG8_SCHED; PG8_LDA(At, 1, 0); PG8_STAGE(PG8_SA(0, 1), a2 + hstepA, voffA);
;             PG8_WAIT_V(8); PG8_WAIT_L(0); PG8_BAR; PG8_MMA(0, 0, At, B0); PG8_MMA(0, 1, At, B1); PG8_BAR; PG8_SCHED;
	s_setprio 1
	s_waitcnt lgkmcnt(0)
	v_mfma_f32_16x16x32_bf16 v[60:63], v[148:151], v[180:183], v[60:63]
	v_mfma_f32_16x16x32_bf16 v[56:59], v[156:159], v[180:183], v[56:59]
	v_mfma_f32_16x16x32_bf16 v[44:47], v[148:151], v[188:191], v[44:47]
	v_mfma_f32_16x16x32_bf16 v[40:43], v[156:159], v[188:191], v[40:43]
	v_mfma_f32_16x16x32_bf16 v[28:31], v[148:151], v[196:199], v[28:31]
	v_mfma_f32_16x16x32_bf16 v[24:27], v[156:159], v[196:199], v[24:27]
	v_mfma_f32_16x16x32_bf16 v[12:15], v[148:151], v[204:207], v[12:15]
	v_mfma_f32_16x16x32_bf16 v[8:11], v[156:159], v[204:207], v[8:11]
	v_mfma_f32_16x16x32_bf16 v[60:63], v[152:155], v[184:187], v[60:63]
	v_mfma_f32_16x16x32_bf16 v[56:59], v[160:163], v[184:187], v[56:59]
	v_mfma_f32_16x16x32_bf16 v[44:47], v[152:155], v[192:195], v[44:47]
	v_mfma_f32_16x16x32_bf16 v[40:43], v[160:163], v[192:195], v[40:43]
	v_mfma_f32_16x16x32_bf16 v[28:31], v[152:155], v[200:203], v[28:31]
	v_mfma_f32_16x16x32_bf16 v[24:27], v[160:163], v[200:203], v[24:27]
	v_mfma_f32_16x16x32_bf16 v[12:15], v[152:155], v[218:221], v[12:15]
	v_mfma_f32_16x16x32_bf16 v[8:11], v[160:163], v[218:221], v[8:11]
	s_setprio 0
	s_setprio 1
	v_mfma_f32_16x16x32_bf16 v[52:55], v[164:167], v[180:183], v[52:55]
	v_mfma_f32_16x16x32_bf16 v[48:51], v[172:175], v[180:183], v[48:51]
	v_mfma_f32_16x16x32_bf16 v[36:39], v[164:167], v[188:191], v[36:39]
	v_mfma_f32_16x16x32_bf16 v[32:35], v[172:175], v[188:191], v[32:35]
	v_mfma_f32_16x16x32_bf16 v[20:23], v[164:167], v[196:199], v[20:23]
	v_mfma_f32_16x16x32_bf16 v[16:19], v[172:175], v[196:199], v[16:19]
	v_mfma_f32_16x16x32_bf16 v[4:7], v[164:167], v[204:207], v[4:7]
	v_mfma_f32_16x16x32_bf16 v[0:3], v[172:175], v[204:207], v[0:3]
	v_mfma_f32_16x16x32_bf16 v[52:55], v[168:171], v[184:187], v[52:55]
	v_mfma_f32_16x16x32_bf16 v[48:51], v[176:179], v[184:187], v[48:51]
	v_mfma_f32_16x16x32_bf16 v[36:39], v[168:171], v[192:195], v[36:39]
	v_mfma_f32_16x16x32_bf16 v[32:35], v[176:179], v[192:195], v[32:35]
	v_mfma_f32_16x16x32_bf16 v[20:23], v[168:171], v[200:203], v[20:23]
	v_mfma_f32_16x16x32_bf16 v[16:19], v[176:179], v[200:203], v[16:19]
	v_mfma_f32_16x16x32_bf16 v[4:7], v[168:171], v[218:221], v[4:7]
	v_mfma_f32_16x16x32_bf16 v[0:3], v[176:179], v[218:221], v[0:3]
	v_lshl_add_u64 v[224:225], s[22:23], 0, v[128:129]
	s_mov_b32 m0, s27
	s_nop 0
	global_load_lds_dwordx4 v[224:225], off
	v_lshl_add_u64 v[224:225], s[22:23], 0, v[130:131]
	s_mov_b32 m0, s28
	s_nop 0
	global_load_lds_dwordx4 v[224:225], off
	s_setprio 0
	s_barrier
	s_add_i32 s48, 0, 0x18000
	v_add_u32_e32 v137, s48, v144
	s_add_i32 s49, 0, 0x1c000
	ds_read_b128 v[148:151], v137
	ds_read_b128 v[152:155], v137 offset:1024
	ds_read_b128 v[156:159], v137 offset:2048
	ds_read_b128 v[160:163], v137 offset:3072
	v_add_u32_e32 v137, s49, v144
	ds_read_b128 v[164:167], v137
	ds_read_b128 v[168:171], v137 offset:1024
	ds_read_b128 v[172:175], v137 offset:2048
	ds_read_b128 v[176:179], v137 offset:3072
	s_add_u32 s22, s22, 0x10000
	s_addc_u32 s23, s23, 0
	s_mov_b32 m0, s29
	v_lshl_add_u64 v[224:225], s[22:23], 0, v[128:129]
	ds_read_b128 v[180:183], v142 offset:32768
	ds_read_b128 v[184:187], v142 offset:33792
	ds_read_b128 v[188:191], v142 offset:34816
	ds_read_b128 v[192:195], v142 offset:35840
	ds_read_b128 v[196:199], v142 offset:36864
	ds_read_b128 v[200:203], v142 offset:37888
	ds_read_b128 v[204:207], v142 offset:38912
	ds_read_b128 v[218:221], v142 offset:39936
	global_load_lds_dwordx4 v[224:225], off
	v_lshl_add_u64 v[224:225], s[22:23], 0, v[130:131]
	s_mov_b32 m0, s30
	s_nop 0
	global_load_lds_dwordx4 v[224:225], off
	s_waitcnt vmcnt(8)
	s_waitcnt lgkmcnt(0)
	s_barrier
	s_setprio 1
	s_waitcnt lgkmcnt(0)
	v_mfma_f32_16x16x32_bf16 v[124:127], v[148:151], v[180:183], v[124:127]
	v_mfma_f32_16x16x32_bf16 v[120:123], v[156:159], v[180:183], v[120:123]
	v_mfma_f32_16x16x32_bf16 v[108:111], v[148:151], v[188:191], v[108:111]
	v_mfma_f32_16x16x32_bf16 v[104:107], v[156:159], v[188:191], v[104:107]
	v_mfma_f32_16x16x32_bf16 v[92:95], v[148:151], v[196:199], v[92:95]
	v_mfma_f32_16x16x32_bf16 v[88:91], v[156:159], v[196:199], v[88:91]
	v_mfma_f32_16x16x32_bf16 v[76:79], v[148:151], v[204:207], v[76:79]
	v_mfma_f32_16x16x32_bf16 v[72:75], v[156:159], v[204:207], v[72:75]
	v_mfma_f32_16x16x32_bf16 v[124:127], v[152:155], v[184:187], v[124:127]
	v_mfma_f32_16x16x32_bf16 v[120:123], v[160:163], v[184:187], v[120:123]
	v_mfma_f32_16x16x32_bf16 v[108:111], v[152:155], v[192:195], v[108:111]
	v_mfma_f32_16x16x32_bf16 v[104:107], v[160:163], v[192:195], v[104:107]
	v_mfma_f32_16x16x32_bf16 v[92:95], v[152:155], v[200:203], v[92:95]
	v_mfma_f32_16x16x32_bf16 v[88:91], v[160:163], v[200:203], v[88:91]
	v_mfma_f32_16x16x32_bf16 v[76:79], v[152:155], v[218:221], v[76:79]
	v_mfma_f32_16x16x32_bf16 v[72:75], v[160:163], v[218:221], v[72:75]
	s_setprio 0
	s_setprio 1
	v_mfma_f32_16x16x32_bf16 v[116:119], v[164:167], v[180:183], v[116:119]
	v_mfma_f32_16x16x32_bf16 v[112:115], v[172:175], v[180:183], v[112:115]
	v_mfma_f32_16x16x32_bf16 v[100:103], v[164:167], v[188:191], v[100:103]
	v_mfma_f32_16x16x32_bf16 v[96:99], v[172:175], v[188:191], v[96:99]
	v_mfma_f32_16x16x32_bf16 v[84:87], v[164:167], v[196:199], v[84:87]
	v_mfma_f32_16x16x32_bf16 v[80:83], v[172:175], v[196:199], v[80:83]
	v_mfma_f32_16x16x32_bf16 v[68:71], v[164:167], v[204:207], v[68:71]
	v_mfma_f32_16x16x32_bf16 v[64:67], v[172:175], v[204:207], v[64:67]
	v_mfma_f32_16x16x32_bf16 v[116:119], v[168:171], v[184:187], v[116:119]
	v_mfma_f32_16x16x32_bf16 v[112:115], v[176:179], v[184:187], v[112:115]
	v_mfma_f32_16x16x32_bf16 v[100:103], v[168:171], v[192:195], v[100:103]
	v_mfma_f32_16x16x32_bf16 v[96:99], v[176:179], v[192:195], v[96:99]
	v_mfma_f32_16x16x32_bf16 v[84:87], v[168:171], v[200:203], v[84:87]
	v_mfma_f32_16x16x32_bf16 v[80:83], v[176:179], v[200:203], v[80:83]
	v_mfma_f32_16x16x32_bf16 v[68:71], v[168:171], v[218:221], v[68:71]
	v_mfma_f32_16x16x32_bf16 v[64:67], v[176:179], v[218:221], v[64:67]
	s_setprio 0
	s_barrier
; #define PG8_STAGE(bufoff, gbase, voff) do { _Pragma("unroll") for (int _i = 0; _i < 2; ++_i) \
;         __builtin_amdgcn_global_load_lds((const unsigned*)((const char*)(gbase) + (voff)[_i]), (PG8_LAS unsigned*)(lds + (bufoff) + ldsw + _i * 8192), 16, 0, 0); } while (0)
; #define PG8_LDA(dst, b, h) do { _Pragma("unroll") for (int m = 0; m < 4; ++m) _Pragma("unroll") for (int k = 0; k < 2; ++k) dst[m][k] = *(const PG8_LAS bf16x8*)(lds + PG8_SA(b, h) + aoff + m * 2048 + k * 1024); } while (0)
; #define PG8_MMA(ai, bj, At, Bt) do { __builtin_amdgcn_s_setprio(1); _Pragma("unroll") for (int m = 0; m < 4; ++m) _Pragma("unroll") for (int n = 0; n < 2; ++n) _Pragma("unroll") for (int k = 0; k < 2; ++k) \
;         acc[ai][bj][m][n] = __builtin_amdgcn_mfma_f32_16x16x32_bf16(Bt[n][k], At[m][k], acc[ai][bj][m][n], 0, 0, 0); __builtin_amdgcn_s_setprio(0); } while (0)
; #define PG8_WAIT_V(n) asm volatile("s_waitcnt vmcnt(" #n ")" ::: "memory")
; #define PG8_WAIT_L(n) asm volatile("s_waitcnt lgkmcnt(" #n ")" ::: "memory")
; #define PG8_BAR __builtin_amdgcn_s_barrier()
; #define PG8_SCHED __builtin_amdgcn_sched_barrier(0)
;     ...
;             PG8_LDA(At, 1, 1); PG8_STAGE(PG8_SB(1, 0), b3, voffB); PG8_STAGE(PG8_SB(1, 1), b3 + hstepB, voffB); PG8_STAGE(PG8_SA(1, 0), a3, voffA);
;             PG8_WAIT_V(8); PG8_WAIT_L(0); PG8_BAR; PG8_MMA(1, 0, At, B0); PG8_MMA(1, 1, At, B1); PG8_BAR; PG8_SCHED;
;         }
	s_mov_b64 s[50:51], 0x80
	s_add_i32 s22, s48, s26
	v_lshl_add_u64 v[140:141], v[140:141], 0, s[50:51]
	s_mov_b32 m0, s22
	ds_read_b128 v[180:183], v142 offset:49152
	ds_read_b128 v[184:187], v142 offset:50176
	ds_read_b128 v[188:191], v142 offset:51200
	ds_read_b128 v[192:195], v142 offset:52224
	ds_read_b128 v[196:199], v142 offset:53248
	ds_read_b128 v[200:203], v142 offset:54272
	ds_read_b128 v[204:207], v142 offset:55296
	ds_read_b128 v[218:221], v142 offset:56320
	global_load_lds_dwordx4 v[140:141], off
	s_add_i32 m0, s22, 0x2000
	s_add_u32 s20, s20, 0x20080
	v_lshl_add_u64 v[140:141], v[222:223], 0, s[50:51]
	s_addc_u32 s21, s21, 0
	s_add_i32 s22, s49, s26
	global_load_lds_dwordx4 v[140:141], off
	v_lshl_add_u64 v[140:141], s[20:21], 0, v[134:135]
	s_mov_b32 m0, s22
	s_nop 0
	global_load_lds_dwordx4 v[140:141], off
	v_lshl_add_u64 v[140:141], s[20:21], 0, v[132:133]
	s_add_i32 m0, s22, 0x2000
	s_nop 0
	global_load_lds_dwordx4 v[140:141], off
	s_waitcnt vmcnt(6)
	s_waitcnt lgkmcnt(0)
	s_barrier
	s_setprio 1
	s_waitcnt lgkmcnt(0)
	v_mfma_f32_16x16x32_bf16 v[60:63], v[148:151], v[180:183], v[60:63]
	v_mfma_f32_16x16x32_bf16 v[56:59], v[156:159], v[180:183], v[56:59]
	v_mfma_f32_16x16x32_bf16 v[44:47], v[148:151], v[188:191], v[44:47]
	v_mfma_f32_16x16x32_bf16 v[40:43], v[156:159], v[188:191], v[40:43]
	v_mfma_f32_16x16x32_bf16 v[28:31], v[148:151], v[196:199], v[28:31]
	v_mfma_f32_16x16x32_bf16 v[24:27], v[156:159], v[196:199], v[24:27]
	v_mfma_f32_16x16x32_bf16 v[12:15], v[148:151], v[204:207], v[12:15]
	v_mfma_f32_16x16x32_bf16 v[8:11], v[156:159], v[204:207], v[8:11]
	v_mfma_f32_16x16x32_bf16 v[60:63], v[152:155], v[184:187], v[60:63]
	v_mfma_f32_16x16x32_bf16 v[56:59], v[160:163], v[184:187], v[56:59]
	v_mfma_f32_16x16x32_bf16 v[44:47], v[152:155], v[192:195], v[44:47]
	v_mfma_f32_16x16x32_bf16 v[40:43], v[160:163], v[192:195], v[40:43]
	v_mfma_f32_16x16x32_bf16 v[28:31], v[152:155], v[200:203], v[28:31]
	v_mfma_f32_16x16x32_bf16 v[24:27], v[160:163], v[200:203], v[24:27]
	v_mfma_f32_16x16x32_bf16 v[12:15], v[152:155], v[218:221], v[12:15]
	v_mfma_f32_16x16x32_bf16 v[8:11], v[160:163], v[218:221], v[8:11]
	s_setprio 0
	s_setprio 1
	v_mfma_f32_16x16x32_bf16 v[52:55], v[164:167], v[180:183], v[52:55]
	v_mfma_f32_16x16x32_bf16 v[48:51], v[172:175], v[180:183], v[48:51]
	v_mfma_f32_16x16x32_bf16 v[36:39], v[164:167], v[188:191], v[36:39]
	v_mfma_f32_16x16x32_bf16 v[32:35], v[172:175], v[188:191], v[32:35]
	v_mfma_f32_16x16x32_bf16 v[20:23], v[164:167], v[196:199], v[20:23]
	v_mfma_f32_16x16x32_bf16 v[16:19], v[172:175], v[196:199], v[16:19]
	v_mfma_f32_16x16x32_bf16 v[4:7], v[164:167], v[204:207], v[4:7]
	v_mfma_f32_16x16x32_bf16 v[0:3], v[172:175], v[204:207], v[0:3]
	v_mfma_f32_16x16x32_bf16 v[52:55], v[168:171], v[184:187], v[52:55]
	v_mfma_f32_16x16x32_bf16 v[48:51], v[176:179], v[184:187], v[48:51]
	v_mfma_f32_16x16x32_bf16 v[36:39], v[168:171], v[192:195], v[36:39]
	v_mfma_f32_16x16x32_bf16 v[32:35], v[176:179], v[192:195], v[32:35]
	v_mfma_f32_16x16x32_bf16 v[20:23], v[168:171], v[200:203], v[20:23]
	v_mfma_f32_16x16x32_bf16 v[16:19], v[176:179], v[200:203], v[16:19]
	v_mfma_f32_16x16x32_bf16 v[4:7], v[168:171], v[218:221], v[4:7]
	v_mfma_f32_16x16x32_bf16 v[0:3], v[176:179], v[218:221], v[0:3]
	v_lshl_add_u64 v[140:141], s[18:19], 0, v[128:129]
	s_mov_b32 m0, s31
	s_nop 0
	global_load_lds_dwordx4 v[140:141], off
	v_lshl_add_u64 v[140:141], s[18:19], 0, v[130:131]
	s_mov_b32 m0, s34
	s_nop 0
	global_load_lds_dwordx4 v[140:141], off
	s_setprio 0
	s_barrier
	s_add_u32 s16, s16, 0x100
	s_addc_u32 s17, s17, 0
	s_add_i32 s46, s46, 2
	s_cmp_gt_u32 s47, 5
	s_cbranch_scc1 .LBB0_838
